# MFMA pairs with alternating k order so consecutive MFMAs share an accumulator or an operand register
# speedup vs baseline: 1.0093x; 1.0006x over previous
.LBB0_142:
	ds_read_b128 v[168:171], v165
	ds_read_b128 v[172:175], v165 offset:1024
	ds_read_b128 v[176:179], v165 offset:2048
	ds_read_b128 v[180:183], v165 offset:3072
	ds_read_b128 v[184:187], v166
	ds_read_b128 v[188:191], v166 offset:1024
	ds_read_b128 v[192:195], v166 offset:2048
	ds_read_b128 v[196:199], v166 offset:3072
	s_add_i32 s54, s22, 2
	s_add_u32 s55, s20, 0x80
	s_addc_u32 s23, s21, 0
	s_cmp_eq_u32 s42, s22
	s_cselect_b32 s22, s4, s55
	s_cselect_b32 s23, s5, s23
	s_cselect_b32 s61, s19, s53
	s_cselect_b32 s60, s18, s52
	v_lshl_add_u64 v[234:235], s[20:21], 0, v[154:155]
	s_add_i32 m0, s31, 0xc000
	ds_read_b128 v[200:203], v167
	ds_read_b128 v[204:207], v167 offset:1024
	ds_read_b128 v[208:211], v167 offset:2048
	ds_read_b128 v[212:215], v167 offset:3072
	ds_read_b128 v[216:219], v167 offset:4096
	ds_read_b128 v[222:225], v167 offset:5120
	ds_read_b128 v[226:229], v167 offset:6144
	ds_read_b128 v[230:233], v167 offset:7168
	global_load_lds_dwordx4 v[234:235], off
	v_lshl_add_u64 v[234:235], s[20:21], 0, v[156:157]
	s_add_i32 m0, s31, 0xe000
	s_nop 0
	global_load_lds_dwordx4 v[234:235], off
	s_waitcnt vmcnt(8)
	s_waitcnt lgkmcnt(0)
	s_barrier
	s_setprio 1
	s_waitcnt lgkmcnt(0)
	v_mfma_f32_16x16x32_bf16 v[120:123], v[168:171], v[200:203], v[120:123]
	v_mfma_f32_16x16x32_bf16 v[120:123], v[172:175], v[204:207], v[120:123]
	v_mfma_f32_16x16x32_bf16 v[116:119], v[180:183], v[204:207], v[116:119]
	v_mfma_f32_16x16x32_bf16 v[116:119], v[176:179], v[200:203], v[116:119]
	v_mfma_f32_16x16x32_bf16 v[108:111], v[168:171], v[208:211], v[108:111]
	v_mfma_f32_16x16x32_bf16 v[108:111], v[172:175], v[212:215], v[108:111]
	v_mfma_f32_16x16x32_bf16 v[100:103], v[180:183], v[212:215], v[100:103]
	v_mfma_f32_16x16x32_bf16 v[100:103], v[176:179], v[208:211], v[100:103]
	v_mfma_f32_16x16x32_bf16 v[92:95], v[168:171], v[216:219], v[92:95]
	v_mfma_f32_16x16x32_bf16 v[92:95], v[172:175], v[222:225], v[92:95]
	v_mfma_f32_16x16x32_bf16 v[84:87], v[180:183], v[222:225], v[84:87]
	v_mfma_f32_16x16x32_bf16 v[84:87], v[176:179], v[216:219], v[84:87]
	v_mfma_f32_16x16x32_bf16 v[76:79], v[168:171], v[226:229], v[76:79]
	v_mfma_f32_16x16x32_bf16 v[76:79], v[172:175], v[230:233], v[76:79]
	v_mfma_f32_16x16x32_bf16 v[68:71], v[180:183], v[230:233], v[68:71]
	v_mfma_f32_16x16x32_bf16 v[68:71], v[176:179], v[226:229], v[68:71]
	s_setprio 0
	s_setprio 1
	v_mfma_f32_16x16x32_bf16 v[124:127], v[184:187], v[200:203], v[124:127]
	v_mfma_f32_16x16x32_bf16 v[124:127], v[188:191], v[204:207], v[124:127]
	v_mfma_f32_16x16x32_bf16 v[112:115], v[196:199], v[204:207], v[112:115]
	v_mfma_f32_16x16x32_bf16 v[112:115], v[192:195], v[200:203], v[112:115]
	v_mfma_f32_16x16x32_bf16 v[104:107], v[184:187], v[208:211], v[104:107]
	v_mfma_f32_16x16x32_bf16 v[104:107], v[188:191], v[212:215], v[104:107]
	v_mfma_f32_16x16x32_bf16 v[96:99], v[196:199], v[212:215], v[96:99]
	v_mfma_f32_16x16x32_bf16 v[96:99], v[192:195], v[208:211], v[96:99]
	v_mfma_f32_16x16x32_bf16 v[88:91], v[184:187], v[216:219], v[88:91]
	v_mfma_f32_16x16x32_bf16 v[88:91], v[188:191], v[222:225], v[88:91]
	v_mfma_f32_16x16x32_bf16 v[80:83], v[196:199], v[222:225], v[80:83]
	v_mfma_f32_16x16x32_bf16 v[80:83], v[192:195], v[216:219], v[80:83]
	v_mfma_f32_16x16x32_bf16 v[72:75], v[184:187], v[226:229], v[72:75]
	v_mfma_f32_16x16x32_bf16 v[72:75], v[188:191], v[230:233], v[72:75]
	v_mfma_f32_16x16x32_bf16 v[64:67], v[196:199], v[230:233], v[64:67]
	v_mfma_f32_16x16x32_bf16 v[64:67], v[192:195], v[226:229], v[64:67]
	s_setprio 0
	s_barrier
	s_add_i32 s55, s46, s28
	v_lshl_add_u64 v[234:235], s[60:61], 0, v[132:133]
	s_mov_b32 m0, s55
	ds_read_b128 v[200:203], v167 offset:16384
	ds_read_b128 v[204:207], v167 offset:17408
	ds_read_b128 v[208:211], v167 offset:18432
	ds_read_b128 v[212:215], v167 offset:19456
	ds_read_b128 v[216:219], v167 offset:20480
	ds_read_b128 v[222:225], v167 offset:21504
	ds_read_b128 v[226:229], v167 offset:22528
	ds_read_b128 v[230:233], v167 offset:23552
	global_load_lds_dwordx4 v[234:235], off
	s_add_i32 m0, s55, 0x2000
	v_lshl_add_u64 v[236:237], s[60:61], 0, v[128:129]
	s_add_u32 s60, s60, s10
	s_addc_u32 s61, s61, s11
	s_add_i32 s55, s47, s28
	global_load_lds_dwordx4 v[236:237], off
	v_lshl_add_u64 v[238:239], s[60:61], 0, v[132:133]
	s_mov_b32 m0, s55
	v_lshl_add_u64 v[240:241], s[60:61], 0, v[128:129]
	global_load_lds_dwordx4 v[238:239], off
	s_add_i32 m0, s55, 0x2000
	v_lshl_add_u64 v[242:243], s[22:23], 0, v[134:135]
	global_load_lds_dwordx4 v[240:241], off
	s_mov_b32 m0, s31
	v_lshl_add_u64 v[244:245], s[22:23], 0, v[130:131]
	global_load_lds_dwordx4 v[242:243], off
	s_mov_b32 m0, s33
	s_nop 0
	global_load_lds_dwordx4 v[244:245], off
	s_waitcnt vmcnt(8)
	s_waitcnt lgkmcnt(0)
	s_barrier
	s_setprio 1
	s_waitcnt lgkmcnt(0)
	v_mfma_f32_16x16x32_bf16 v[60:63], v[168:171], v[200:203], v[60:63]
	v_mfma_f32_16x16x32_bf16 v[60:63], v[172:175], v[204:207], v[60:63]
	v_mfma_f32_16x16x32_bf16 v[52:55], v[180:183], v[204:207], v[52:55]
	v_mfma_f32_16x16x32_bf16 v[52:55], v[176:179], v[200:203], v[52:55]
	v_mfma_f32_16x16x32_bf16 v[44:47], v[168:171], v[208:211], v[44:47]
	v_mfma_f32_16x16x32_bf16 v[44:47], v[172:175], v[212:215], v[44:47]
	v_mfma_f32_16x16x32_bf16 v[36:39], v[180:183], v[212:215], v[36:39]
	v_mfma_f32_16x16x32_bf16 v[36:39], v[176:179], v[208:211], v[36:39]
	v_mfma_f32_16x16x32_bf16 v[28:31], v[168:171], v[216:219], v[28:31]
	v_mfma_f32_16x16x32_bf16 v[28:31], v[172:175], v[222:225], v[28:31]
	v_mfma_f32_16x16x32_bf16 v[20:23], v[180:183], v[222:225], v[20:23]
	v_mfma_f32_16x16x32_bf16 v[20:23], v[176:179], v[216:219], v[20:23]
	v_mfma_f32_16x16x32_bf16 v[12:15], v[168:171], v[226:229], v[12:15]
	v_mfma_f32_16x16x32_bf16 v[12:15], v[172:175], v[230:233], v[12:15]
	v_mfma_f32_16x16x32_bf16 v[4:7], v[180:183], v[230:233], v[4:7]
	v_mfma_f32_16x16x32_bf16 v[4:7], v[176:179], v[226:229], v[4:7]
	s_setprio 0
	s_setprio 1
	v_mfma_f32_16x16x32_bf16 v[56:59], v[184:187], v[200:203], v[56:59]
	v_mfma_f32_16x16x32_bf16 v[56:59], v[188:191], v[204:207], v[56:59]
	v_mfma_f32_16x16x32_bf16 v[48:51], v[196:199], v[204:207], v[48:51]
	v_mfma_f32_16x16x32_bf16 v[48:51], v[192:195], v[200:203], v[48:51]
	v_mfma_f32_16x16x32_bf16 v[40:43], v[184:187], v[208:211], v[40:43]
	v_mfma_f32_16x16x32_bf16 v[40:43], v[188:191], v[212:215], v[40:43]
	v_mfma_f32_16x16x32_bf16 v[32:35], v[196:199], v[212:215], v[32:35]
	v_mfma_f32_16x16x32_bf16 v[32:35], v[192:195], v[208:211], v[32:35]
	v_mfma_f32_16x16x32_bf16 v[24:27], v[184:187], v[216:219], v[24:27]
	v_mfma_f32_16x16x32_bf16 v[24:27], v[188:191], v[222:225], v[24:27]
	v_mfma_f32_16x16x32_bf16 v[16:19], v[196:199], v[222:225], v[16:19]
	v_mfma_f32_16x16x32_bf16 v[16:19], v[192:195], v[216:219], v[16:19]
	v_mfma_f32_16x16x32_bf16 v[8:11], v[184:187], v[226:229], v[8:11]
	v_mfma_f32_16x16x32_bf16 v[8:11], v[188:191], v[230:233], v[8:11]
	v_mfma_f32_16x16x32_bf16 v[0:3], v[196:199], v[230:233], v[0:3]
	v_mfma_f32_16x16x32_bf16 v[0:3], v[192:195], v[226:229], v[0:3]
	s_setprio 0
	s_barrier
	s_add_i32 s55, 0, 0x18000
	s_add_i32 s60, 0, 0x1c000
	v_add_u32_e32 v180, s55, v164
	v_add_u32_e32 v196, s60, v164
	ds_read_b128 v[168:171], v180
	ds_read_b128 v[172:175], v180 offset:1024
	ds_read_b128 v[176:179], v180 offset:2048
	ds_read_b128 v[180:183], v180 offset:3072
	ds_read_b128 v[184:187], v196
	ds_read_b128 v[188:191], v196 offset:1024
	ds_read_b128 v[192:195], v196 offset:2048
	ds_read_b128 v[196:199], v196 offset:3072
	s_add_u32 s22, s22, s10
	s_addc_u32 s23, s23, s11
	s_mov_b32 m0, s34
	v_lshl_add_u64 v[246:247], s[22:23], 0, v[134:135]
	ds_read_b128 v[200:203], v167 offset:32768
	ds_read_b128 v[204:207], v167 offset:33792
	ds_read_b128 v[208:211], v167 offset:34816
	ds_read_b128 v[212:215], v167 offset:35840
	ds_read_b128 v[216:219], v167 offset:36864
	ds_read_b128 v[222:225], v167 offset:37888
	ds_read_b128 v[226:229], v167 offset:38912
	ds_read_b128 v[230:233], v167 offset:39936
	global_load_lds_dwordx4 v[246:247], off
	v_lshl_add_u64 v[246:247], s[22:23], 0, v[130:131]
	s_mov_b32 m0, s35
	s_nop 0
	global_load_lds_dwordx4 v[246:247], off
	s_waitcnt vmcnt(8)
	s_waitcnt lgkmcnt(0)
	s_barrier
	s_setprio 1
	s_waitcnt lgkmcnt(0)
	v_mfma_f32_16x16x32_bf16 v[120:123], v[168:171], v[200:203], v[120:123]
	v_mfma_f32_16x16x32_bf16 v[120:123], v[172:175], v[204:207], v[120:123]
	v_mfma_f32_16x16x32_bf16 v[116:119], v[180:183], v[204:207], v[116:119]
	v_mfma_f32_16x16x32_bf16 v[116:119], v[176:179], v[200:203], v[116:119]
	v_mfma_f32_16x16x32_bf16 v[108:111], v[168:171], v[208:211], v[108:111]
	v_mfma_f32_16x16x32_bf16 v[108:111], v[172:175], v[212:215], v[108:111]
	v_mfma_f32_16x16x32_bf16 v[100:103], v[180:183], v[212:215], v[100:103]
	v_mfma_f32_16x16x32_bf16 v[100:103], v[176:179], v[208:211], v[100:103]
	v_mfma_f32_16x16x32_bf16 v[92:95], v[168:171], v[216:219], v[92:95]
	v_mfma_f32_16x16x32_bf16 v[92:95], v[172:175], v[222:225], v[92:95]
	v_mfma_f32_16x16x32_bf16 v[84:87], v[180:183], v[222:225], v[84:87]
	v_mfma_f32_16x16x32_bf16 v[84:87], v[176:179], v[216:219], v[84:87]
	v_mfma_f32_16x16x32_bf16 v[76:79], v[168:171], v[226:229], v[76:79]
	v_mfma_f32_16x16x32_bf16 v[76:79], v[172:175], v[230:233], v[76:79]
	v_mfma_f32_16x16x32_bf16 v[68:71], v[180:183], v[230:233], v[68:71]
	v_mfma_f32_16x16x32_bf16 v[68:71], v[176:179], v[226:229], v[68:71]
	s_setprio 0
	s_setprio 1
	v_mfma_f32_16x16x32_bf16 v[124:127], v[184:187], v[200:203], v[124:127]
	v_mfma_f32_16x16x32_bf16 v[124:127], v[188:191], v[204:207], v[124:127]
	v_mfma_f32_16x16x32_bf16 v[112:115], v[196:199], v[204:207], v[112:115]
	v_mfma_f32_16x16x32_bf16 v[112:115], v[192:195], v[200:203], v[112:115]
	v_mfma_f32_16x16x32_bf16 v[104:107], v[184:187], v[208:211], v[104:107]
	v_mfma_f32_16x16x32_bf16 v[104:107], v[188:191], v[212:215], v[104:107]
	v_mfma_f32_16x16x32_bf16 v[96:99], v[196:199], v[212:215], v[96:99]
	v_mfma_f32_16x16x32_bf16 v[96:99], v[192:195], v[208:211], v[96:99]
	v_mfma_f32_16x16x32_bf16 v[88:91], v[184:187], v[216:219], v[88:91]
	v_mfma_f32_16x16x32_bf16 v[88:91], v[188:191], v[222:225], v[88:91]
	v_mfma_f32_16x16x32_bf16 v[80:83], v[196:199], v[222:225], v[80:83]
	v_mfma_f32_16x16x32_bf16 v[80:83], v[192:195], v[216:219], v[80:83]
	v_mfma_f32_16x16x32_bf16 v[72:75], v[184:187], v[226:229], v[72:75]
	v_mfma_f32_16x16x32_bf16 v[72:75], v[188:191], v[230:233], v[72:75]
	v_mfma_f32_16x16x32_bf16 v[64:67], v[196:199], v[230:233], v[64:67]
	v_mfma_f32_16x16x32_bf16 v[64:67], v[192:195], v[226:229], v[64:67]
	s_setprio 0
	s_barrier
	s_add_i32 s22, s55, s28
	v_lshl_add_u64 v[234:235], v[234:235], 0, s[14:15]
	s_mov_b32 m0, s22
	ds_read_b128 v[200:203], v167 offset:49152
	ds_read_b128 v[204:207], v167 offset:50176
	ds_read_b128 v[208:211], v167 offset:51200
	ds_read_b128 v[212:215], v167 offset:52224
	ds_read_b128 v[216:219], v167 offset:53248
	ds_read_b128 v[222:225], v167 offset:54272
	ds_read_b128 v[226:229], v167 offset:55296
	ds_read_b128 v[230:233], v167 offset:56320
	global_load_lds_dwordx4 v[234:235], off
	v_lshl_add_u64 v[234:235], v[236:237], 0, s[14:15]
	s_add_i32 m0, s22, 0x2000
	s_add_i32 s22, s60, s28
	global_load_lds_dwordx4 v[234:235], off
	v_lshl_add_u64 v[234:235], v[238:239], 0, s[14:15]
	s_mov_b32 m0, s22
	s_nop 0
	global_load_lds_dwordx4 v[234:235], off
	v_lshl_add_u64 v[234:235], v[240:241], 0, s[14:15]
	s_add_i32 m0, s22, 0x2000
	s_nop 0
	global_load_lds_dwordx4 v[234:235], off
	v_lshl_add_u64 v[234:235], v[242:243], 0, s[14:15]
	s_mov_b32 m0, s39
	s_nop 0
	global_load_lds_dwordx4 v[234:235], off
	v_lshl_add_u64 v[234:235], v[244:245], 0, s[14:15]
	s_mov_b32 m0, s40
	s_nop 0
	global_load_lds_dwordx4 v[234:235], off
	s_waitcnt vmcnt(8)
	s_waitcnt lgkmcnt(0)
	s_barrier
	s_setprio 1
	s_waitcnt lgkmcnt(0)
	v_mfma_f32_16x16x32_bf16 v[60:63], v[168:171], v[200:203], v[60:63]
	v_mfma_f32_16x16x32_bf16 v[60:63], v[172:175], v[204:207], v[60:63]
	v_mfma_f32_16x16x32_bf16 v[52:55], v[180:183], v[204:207], v[52:55]
	v_mfma_f32_16x16x32_bf16 v[52:55], v[176:179], v[200:203], v[52:55]
	v_mfma_f32_16x16x32_bf16 v[44:47], v[168:171], v[208:211], v[44:47]
	v_mfma_f32_16x16x32_bf16 v[44:47], v[172:175], v[212:215], v[44:47]
	v_mfma_f32_16x16x32_bf16 v[36:39], v[180:183], v[212:215], v[36:39]
	v_mfma_f32_16x16x32_bf16 v[36:39], v[176:179], v[208:211], v[36:39]
	v_mfma_f32_16x16x32_bf16 v[28:31], v[168:171], v[216:219], v[28:31]
	v_mfma_f32_16x16x32_bf16 v[28:31], v[172:175], v[222:225], v[28:31]
	v_mfma_f32_16x16x32_bf16 v[20:23], v[180:183], v[222:225], v[20:23]
	v_mfma_f32_16x16x32_bf16 v[20:23], v[176:179], v[216:219], v[20:23]
	v_mfma_f32_16x16x32_bf16 v[12:15], v[168:171], v[226:229], v[12:15]
	v_mfma_f32_16x16x32_bf16 v[12:15], v[172:175], v[230:233], v[12:15]
	v_mfma_f32_16x16x32_bf16 v[4:7], v[180:183], v[230:233], v[4:7]
	v_mfma_f32_16x16x32_bf16 v[4:7], v[176:179], v[226:229], v[4:7]
	s_setprio 0
	s_setprio 1
	v_mfma_f32_16x16x32_bf16 v[56:59], v[184:187], v[200:203], v[56:59]
	v_mfma_f32_16x16x32_bf16 v[56:59], v[188:191], v[204:207], v[56:59]
	v_mfma_f32_16x16x32_bf16 v[48:51], v[196:199], v[204:207], v[48:51]
	v_mfma_f32_16x16x32_bf16 v[48:51], v[192:195], v[200:203], v[48:51]
	v_mfma_f32_16x16x32_bf16 v[40:43], v[184:187], v[208:211], v[40:43]
	v_mfma_f32_16x16x32_bf16 v[40:43], v[188:191], v[212:215], v[40:43]
	v_mfma_f32_16x16x32_bf16 v[32:35], v[196:199], v[212:215], v[32:35]
	v_mfma_f32_16x16x32_bf16 v[32:35], v[192:195], v[208:211], v[32:35]
	v_mfma_f32_16x16x32_bf16 v[24:27], v[184:187], v[216:219], v[24:27]
	v_mfma_f32_16x16x32_bf16 v[24:27], v[188:191], v[222:225], v[24:27]
	v_mfma_f32_16x16x32_bf16 v[16:19], v[196:199], v[222:225], v[16:19]
	v_mfma_f32_16x16x32_bf16 v[16:19], v[192:195], v[216:219], v[16:19]
	v_mfma_f32_16x16x32_bf16 v[8:11], v[184:187], v[226:229], v[8:11]
	v_mfma_f32_16x16x32_bf16 v[8:11], v[188:191], v[230:233], v[8:11]
	v_mfma_f32_16x16x32_bf16 v[0:3], v[196:199], v[230:233], v[0:3]
	v_mfma_f32_16x16x32_bf16 v[0:3], v[192:195], v[226:229], v[0:3]
	s_setprio 0
	s_barrier
	s_add_u32 s20, s20, 0x100
	s_addc_u32 s21, s21, 0
	s_add_u32 s52, s52, 0x100
	s_addc_u32 s53, s53, 0
	s_cmp_ge_i32 s54, s41
	s_mov_b32 s22, s54
	s_cbranch_scc0 .LBB0_142

.LBB0_228:
	ds_read_b128 v[140:143], v219
	ds_read_b128 v[144:147], v219 offset:1024
	ds_read_b128 v[148:151], v219 offset:2048
	ds_read_b128 v[152:155], v219 offset:3072
	ds_read_b128 v[156:159], v221
	ds_read_b128 v[164:167], v221 offset:1024
	ds_read_b128 v[168:171], v221 offset:2048
	ds_read_b128 v[172:175], v221 offset:3072
	s_add_i32 s62, s26, 2
	s_add_u32 s27, s24, 0x4000
	s_addc_u32 s28, s25, 0
	s_cmp_eq_u32 s46, s26
	s_cselect_b32 s30, s0, s27
	s_cselect_b32 s31, s1, s28
	s_cselect_b32 s28, s22, s60
	s_cselect_b32 s29, s23, s61
	s_add_u32 s26, s30, 0x8000
	s_addc_u32 s27, s31, 0
	v_lshl_add_u64 v[160:161], s[24:25], 0, v[132:133]
	s_add_i32 m0, s38, 0xc000
	ds_read_b128 v[176:179], v222
	ds_read_b128 v[180:183], v222 offset:1024
	ds_read_b128 v[184:187], v222 offset:2048
	ds_read_b128 v[188:191], v222 offset:3072
	ds_read_b128 v[192:195], v222 offset:4096
	ds_read_b128 v[196:199], v222 offset:5120
	ds_read_b128 v[200:203], v222 offset:6144
	ds_read_b128 v[204:207], v222 offset:7168
	global_load_lds_dwordx4 v[160:161], off
	v_lshl_add_u64 v[160:161], s[24:25], 0, v[134:135]
	s_add_i32 m0, s38, 0xe000
	s_nop 0
	global_load_lds_dwordx4 v[160:161], off
	s_waitcnt vmcnt(8)
	s_waitcnt lgkmcnt(0)
	s_barrier
	s_setprio 1
	s_waitcnt lgkmcnt(0)
	v_mfma_f32_16x16x32_bf16 v[124:127], v[140:143], v[176:179], v[124:127]
	v_mfma_f32_16x16x32_bf16 v[124:127], v[144:147], v[180:183], v[124:127]
	v_mfma_f32_16x16x32_bf16 v[120:123], v[152:155], v[180:183], v[120:123]
	v_mfma_f32_16x16x32_bf16 v[120:123], v[148:151], v[176:179], v[120:123]
	v_mfma_f32_16x16x32_bf16 v[116:119], v[140:143], v[184:187], v[116:119]
	v_mfma_f32_16x16x32_bf16 v[116:119], v[144:147], v[188:191], v[116:119]
	v_mfma_f32_16x16x32_bf16 v[112:115], v[152:155], v[188:191], v[112:115]
	v_mfma_f32_16x16x32_bf16 v[112:115], v[148:151], v[184:187], v[112:115]
	v_mfma_f32_16x16x32_bf16 v[104:107], v[140:143], v[192:195], v[104:107]
	v_mfma_f32_16x16x32_bf16 v[104:107], v[144:147], v[196:199], v[104:107]
	v_mfma_f32_16x16x32_bf16 v[96:99], v[152:155], v[196:199], v[96:99]
	v_mfma_f32_16x16x32_bf16 v[96:99], v[148:151], v[192:195], v[96:99]
	v_mfma_f32_16x16x32_bf16 v[88:91], v[140:143], v[200:203], v[88:91]
	v_mfma_f32_16x16x32_bf16 v[88:91], v[144:147], v[204:207], v[88:91]
	v_mfma_f32_16x16x32_bf16 v[80:83], v[152:155], v[204:207], v[80:83]
	v_mfma_f32_16x16x32_bf16 v[80:83], v[148:151], v[200:203], v[80:83]
	s_setprio 0
	s_setprio 1
	v_mfma_f32_16x16x32_bf16 v[108:111], v[156:159], v[176:179], v[108:111]
	v_mfma_f32_16x16x32_bf16 v[108:111], v[164:167], v[180:183], v[108:111]
	v_mfma_f32_16x16x32_bf16 v[100:103], v[172:175], v[180:183], v[100:103]
	v_mfma_f32_16x16x32_bf16 v[100:103], v[168:171], v[176:179], v[100:103]
	v_mfma_f32_16x16x32_bf16 v[92:95], v[156:159], v[184:187], v[92:95]
	v_mfma_f32_16x16x32_bf16 v[92:95], v[164:167], v[188:191], v[92:95]
	v_mfma_f32_16x16x32_bf16 v[84:87], v[172:175], v[188:191], v[84:87]
	v_mfma_f32_16x16x32_bf16 v[84:87], v[168:171], v[184:187], v[84:87]
	v_mfma_f32_16x16x32_bf16 v[76:79], v[156:159], v[192:195], v[76:79]
	v_mfma_f32_16x16x32_bf16 v[76:79], v[164:167], v[196:199], v[76:79]
	v_mfma_f32_16x16x32_bf16 v[72:75], v[172:175], v[196:199], v[72:75]
	v_mfma_f32_16x16x32_bf16 v[72:75], v[168:171], v[192:195], v[72:75]
	v_mfma_f32_16x16x32_bf16 v[68:71], v[156:159], v[200:203], v[68:71]
	v_mfma_f32_16x16x32_bf16 v[68:71], v[164:167], v[204:207], v[68:71]
	v_mfma_f32_16x16x32_bf16 v[64:67], v[172:175], v[204:207], v[64:67]
	v_mfma_f32_16x16x32_bf16 v[64:67], v[168:171], v[200:203], v[64:67]
	s_setprio 0
	s_barrier
	s_add_i32 s63, s50, s37
	v_lshl_add_u64 v[160:161], s[28:29], 0, v[128:129]
	s_mov_b32 m0, s63
	ds_read_b128 v[176:179], v222 offset:16384
	ds_read_b128 v[180:183], v222 offset:17408
	ds_read_b128 v[184:187], v222 offset:18432
	ds_read_b128 v[188:191], v222 offset:19456
	ds_read_b128 v[192:195], v222 offset:20480
	ds_read_b128 v[196:199], v222 offset:21504
	ds_read_b128 v[200:203], v222 offset:22528
	ds_read_b128 v[204:207], v222 offset:23552
	global_load_lds_dwordx4 v[160:161], off
	s_add_i32 m0, s63, 0x2000
	s_add_u32 s64, s28, 0x4000
	v_lshl_add_u64 v[160:161], s[28:29], 0, v[130:131]
	s_addc_u32 s65, s29, 0
	s_add_i32 s63, s51, s37
	global_load_lds_dwordx4 v[160:161], off
	v_lshl_add_u64 v[160:161], s[64:65], 0, v[128:129]
	s_mov_b32 m0, s63
	s_nop 0
	global_load_lds_dwordx4 v[160:161], off
	v_lshl_add_u64 v[160:161], s[64:65], 0, v[130:131]
	s_add_i32 m0, s63, 0x2000
	s_nop 0
	global_load_lds_dwordx4 v[160:161], off
	v_lshl_add_u64 v[160:161], s[30:31], 0, v[128:129]
	s_mov_b32 m0, s38
	s_nop 0
	global_load_lds_dwordx4 v[160:161], off
	v_lshl_add_u64 v[160:161], s[30:31], 0, v[130:131]
	s_mov_b32 m0, s39
	s_nop 0
	global_load_lds_dwordx4 v[160:161], off
	s_waitcnt vmcnt(8)
	s_waitcnt lgkmcnt(0)
	s_barrier
	s_setprio 1
	s_waitcnt lgkmcnt(0)
	v_mfma_f32_16x16x32_bf16 v[60:63], v[140:143], v[176:179], v[60:63]
	v_mfma_f32_16x16x32_bf16 v[60:63], v[144:147], v[180:183], v[60:63]
	v_mfma_f32_16x16x32_bf16 v[56:59], v[152:155], v[180:183], v[56:59]
	v_mfma_f32_16x16x32_bf16 v[56:59], v[148:151], v[176:179], v[56:59]
	v_mfma_f32_16x16x32_bf16 v[52:55], v[140:143], v[184:187], v[52:55]
	v_mfma_f32_16x16x32_bf16 v[52:55], v[144:147], v[188:191], v[52:55]
	v_mfma_f32_16x16x32_bf16 v[48:51], v[152:155], v[188:191], v[48:51]
	v_mfma_f32_16x16x32_bf16 v[48:51], v[148:151], v[184:187], v[48:51]
	v_mfma_f32_16x16x32_bf16 v[40:43], v[140:143], v[192:195], v[40:43]
	v_mfma_f32_16x16x32_bf16 v[40:43], v[144:147], v[196:199], v[40:43]
	v_mfma_f32_16x16x32_bf16 v[32:35], v[152:155], v[196:199], v[32:35]
	v_mfma_f32_16x16x32_bf16 v[32:35], v[148:151], v[192:195], v[32:35]
	v_mfma_f32_16x16x32_bf16 v[24:27], v[140:143], v[200:203], v[24:27]
	v_mfma_f32_16x16x32_bf16 v[24:27], v[144:147], v[204:207], v[24:27]
	v_mfma_f32_16x16x32_bf16 v[16:19], v[152:155], v[204:207], v[16:19]
	v_mfma_f32_16x16x32_bf16 v[16:19], v[148:151], v[200:203], v[16:19]
	s_setprio 0
	s_setprio 1
	v_mfma_f32_16x16x32_bf16 v[44:47], v[156:159], v[176:179], v[44:47]
	v_mfma_f32_16x16x32_bf16 v[44:47], v[164:167], v[180:183], v[44:47]
	v_mfma_f32_16x16x32_bf16 v[36:39], v[172:175], v[180:183], v[36:39]
	v_mfma_f32_16x16x32_bf16 v[36:39], v[168:171], v[176:179], v[36:39]
	v_mfma_f32_16x16x32_bf16 v[28:31], v[156:159], v[184:187], v[28:31]
	v_mfma_f32_16x16x32_bf16 v[28:31], v[164:167], v[188:191], v[28:31]
	v_mfma_f32_16x16x32_bf16 v[20:23], v[172:175], v[188:191], v[20:23]
	v_mfma_f32_16x16x32_bf16 v[20:23], v[168:171], v[184:187], v[20:23]
	v_mfma_f32_16x16x32_bf16 v[12:15], v[156:159], v[192:195], v[12:15]
	v_mfma_f32_16x16x32_bf16 v[12:15], v[164:167], v[196:199], v[12:15]
	v_mfma_f32_16x16x32_bf16 v[8:11], v[172:175], v[196:199], v[8:11]
	v_mfma_f32_16x16x32_bf16 v[8:11], v[168:171], v[192:195], v[8:11]
	v_mfma_f32_16x16x32_bf16 v[4:7], v[156:159], v[200:203], v[4:7]
	v_mfma_f32_16x16x32_bf16 v[4:7], v[164:167], v[204:207], v[4:7]
	v_mfma_f32_16x16x32_bf16 v[0:3], v[172:175], v[204:207], v[0:3]
	v_mfma_f32_16x16x32_bf16 v[0:3], v[168:171], v[200:203], v[0:3]
	s_setprio 0
	s_barrier
	s_add_i32 s63, 0, 0x18000
	s_add_i32 s64, 0, 0x1c000
	v_add_u32_e32 v152, s63, v217
	v_add_u32_e32 v160, s64, v217
	ds_read_b128 v[140:143], v152
	ds_read_b128 v[144:147], v152 offset:1024
	ds_read_b128 v[148:151], v152 offset:2048
	ds_read_b128 v[152:155], v152 offset:3072
	ds_read_b128 v[156:159], v160
	ds_read_b128 v[164:167], v160 offset:1024
	ds_read_b128 v[168:171], v160 offset:2048
	ds_read_b128 v[172:175], v160 offset:3072
	s_add_u32 s30, s30, 0x4000
	s_addc_u32 s31, s31, 0
	s_mov_b32 m0, s40
	v_lshl_add_u64 v[160:161], s[30:31], 0, v[128:129]
	ds_read_b128 v[176:179], v222 offset:32768
	ds_read_b128 v[180:183], v222 offset:33792
	ds_read_b128 v[184:187], v222 offset:34816
	ds_read_b128 v[188:191], v222 offset:35840
	ds_read_b128 v[192:195], v222 offset:36864
	ds_read_b128 v[196:199], v222 offset:37888
	ds_read_b128 v[200:203], v222 offset:38912
	ds_read_b128 v[204:207], v222 offset:39936
	global_load_lds_dwordx4 v[160:161], off
	v_lshl_add_u64 v[160:161], s[30:31], 0, v[130:131]
	s_mov_b32 m0, s41
	s_nop 0
	global_load_lds_dwordx4 v[160:161], off
	s_waitcnt vmcnt(8)
	s_waitcnt lgkmcnt(0)
	s_barrier
	s_setprio 1
	s_waitcnt lgkmcnt(0)
	v_mfma_f32_16x16x32_bf16 v[124:127], v[140:143], v[176:179], v[124:127]
	v_mfma_f32_16x16x32_bf16 v[124:127], v[144:147], v[180:183], v[124:127]
	v_mfma_f32_16x16x32_bf16 v[120:123], v[152:155], v[180:183], v[120:123]
	v_mfma_f32_16x16x32_bf16 v[120:123], v[148:151], v[176:179], v[120:123]
	v_mfma_f32_16x16x32_bf16 v[116:119], v[140:143], v[184:187], v[116:119]
	v_mfma_f32_16x16x32_bf16 v[116:119], v[144:147], v[188:191], v[116:119]
	v_mfma_f32_16x16x32_bf16 v[112:115], v[152:155], v[188:191], v[112:115]
	v_mfma_f32_16x16x32_bf16 v[112:115], v[148:151], v[184:187], v[112:115]
	v_mfma_f32_16x16x32_bf16 v[104:107], v[140:143], v[192:195], v[104:107]
	v_mfma_f32_16x16x32_bf16 v[104:107], v[144:147], v[196:199], v[104:107]
	v_mfma_f32_16x16x32_bf16 v[96:99], v[152:155], v[196:199], v[96:99]
	v_mfma_f32_16x16x32_bf16 v[96:99], v[148:151], v[192:195], v[96:99]
	v_mfma_f32_16x16x32_bf16 v[88:91], v[140:143], v[200:203], v[88:91]
	v_mfma_f32_16x16x32_bf16 v[88:91], v[144:147], v[204:207], v[88:91]
	v_mfma_f32_16x16x32_bf16 v[80:83], v[152:155], v[204:207], v[80:83]
	v_mfma_f32_16x16x32_bf16 v[80:83], v[148:151], v[200:203], v[80:83]
	s_setprio 0
	s_setprio 1
	v_mfma_f32_16x16x32_bf16 v[108:111], v[156:159], v[176:179], v[108:111]
	v_mfma_f32_16x16x32_bf16 v[108:111], v[164:167], v[180:183], v[108:111]
	v_mfma_f32_16x16x32_bf16 v[100:103], v[172:175], v[180:183], v[100:103]
	v_mfma_f32_16x16x32_bf16 v[100:103], v[168:171], v[176:179], v[100:103]
	v_mfma_f32_16x16x32_bf16 v[92:95], v[156:159], v[184:187], v[92:95]
	v_mfma_f32_16x16x32_bf16 v[92:95], v[164:167], v[188:191], v[92:95]
	v_mfma_f32_16x16x32_bf16 v[84:87], v[172:175], v[188:191], v[84:87]
	v_mfma_f32_16x16x32_bf16 v[84:87], v[168:171], v[184:187], v[84:87]
	v_mfma_f32_16x16x32_bf16 v[76:79], v[156:159], v[192:195], v[76:79]
	v_mfma_f32_16x16x32_bf16 v[76:79], v[164:167], v[196:199], v[76:79]
	v_mfma_f32_16x16x32_bf16 v[72:75], v[172:175], v[196:199], v[72:75]
	v_mfma_f32_16x16x32_bf16 v[72:75], v[168:171], v[192:195], v[72:75]
	v_mfma_f32_16x16x32_bf16 v[68:71], v[156:159], v[200:203], v[68:71]
	v_mfma_f32_16x16x32_bf16 v[68:71], v[164:167], v[204:207], v[68:71]
	v_mfma_f32_16x16x32_bf16 v[64:67], v[172:175], v[204:207], v[64:67]
	v_mfma_f32_16x16x32_bf16 v[64:67], v[168:171], v[200:203], v[64:67]
	s_setprio 0
	s_barrier
	s_add_u32 s30, s28, 0x8000
	s_addc_u32 s31, s29, 0
	s_add_i32 s63, s63, s37
	v_lshl_add_u64 v[160:161], s[30:31], 0, v[128:129]
	s_mov_b32 m0, s63
	ds_read_b128 v[176:179], v222 offset:49152
	ds_read_b128 v[180:183], v222 offset:50176
	ds_read_b128 v[184:187], v222 offset:51200
	ds_read_b128 v[188:191], v222 offset:52224
	ds_read_b128 v[192:195], v222 offset:53248
	ds_read_b128 v[196:199], v222 offset:54272
	ds_read_b128 v[200:203], v222 offset:55296
	ds_read_b128 v[204:207], v222 offset:56320
	global_load_lds_dwordx4 v[160:161], off
	s_add_i32 m0, s63, 0x2000
	s_add_u32 s28, s28, 0xc000
	v_lshl_add_u64 v[160:161], s[30:31], 0, v[130:131]
	s_addc_u32 s29, s29, 0
	s_add_i32 s30, s64, s37
	global_load_lds_dwordx4 v[160:161], off
	v_lshl_add_u64 v[160:161], s[28:29], 0, v[128:129]
	s_mov_b32 m0, s30
	s_nop 0
	global_load_lds_dwordx4 v[160:161], off
	v_lshl_add_u64 v[160:161], s[28:29], 0, v[130:131]
	s_add_i32 m0, s30, 0x2000
	s_nop 0
	global_load_lds_dwordx4 v[160:161], off
	v_lshl_add_u64 v[160:161], s[26:27], 0, v[128:129]
	s_mov_b32 m0, s44
	s_nop 0
	global_load_lds_dwordx4 v[160:161], off
	v_lshl_add_u64 v[160:161], s[26:27], 0, v[130:131]
	s_mov_b32 m0, s45
	s_nop 0
	global_load_lds_dwordx4 v[160:161], off
	s_waitcnt vmcnt(8)
	s_waitcnt lgkmcnt(0)
	s_barrier
	s_setprio 1
	s_waitcnt lgkmcnt(0)
	v_mfma_f32_16x16x32_bf16 v[60:63], v[140:143], v[176:179], v[60:63]
	v_mfma_f32_16x16x32_bf16 v[60:63], v[144:147], v[180:183], v[60:63]
	v_mfma_f32_16x16x32_bf16 v[56:59], v[152:155], v[180:183], v[56:59]
	v_mfma_f32_16x16x32_bf16 v[56:59], v[148:151], v[176:179], v[56:59]
	v_mfma_f32_16x16x32_bf16 v[52:55], v[140:143], v[184:187], v[52:55]
	v_mfma_f32_16x16x32_bf16 v[52:55], v[144:147], v[188:191], v[52:55]
	v_mfma_f32_16x16x32_bf16 v[48:51], v[152:155], v[188:191], v[48:51]
	v_mfma_f32_16x16x32_bf16 v[48:51], v[148:151], v[184:187], v[48:51]
	v_mfma_f32_16x16x32_bf16 v[40:43], v[140:143], v[192:195], v[40:43]
	v_mfma_f32_16x16x32_bf16 v[40:43], v[144:147], v[196:199], v[40:43]
	v_mfma_f32_16x16x32_bf16 v[32:35], v[152:155], v[196:199], v[32:35]
	v_mfma_f32_16x16x32_bf16 v[32:35], v[148:151], v[192:195], v[32:35]
	v_mfma_f32_16x16x32_bf16 v[24:27], v[140:143], v[200:203], v[24:27]
	v_mfma_f32_16x16x32_bf16 v[24:27], v[144:147], v[204:207], v[24:27]
	v_mfma_f32_16x16x32_bf16 v[16:19], v[152:155], v[204:207], v[16:19]
	v_mfma_f32_16x16x32_bf16 v[16:19], v[148:151], v[200:203], v[16:19]
	s_setprio 0
	s_setprio 1
	v_mfma_f32_16x16x32_bf16 v[44:47], v[156:159], v[176:179], v[44:47]
	v_mfma_f32_16x16x32_bf16 v[44:47], v[164:167], v[180:183], v[44:47]
	v_mfma_f32_16x16x32_bf16 v[36:39], v[172:175], v[180:183], v[36:39]
	v_mfma_f32_16x16x32_bf16 v[36:39], v[168:171], v[176:179], v[36:39]
	v_mfma_f32_16x16x32_bf16 v[28:31], v[156:159], v[184:187], v[28:31]
	v_mfma_f32_16x16x32_bf16 v[28:31], v[164:167], v[188:191], v[28:31]
	v_mfma_f32_16x16x32_bf16 v[20:23], v[172:175], v[188:191], v[20:23]
	v_mfma_f32_16x16x32_bf16 v[20:23], v[168:171], v[184:187], v[20:23]
	v_mfma_f32_16x16x32_bf16 v[12:15], v[156:159], v[192:195], v[12:15]
	v_mfma_f32_16x16x32_bf16 v[12:15], v[164:167], v[196:199], v[12:15]
	v_mfma_f32_16x16x32_bf16 v[8:11], v[172:175], v[196:199], v[8:11]
	v_mfma_f32_16x16x32_bf16 v[8:11], v[168:171], v[192:195], v[8:11]
	v_mfma_f32_16x16x32_bf16 v[4:7], v[156:159], v[200:203], v[4:7]
	v_mfma_f32_16x16x32_bf16 v[4:7], v[164:167], v[204:207], v[4:7]
	v_mfma_f32_16x16x32_bf16 v[0:3], v[172:175], v[204:207], v[0:3]
	v_mfma_f32_16x16x32_bf16 v[0:3], v[168:171], v[200:203], v[0:3]
	s_setprio 0
	s_barrier
	s_add_u32 s24, s24, 0x10000
	s_addc_u32 s25, s25, 0
	s_add_u32 s60, s60, 0x10000
	s_addc_u32 s61, s61, 0
	s_cmp_ge_i32 s62, s43
	s_mov_b32 s26, s62
	s_cbranch_scc0 .LBB0_228
	v_pk_mul_f32 v[200:201], v[126:127], 0.5 op_sel_hi:[1,0]
	v_pk_mul_f32 v[202:203], v[124:125], 0.5 op_sel_hi:[1,0]
	v_pk_mul_f32 v[204:205], v[122:123], 0.5 op_sel_hi:[1,0]
	v_pk_mul_f32 v[206:207], v[120:121], 0.5 op_sel_hi:[1,0]
	v_pk_mul_f32 v[210:211], v[110:111], 0.5 op_sel_hi:[1,0]
	v_pk_mul_f32 v[208:209], v[108:109], 0.5 op_sel_hi:[1,0]
	v_pk_mul_f32 v[198:199], v[102:103], 0.5 op_sel_hi:[1,0]
	v_pk_mul_f32 v[196:197], v[100:101], 0.5 op_sel_hi:[1,0]
	v_pk_mul_f32 v[194:195], v[118:119], 0.5 op_sel_hi:[1,0]
	v_pk_mul_f32 v[192:193], v[116:117], 0.5 op_sel_hi:[1,0]
	v_pk_mul_f32 v[190:191], v[114:115], 0.5 op_sel_hi:[1,0]
	v_pk_mul_f32 v[188:189], v[112:113], 0.5 op_sel_hi:[1,0]
	v_pk_mul_f32 v[186:187], v[94:95], 0.5 op_sel_hi:[1,0]
	v_pk_mul_f32 v[184:185], v[92:93], 0.5 op_sel_hi:[1,0]
	v_pk_mul_f32 v[182:183], v[86:87], 0.5 op_sel_hi:[1,0]
	v_pk_mul_f32 v[180:181], v[84:85], 0.5 op_sel_hi:[1,0]
	v_pk_mul_f32 v[178:179], v[106:107], 0.5 op_sel_hi:[1,0]
	v_pk_mul_f32 v[176:177], v[104:105], 0.5 op_sel_hi:[1,0]
	v_pk_mul_f32 v[174:175], v[98:99], 0.5 op_sel_hi:[1,0]
	v_pk_mul_f32 v[172:173], v[96:97], 0.5 op_sel_hi:[1,0]
	v_pk_mul_f32 v[170:171], v[78:79], 0.5 op_sel_hi:[1,0]
	v_pk_mul_f32 v[168:169], v[76:77], 0.5 op_sel_hi:[1,0]
	v_pk_mul_f32 v[166:167], v[74:75], 0.5 op_sel_hi:[1,0]
	v_pk_mul_f32 v[164:165], v[72:73], 0.5 op_sel_hi:[1,0]
	v_pk_mul_f32 v[160:161], v[90:91], 0.5 op_sel_hi:[1,0]
	v_pk_mul_f32 v[158:159], v[88:89], 0.5 op_sel_hi:[1,0]
	v_pk_mul_f32 v[156:157], v[82:83], 0.5 op_sel_hi:[1,0]
	v_pk_mul_f32 v[154:155], v[80:81], 0.5 op_sel_hi:[1,0]
	v_pk_mul_f32 v[152:153], v[70:71], 0.5 op_sel_hi:[1,0]
	v_pk_mul_f32 v[150:151], v[68:69], 0.5 op_sel_hi:[1,0]
	v_pk_mul_f32 v[148:149], v[66:67], 0.5 op_sel_hi:[1,0]
	v_pk_mul_f32 v[146:147], v[64:65], 0.5 op_sel_hi:[1,0]
	v_pk_mul_f32 v[144:145], v[62:63], 0.5 op_sel_hi:[1,0]
	v_pk_mul_f32 v[142:143], v[60:61], 0.5 op_sel_hi:[1,0]
	v_pk_mul_f32 v[126:127], v[58:59], 0.5 op_sel_hi:[1,0]
	v_pk_mul_f32 v[124:125], v[56:57], 0.5 op_sel_hi:[1,0]
	v_pk_mul_f32 v[122:123], v[46:47], 0.5 op_sel_hi:[1,0]
	v_pk_mul_f32 v[120:121], v[44:45], 0.5 op_sel_hi:[1,0]
	v_pk_mul_f32 v[118:119], v[38:39], 0.5 op_sel_hi:[1,0]
	v_pk_mul_f32 v[116:117], v[36:37], 0.5 op_sel_hi:[1,0]
	v_pk_mul_f32 v[114:115], v[54:55], 0.5 op_sel_hi:[1,0]
	v_pk_mul_f32 v[112:113], v[52:53], 0.5 op_sel_hi:[1,0]
	v_pk_mul_f32 v[110:111], v[50:51], 0.5 op_sel_hi:[1,0]
	v_pk_mul_f32 v[108:109], v[48:49], 0.5 op_sel_hi:[1,0]
	v_pk_mul_f32 v[106:107], v[30:31], 0.5 op_sel_hi:[1,0]
	v_pk_mul_f32 v[104:105], v[28:29], 0.5 op_sel_hi:[1,0]
	v_pk_mul_f32 v[102:103], v[22:23], 0.5 op_sel_hi:[1,0]
	v_pk_mul_f32 v[100:101], v[20:21], 0.5 op_sel_hi:[1,0]
	v_pk_mul_f32 v[98:99], v[42:43], 0.5 op_sel_hi:[1,0]
	v_pk_mul_f32 v[96:97], v[40:41], 0.5 op_sel_hi:[1,0]
	v_pk_mul_f32 v[94:95], v[34:35], 0.5 op_sel_hi:[1,0]
	v_pk_mul_f32 v[92:93], v[32:33], 0.5 op_sel_hi:[1,0]
	v_pk_mul_f32 v[90:91], v[14:15], 0.5 op_sel_hi:[1,0]
	v_pk_mul_f32 v[88:89], v[12:13], 0.5 op_sel_hi:[1,0]
	v_pk_mul_f32 v[86:87], v[10:11], 0.5 op_sel_hi:[1,0]
	v_pk_mul_f32 v[84:85], v[8:9], 0.5 op_sel_hi:[1,0]
	v_pk_mul_f32 v[82:83], v[26:27], 0.5 op_sel_hi:[1,0]
	v_pk_mul_f32 v[80:81], v[24:25], 0.5 op_sel_hi:[1,0]
	v_pk_mul_f32 v[78:79], v[18:19], 0.5 op_sel_hi:[1,0]
	v_pk_mul_f32 v[76:77], v[16:17], 0.5 op_sel_hi:[1,0]
	v_pk_mul_f32 v[74:75], v[6:7], 0.5 op_sel_hi:[1,0]
	v_pk_mul_f32 v[72:73], v[4:5], 0.5 op_sel_hi:[1,0]
	v_pk_mul_f32 v[70:71], v[2:3], 0.5 op_sel_hi:[1,0]
	v_pk_mul_f32 v[68:69], v[0:1], 0.5 op_sel_hi:[1,0]

.LBB0_323:
	ds_read_b128 v[128:131], v222
	ds_read_b128 v[132:135], v222 offset:1024
	ds_read_b128 v[136:139], v222 offset:2048
	ds_read_b128 v[140:143], v222 offset:3072
	ds_read_b128 v[144:147], v223
	ds_read_b128 v[148:151], v223 offset:1024
	ds_read_b128 v[152:155], v223 offset:2048
	ds_read_b128 v[156:159], v223 offset:3072
	s_add_i32 s53, s50, 2
	s_add_u32 s54, s0, 0x80
	s_addc_u32 s51, s1, 0
	s_cmp_eq_u32 s78, s50
	s_cselect_b32 s50, s46, s54
	s_cselect_b32 s51, s47, s51
	s_cselect_b32 s55, s49, s52
	s_cselect_b32 s54, s48, s33
	v_lshl_add_u64 v[160:161], s[0:1], 0, v[176:177]
	s_add_i32 m0, s71, 0xc000
	ds_read_b128 v[184:187], v224
	ds_read_b128 v[188:191], v224 offset:1024
	ds_read_b128 v[192:195], v224 offset:2048
	ds_read_b128 v[196:199], v224 offset:3072
	ds_read_b128 v[200:203], v224 offset:4096
	ds_read_b128 v[204:207], v224 offset:5120
	ds_read_b128 v[208:211], v224 offset:6144
	ds_read_b128 v[212:215], v224 offset:7168
	global_load_lds_dwordx4 v[160:161], off
	v_lshl_add_u64 v[160:161], s[0:1], 0, v[178:179]
	s_add_i32 m0, s71, 0xe000
	s_nop 0
	global_load_lds_dwordx4 v[160:161], off
	s_waitcnt vmcnt(8)
	s_waitcnt lgkmcnt(0)
	s_barrier
	s_setprio 1
	s_waitcnt lgkmcnt(0)
	v_mfma_f32_16x16x32_bf16 v[124:127], v[128:131], v[184:187], v[124:127]
	v_mfma_f32_16x16x32_bf16 v[124:127], v[132:135], v[188:191], v[124:127]
	v_mfma_f32_16x16x32_bf16 v[120:123], v[140:143], v[188:191], v[120:123]
	v_mfma_f32_16x16x32_bf16 v[120:123], v[136:139], v[184:187], v[120:123]
	v_mfma_f32_16x16x32_bf16 v[108:111], v[128:131], v[192:195], v[108:111]
	v_mfma_f32_16x16x32_bf16 v[108:111], v[132:135], v[196:199], v[108:111]
	v_mfma_f32_16x16x32_bf16 v[104:107], v[140:143], v[196:199], v[104:107]
	v_mfma_f32_16x16x32_bf16 v[104:107], v[136:139], v[192:195], v[104:107]
	v_mfma_f32_16x16x32_bf16 v[92:95], v[128:131], v[200:203], v[92:95]
	v_mfma_f32_16x16x32_bf16 v[92:95], v[132:135], v[204:207], v[92:95]
	v_mfma_f32_16x16x32_bf16 v[88:91], v[140:143], v[204:207], v[88:91]
	v_mfma_f32_16x16x32_bf16 v[88:91], v[136:139], v[200:203], v[88:91]
	v_mfma_f32_16x16x32_bf16 v[76:79], v[128:131], v[208:211], v[76:79]
	v_mfma_f32_16x16x32_bf16 v[76:79], v[132:135], v[212:215], v[76:79]
	v_mfma_f32_16x16x32_bf16 v[72:75], v[140:143], v[212:215], v[72:75]
	v_mfma_f32_16x16x32_bf16 v[72:75], v[136:139], v[208:211], v[72:75]
	s_setprio 0
	s_setprio 1
	v_mfma_f32_16x16x32_bf16 v[116:119], v[144:147], v[184:187], v[116:119]
	v_mfma_f32_16x16x32_bf16 v[116:119], v[148:151], v[188:191], v[116:119]
	v_mfma_f32_16x16x32_bf16 v[112:115], v[156:159], v[188:191], v[112:115]
	v_mfma_f32_16x16x32_bf16 v[112:115], v[152:155], v[184:187], v[112:115]
	v_mfma_f32_16x16x32_bf16 v[100:103], v[144:147], v[192:195], v[100:103]
	v_mfma_f32_16x16x32_bf16 v[100:103], v[148:151], v[196:199], v[100:103]
	v_mfma_f32_16x16x32_bf16 v[96:99], v[156:159], v[196:199], v[96:99]
	v_mfma_f32_16x16x32_bf16 v[96:99], v[152:155], v[192:195], v[96:99]
	v_mfma_f32_16x16x32_bf16 v[84:87], v[144:147], v[200:203], v[84:87]
	v_mfma_f32_16x16x32_bf16 v[84:87], v[148:151], v[204:207], v[84:87]
	v_mfma_f32_16x16x32_bf16 v[80:83], v[156:159], v[204:207], v[80:83]
	v_mfma_f32_16x16x32_bf16 v[80:83], v[152:155], v[200:203], v[80:83]
	v_mfma_f32_16x16x32_bf16 v[68:71], v[144:147], v[208:211], v[68:71]
	v_mfma_f32_16x16x32_bf16 v[68:71], v[148:151], v[212:215], v[68:71]
	v_mfma_f32_16x16x32_bf16 v[64:67], v[156:159], v[212:215], v[64:67]
	v_mfma_f32_16x16x32_bf16 v[64:67], v[152:155], v[208:211], v[64:67]
	s_setprio 0
	s_barrier
	s_add_i32 s60, s82, s70
	v_lshl_add_u64 v[160:161], s[54:55], 0, v[166:167]
	s_mov_b32 m0, s60
	ds_read_b128 v[184:187], v224 offset:16384
	ds_read_b128 v[188:191], v224 offset:17408
	ds_read_b128 v[192:195], v224 offset:18432
	ds_read_b128 v[196:199], v224 offset:19456
	ds_read_b128 v[200:203], v224 offset:20480
	ds_read_b128 v[204:207], v224 offset:21504
	ds_read_b128 v[208:211], v224 offset:22528
	ds_read_b128 v[212:215], v224 offset:23552
	global_load_lds_dwordx4 v[160:161], off
	s_add_i32 m0, s60, 0x2000
	v_lshl_add_u64 v[216:217], s[54:55], 0, v[170:171]
	s_add_u32 s54, s54, s10
	s_addc_u32 s55, s55, s11
	s_add_i32 s60, s83, s70
	global_load_lds_dwordx4 v[216:217], off
	v_lshl_add_u64 v[218:219], s[54:55], 0, v[166:167]
	s_mov_b32 m0, s60
	v_lshl_add_u64 v[230:231], s[54:55], 0, v[170:171]
	global_load_lds_dwordx4 v[218:219], off
	s_add_i32 m0, s60, 0x2000
	v_lshl_add_u64 v[232:233], s[50:51], 0, v[164:165]
	global_load_lds_dwordx4 v[230:231], off
	s_mov_b32 m0, s71
	v_lshl_add_u64 v[234:235], s[50:51], 0, v[168:169]
	global_load_lds_dwordx4 v[232:233], off
	s_mov_b32 m0, s72
	s_nop 0
	global_load_lds_dwordx4 v[234:235], off
	s_waitcnt vmcnt(8)
	s_waitcnt lgkmcnt(0)
	s_barrier
	s_setprio 1
	s_waitcnt lgkmcnt(0)
	v_mfma_f32_16x16x32_bf16 v[60:63], v[128:131], v[184:187], v[60:63]
	v_mfma_f32_16x16x32_bf16 v[60:63], v[132:135], v[188:191], v[60:63]
	v_mfma_f32_16x16x32_bf16 v[56:59], v[140:143], v[188:191], v[56:59]
	v_mfma_f32_16x16x32_bf16 v[56:59], v[136:139], v[184:187], v[56:59]
	v_mfma_f32_16x16x32_bf16 v[44:47], v[128:131], v[192:195], v[44:47]
	v_mfma_f32_16x16x32_bf16 v[44:47], v[132:135], v[196:199], v[44:47]
	v_mfma_f32_16x16x32_bf16 v[40:43], v[140:143], v[196:199], v[40:43]
	v_mfma_f32_16x16x32_bf16 v[40:43], v[136:139], v[192:195], v[40:43]
	v_mfma_f32_16x16x32_bf16 v[28:31], v[128:131], v[200:203], v[28:31]
	v_mfma_f32_16x16x32_bf16 v[28:31], v[132:135], v[204:207], v[28:31]
	v_mfma_f32_16x16x32_bf16 v[24:27], v[140:143], v[204:207], v[24:27]
	v_mfma_f32_16x16x32_bf16 v[24:27], v[136:139], v[200:203], v[24:27]
	v_mfma_f32_16x16x32_bf16 v[12:15], v[128:131], v[208:211], v[12:15]
	v_mfma_f32_16x16x32_bf16 v[12:15], v[132:135], v[212:215], v[12:15]
	v_mfma_f32_16x16x32_bf16 v[8:11], v[140:143], v[212:215], v[8:11]
	v_mfma_f32_16x16x32_bf16 v[8:11], v[136:139], v[208:211], v[8:11]
	s_setprio 0
	s_setprio 1
	v_mfma_f32_16x16x32_bf16 v[52:55], v[144:147], v[184:187], v[52:55]
	v_mfma_f32_16x16x32_bf16 v[52:55], v[148:151], v[188:191], v[52:55]
	v_mfma_f32_16x16x32_bf16 v[48:51], v[156:159], v[188:191], v[48:51]
	v_mfma_f32_16x16x32_bf16 v[48:51], v[152:155], v[184:187], v[48:51]
	v_mfma_f32_16x16x32_bf16 v[36:39], v[144:147], v[192:195], v[36:39]
	v_mfma_f32_16x16x32_bf16 v[36:39], v[148:151], v[196:199], v[36:39]
	v_mfma_f32_16x16x32_bf16 v[32:35], v[156:159], v[196:199], v[32:35]
	v_mfma_f32_16x16x32_bf16 v[32:35], v[152:155], v[192:195], v[32:35]
	v_mfma_f32_16x16x32_bf16 v[20:23], v[144:147], v[200:203], v[20:23]
	v_mfma_f32_16x16x32_bf16 v[20:23], v[148:151], v[204:207], v[20:23]
	v_mfma_f32_16x16x32_bf16 v[16:19], v[156:159], v[204:207], v[16:19]
	v_mfma_f32_16x16x32_bf16 v[16:19], v[152:155], v[200:203], v[16:19]
	v_mfma_f32_16x16x32_bf16 v[4:7], v[144:147], v[208:211], v[4:7]
	v_mfma_f32_16x16x32_bf16 v[4:7], v[148:151], v[212:215], v[4:7]
	v_mfma_f32_16x16x32_bf16 v[0:3], v[156:159], v[212:215], v[0:3]
	v_mfma_f32_16x16x32_bf16 v[0:3], v[152:155], v[208:211], v[0:3]
	s_setprio 0
	s_barrier
	s_add_i32 s54, 0, 0x18000
	s_add_i32 s55, 0, 0x1c000
	v_add_u32_e32 v140, s54, v221
	v_add_u32_e32 v156, s55, v221
	ds_read_b128 v[128:131], v140
	ds_read_b128 v[132:135], v140 offset:1024
	ds_read_b128 v[136:139], v140 offset:2048
	ds_read_b128 v[140:143], v140 offset:3072
	ds_read_b128 v[144:147], v156
	ds_read_b128 v[148:151], v156 offset:1024
	ds_read_b128 v[152:155], v156 offset:2048
	ds_read_b128 v[156:159], v156 offset:3072
	s_add_u32 s50, s50, s10
	s_addc_u32 s51, s51, s11
	s_mov_b32 m0, s73
	v_lshl_add_u64 v[236:237], s[50:51], 0, v[164:165]
	ds_read_b128 v[184:187], v224 offset:32768
	ds_read_b128 v[188:191], v224 offset:33792
	ds_read_b128 v[192:195], v224 offset:34816
	ds_read_b128 v[196:199], v224 offset:35840
	ds_read_b128 v[200:203], v224 offset:36864
	ds_read_b128 v[204:207], v224 offset:37888
	ds_read_b128 v[208:211], v224 offset:38912
	ds_read_b128 v[212:215], v224 offset:39936
	global_load_lds_dwordx4 v[236:237], off
	v_lshl_add_u64 v[236:237], s[50:51], 0, v[168:169]
	s_mov_b32 m0, s74
	s_nop 0
	global_load_lds_dwordx4 v[236:237], off
	s_waitcnt vmcnt(8)
	s_waitcnt lgkmcnt(0)
	s_barrier
	s_setprio 1
	s_waitcnt lgkmcnt(0)
	v_mfma_f32_16x16x32_bf16 v[124:127], v[128:131], v[184:187], v[124:127]
	v_mfma_f32_16x16x32_bf16 v[124:127], v[132:135], v[188:191], v[124:127]
	v_mfma_f32_16x16x32_bf16 v[120:123], v[140:143], v[188:191], v[120:123]
	v_mfma_f32_16x16x32_bf16 v[120:123], v[136:139], v[184:187], v[120:123]
	v_mfma_f32_16x16x32_bf16 v[108:111], v[128:131], v[192:195], v[108:111]
	v_mfma_f32_16x16x32_bf16 v[108:111], v[132:135], v[196:199], v[108:111]
	v_mfma_f32_16x16x32_bf16 v[104:107], v[140:143], v[196:199], v[104:107]
	v_mfma_f32_16x16x32_bf16 v[104:107], v[136:139], v[192:195], v[104:107]
	v_mfma_f32_16x16x32_bf16 v[92:95], v[128:131], v[200:203], v[92:95]
	v_mfma_f32_16x16x32_bf16 v[92:95], v[132:135], v[204:207], v[92:95]
	v_mfma_f32_16x16x32_bf16 v[88:91], v[140:143], v[204:207], v[88:91]
	v_mfma_f32_16x16x32_bf16 v[88:91], v[136:139], v[200:203], v[88:91]
	v_mfma_f32_16x16x32_bf16 v[76:79], v[128:131], v[208:211], v[76:79]
	v_mfma_f32_16x16x32_bf16 v[76:79], v[132:135], v[212:215], v[76:79]
	v_mfma_f32_16x16x32_bf16 v[72:75], v[140:143], v[212:215], v[72:75]
	v_mfma_f32_16x16x32_bf16 v[72:75], v[136:139], v[208:211], v[72:75]
	s_setprio 0
	s_setprio 1
	v_mfma_f32_16x16x32_bf16 v[116:119], v[144:147], v[184:187], v[116:119]
	v_mfma_f32_16x16x32_bf16 v[116:119], v[148:151], v[188:191], v[116:119]
	v_mfma_f32_16x16x32_bf16 v[112:115], v[156:159], v[188:191], v[112:115]
	v_mfma_f32_16x16x32_bf16 v[112:115], v[152:155], v[184:187], v[112:115]
	v_mfma_f32_16x16x32_bf16 v[100:103], v[144:147], v[192:195], v[100:103]
	v_mfma_f32_16x16x32_bf16 v[100:103], v[148:151], v[196:199], v[100:103]
	v_mfma_f32_16x16x32_bf16 v[96:99], v[156:159], v[196:199], v[96:99]
	v_mfma_f32_16x16x32_bf16 v[96:99], v[152:155], v[192:195], v[96:99]
	v_mfma_f32_16x16x32_bf16 v[84:87], v[144:147], v[200:203], v[84:87]
	v_mfma_f32_16x16x32_bf16 v[84:87], v[148:151], v[204:207], v[84:87]
	v_mfma_f32_16x16x32_bf16 v[80:83], v[156:159], v[204:207], v[80:83]
	v_mfma_f32_16x16x32_bf16 v[80:83], v[152:155], v[200:203], v[80:83]
	v_mfma_f32_16x16x32_bf16 v[68:71], v[144:147], v[208:211], v[68:71]
	v_mfma_f32_16x16x32_bf16 v[68:71], v[148:151], v[212:215], v[68:71]
	v_mfma_f32_16x16x32_bf16 v[64:67], v[156:159], v[212:215], v[64:67]
	v_mfma_f32_16x16x32_bf16 v[64:67], v[152:155], v[208:211], v[64:67]
	s_setprio 0
	s_barrier
	s_add_i32 s50, s54, s70
	v_lshl_add_u64 v[160:161], v[160:161], 0, s[36:37]
	s_mov_b32 m0, s50
	ds_read_b128 v[184:187], v224 offset:49152
	ds_read_b128 v[188:191], v224 offset:50176
	ds_read_b128 v[192:195], v224 offset:51200
	ds_read_b128 v[196:199], v224 offset:52224
	ds_read_b128 v[200:203], v224 offset:53248
	ds_read_b128 v[204:207], v224 offset:54272
	ds_read_b128 v[208:211], v224 offset:55296
	ds_read_b128 v[212:215], v224 offset:56320
	global_load_lds_dwordx4 v[160:161], off
	v_lshl_add_u64 v[160:161], v[216:217], 0, s[36:37]
	s_add_i32 m0, s50, 0x2000
	s_add_i32 s50, s55, s70
	global_load_lds_dwordx4 v[160:161], off
	v_lshl_add_u64 v[160:161], v[218:219], 0, s[36:37]
	s_mov_b32 m0, s50
	s_nop 0
	global_load_lds_dwordx4 v[160:161], off
	v_lshl_add_u64 v[160:161], v[230:231], 0, s[36:37]
	s_add_i32 m0, s50, 0x2000
	s_nop 0
	global_load_lds_dwordx4 v[160:161], off
	v_lshl_add_u64 v[160:161], v[232:233], 0, s[36:37]
	s_mov_b32 m0, s76
	s_nop 0
	global_load_lds_dwordx4 v[160:161], off
	v_lshl_add_u64 v[160:161], v[234:235], 0, s[36:37]
	s_mov_b32 m0, s77
	s_nop 0
	global_load_lds_dwordx4 v[160:161], off
	s_waitcnt vmcnt(8)
	s_waitcnt lgkmcnt(0)
	s_barrier
	s_setprio 1
	s_waitcnt lgkmcnt(0)
	v_mfma_f32_16x16x32_bf16 v[60:63], v[128:131], v[184:187], v[60:63]
	v_mfma_f32_16x16x32_bf16 v[60:63], v[132:135], v[188:191], v[60:63]
	v_mfma_f32_16x16x32_bf16 v[56:59], v[140:143], v[188:191], v[56:59]
	v_mfma_f32_16x16x32_bf16 v[56:59], v[136:139], v[184:187], v[56:59]
	v_mfma_f32_16x16x32_bf16 v[44:47], v[128:131], v[192:195], v[44:47]
	v_mfma_f32_16x16x32_bf16 v[44:47], v[132:135], v[196:199], v[44:47]
	v_mfma_f32_16x16x32_bf16 v[40:43], v[140:143], v[196:199], v[40:43]
	v_mfma_f32_16x16x32_bf16 v[40:43], v[136:139], v[192:195], v[40:43]
	v_mfma_f32_16x16x32_bf16 v[28:31], v[128:131], v[200:203], v[28:31]
	v_mfma_f32_16x16x32_bf16 v[28:31], v[132:135], v[204:207], v[28:31]
	v_mfma_f32_16x16x32_bf16 v[24:27], v[140:143], v[204:207], v[24:27]
	v_mfma_f32_16x16x32_bf16 v[24:27], v[136:139], v[200:203], v[24:27]
	v_mfma_f32_16x16x32_bf16 v[12:15], v[128:131], v[208:211], v[12:15]
	v_mfma_f32_16x16x32_bf16 v[12:15], v[132:135], v[212:215], v[12:15]
	v_mfma_f32_16x16x32_bf16 v[8:11], v[140:143], v[212:215], v[8:11]
	v_mfma_f32_16x16x32_bf16 v[8:11], v[136:139], v[208:211], v[8:11]
	s_setprio 0
	s_setprio 1
	v_mfma_f32_16x16x32_bf16 v[52:55], v[144:147], v[184:187], v[52:55]
	v_mfma_f32_16x16x32_bf16 v[52:55], v[148:151], v[188:191], v[52:55]
	v_mfma_f32_16x16x32_bf16 v[48:51], v[156:159], v[188:191], v[48:51]
	v_mfma_f32_16x16x32_bf16 v[48:51], v[152:155], v[184:187], v[48:51]
	v_mfma_f32_16x16x32_bf16 v[36:39], v[144:147], v[192:195], v[36:39]
	v_mfma_f32_16x16x32_bf16 v[36:39], v[148:151], v[196:199], v[36:39]
	v_mfma_f32_16x16x32_bf16 v[32:35], v[156:159], v[196:199], v[32:35]
	v_mfma_f32_16x16x32_bf16 v[32:35], v[152:155], v[192:195], v[32:35]
	v_mfma_f32_16x16x32_bf16 v[20:23], v[144:147], v[200:203], v[20:23]
	v_mfma_f32_16x16x32_bf16 v[20:23], v[148:151], v[204:207], v[20:23]
	v_mfma_f32_16x16x32_bf16 v[16:19], v[156:159], v[204:207], v[16:19]
	v_mfma_f32_16x16x32_bf16 v[16:19], v[152:155], v[200:203], v[16:19]
	v_mfma_f32_16x16x32_bf16 v[4:7], v[144:147], v[208:211], v[4:7]
	v_mfma_f32_16x16x32_bf16 v[4:7], v[148:151], v[212:215], v[4:7]
	v_mfma_f32_16x16x32_bf16 v[0:3], v[156:159], v[212:215], v[0:3]
	v_mfma_f32_16x16x32_bf16 v[0:3], v[152:155], v[208:211], v[0:3]
	s_setprio 0
	s_barrier
	s_add_u32 s0, s0, 0x100
	s_addc_u32 s1, s1, 0
	s_add_u32 s33, s33, 0x100
	s_addc_u32 s52, s52, 0
	s_cmp_ge_i32 s53, s75
	s_mov_b32 s50, s53
	s_cbranch_scc0 .LBB0_323

.LBB0_592:
	ds_read_b128 v[144:147], v157
	ds_read_b128 v[148:151], v157 offset:1024
	ds_read_b128 v[164:167], v157 offset:2048
	ds_read_b128 v[168:171], v157 offset:3072
	ds_read_b128 v[172:175], v158
	ds_read_b128 v[176:179], v158 offset:1024
	ds_read_b128 v[180:183], v158 offset:2048
	ds_read_b128 v[184:187], v158 offset:3072
	s_add_i32 s64, s34, 2
	s_add_u32 s65, s30, 0x80
	s_addc_u32 s35, s31, 0
	s_cmp_eq_u32 s49, s34
	s_cselect_b32 s34, s2, s65
	s_cselect_b32 s35, s3, s35
	s_cselect_b32 s67, s29, s63
	s_cselect_b32 s66, s28, s62
	v_lshl_add_u64 v[152:153], s[30:31], 0, v[136:137]
	s_add_i32 m0, s41, 0xc000
	ds_read_b128 v[188:191], v159
	ds_read_b128 v[192:195], v159 offset:1024
	ds_read_b128 v[196:199], v159 offset:2048
	ds_read_b128 v[200:203], v159 offset:3072
	ds_read_b128 v[204:207], v159 offset:4096
	ds_read_b128 v[208:211], v159 offset:5120
	ds_read_b128 v[212:215], v159 offset:6144
	ds_read_b128 v[216:219], v159 offset:7168
	global_load_lds_dwordx4 v[152:153], off
	v_lshl_add_u64 v[152:153], s[30:31], 0, v[138:139]
	s_add_i32 m0, s41, 0xe000
	s_nop 0
	global_load_lds_dwordx4 v[152:153], off
	s_waitcnt vmcnt(8)
	s_waitcnt lgkmcnt(0)
	s_barrier
	s_setprio 1
	s_waitcnt lgkmcnt(0)
	v_mfma_f32_16x16x32_bf16 v[120:123], v[144:147], v[188:191], v[120:123]
	v_mfma_f32_16x16x32_bf16 v[120:123], v[148:151], v[192:195], v[120:123]
	v_mfma_f32_16x16x32_bf16 v[124:127], v[168:171], v[192:195], v[124:127]
	v_mfma_f32_16x16x32_bf16 v[124:127], v[164:167], v[188:191], v[124:127]
	v_mfma_f32_16x16x32_bf16 v[108:111], v[144:147], v[196:199], v[108:111]
	v_mfma_f32_16x16x32_bf16 v[108:111], v[148:151], v[200:203], v[108:111]
	v_mfma_f32_16x16x32_bf16 v[104:107], v[168:171], v[200:203], v[104:107]
	v_mfma_f32_16x16x32_bf16 v[104:107], v[164:167], v[196:199], v[104:107]
	v_mfma_f32_16x16x32_bf16 v[92:95], v[144:147], v[204:207], v[92:95]
	v_mfma_f32_16x16x32_bf16 v[92:95], v[148:151], v[208:211], v[92:95]
	v_mfma_f32_16x16x32_bf16 v[88:91], v[168:171], v[208:211], v[88:91]
	v_mfma_f32_16x16x32_bf16 v[88:91], v[164:167], v[204:207], v[88:91]
	v_mfma_f32_16x16x32_bf16 v[76:79], v[144:147], v[212:215], v[76:79]
	v_mfma_f32_16x16x32_bf16 v[76:79], v[148:151], v[216:219], v[76:79]
	v_mfma_f32_16x16x32_bf16 v[72:75], v[168:171], v[216:219], v[72:75]
	v_mfma_f32_16x16x32_bf16 v[72:75], v[164:167], v[212:215], v[72:75]
	s_setprio 0
	s_setprio 1
	v_mfma_f32_16x16x32_bf16 v[116:119], v[172:175], v[188:191], v[116:119]
	v_mfma_f32_16x16x32_bf16 v[116:119], v[176:179], v[192:195], v[116:119]
	v_mfma_f32_16x16x32_bf16 v[112:115], v[184:187], v[192:195], v[112:115]
	v_mfma_f32_16x16x32_bf16 v[112:115], v[180:183], v[188:191], v[112:115]
	v_mfma_f32_16x16x32_bf16 v[100:103], v[172:175], v[196:199], v[100:103]
	v_mfma_f32_16x16x32_bf16 v[100:103], v[176:179], v[200:203], v[100:103]
	v_mfma_f32_16x16x32_bf16 v[96:99], v[184:187], v[200:203], v[96:99]
	v_mfma_f32_16x16x32_bf16 v[96:99], v[180:183], v[196:199], v[96:99]
	v_mfma_f32_16x16x32_bf16 v[84:87], v[172:175], v[204:207], v[84:87]
	v_mfma_f32_16x16x32_bf16 v[84:87], v[176:179], v[208:211], v[84:87]
	v_mfma_f32_16x16x32_bf16 v[80:83], v[184:187], v[208:211], v[80:83]
	v_mfma_f32_16x16x32_bf16 v[80:83], v[180:183], v[204:207], v[80:83]
	v_mfma_f32_16x16x32_bf16 v[68:71], v[172:175], v[212:215], v[68:71]
	v_mfma_f32_16x16x32_bf16 v[68:71], v[176:179], v[216:219], v[68:71]
	v_mfma_f32_16x16x32_bf16 v[64:67], v[184:187], v[216:219], v[64:67]
	v_mfma_f32_16x16x32_bf16 v[64:67], v[180:183], v[212:215], v[64:67]
	s_setprio 0
	s_barrier
	s_add_i32 s65, s52, s40
	v_lshl_add_u64 v[152:153], s[66:67], 0, v[130:131]
	s_mov_b32 m0, s65
	ds_read_b128 v[188:191], v159 offset:16384
	ds_read_b128 v[192:195], v159 offset:17408
	ds_read_b128 v[196:199], v159 offset:18432
	ds_read_b128 v[200:203], v159 offset:19456
	ds_read_b128 v[204:207], v159 offset:20480
	ds_read_b128 v[208:211], v159 offset:21504
	ds_read_b128 v[212:215], v159 offset:22528
	ds_read_b128 v[216:219], v159 offset:23552
	global_load_lds_dwordx4 v[152:153], off
	s_add_i32 m0, s65, 0x2000
	v_lshl_add_u64 v[160:161], s[66:67], 0, v[134:135]
	s_add_u32 s66, s66, s8
	s_addc_u32 s67, s67, s9
	s_add_i32 s65, s53, s40
	global_load_lds_dwordx4 v[160:161], off
	v_lshl_add_u64 v[222:223], s[66:67], 0, v[130:131]
	s_mov_b32 m0, s65
	v_lshl_add_u64 v[224:225], s[66:67], 0, v[134:135]
	global_load_lds_dwordx4 v[222:223], off
	s_add_i32 m0, s65, 0x2000
	v_lshl_add_u64 v[226:227], s[34:35], 0, v[128:129]
	global_load_lds_dwordx4 v[224:225], off
	s_mov_b32 m0, s41
	v_lshl_add_u64 v[228:229], s[34:35], 0, v[132:133]
	global_load_lds_dwordx4 v[226:227], off
	s_mov_b32 m0, s42
	s_nop 0
	global_load_lds_dwordx4 v[228:229], off
	s_waitcnt vmcnt(8)
	s_waitcnt lgkmcnt(0)
	s_barrier
	s_setprio 1
	s_waitcnt lgkmcnt(0)
	v_mfma_f32_16x16x32_bf16 v[60:63], v[144:147], v[188:191], v[60:63]
	v_mfma_f32_16x16x32_bf16 v[60:63], v[148:151], v[192:195], v[60:63]
	v_mfma_f32_16x16x32_bf16 v[56:59], v[168:171], v[192:195], v[56:59]
	v_mfma_f32_16x16x32_bf16 v[56:59], v[164:167], v[188:191], v[56:59]
	v_mfma_f32_16x16x32_bf16 v[44:47], v[144:147], v[196:199], v[44:47]
	v_mfma_f32_16x16x32_bf16 v[44:47], v[148:151], v[200:203], v[44:47]
	v_mfma_f32_16x16x32_bf16 v[40:43], v[168:171], v[200:203], v[40:43]
	v_mfma_f32_16x16x32_bf16 v[40:43], v[164:167], v[196:199], v[40:43]
	v_mfma_f32_16x16x32_bf16 v[28:31], v[144:147], v[204:207], v[28:31]
	v_mfma_f32_16x16x32_bf16 v[28:31], v[148:151], v[208:211], v[28:31]
	v_mfma_f32_16x16x32_bf16 v[24:27], v[168:171], v[208:211], v[24:27]
	v_mfma_f32_16x16x32_bf16 v[24:27], v[164:167], v[204:207], v[24:27]
	v_mfma_f32_16x16x32_bf16 v[12:15], v[144:147], v[212:215], v[12:15]
	v_mfma_f32_16x16x32_bf16 v[12:15], v[148:151], v[216:219], v[12:15]
	v_mfma_f32_16x16x32_bf16 v[8:11], v[168:171], v[216:219], v[8:11]
	v_mfma_f32_16x16x32_bf16 v[8:11], v[164:167], v[212:215], v[8:11]
	s_setprio 0
	s_setprio 1
	v_mfma_f32_16x16x32_bf16 v[52:55], v[172:175], v[188:191], v[52:55]
	v_mfma_f32_16x16x32_bf16 v[52:55], v[176:179], v[192:195], v[52:55]
	v_mfma_f32_16x16x32_bf16 v[48:51], v[184:187], v[192:195], v[48:51]
	v_mfma_f32_16x16x32_bf16 v[48:51], v[180:183], v[188:191], v[48:51]
	v_mfma_f32_16x16x32_bf16 v[36:39], v[172:175], v[196:199], v[36:39]
	v_mfma_f32_16x16x32_bf16 v[36:39], v[176:179], v[200:203], v[36:39]
	v_mfma_f32_16x16x32_bf16 v[32:35], v[184:187], v[200:203], v[32:35]
	v_mfma_f32_16x16x32_bf16 v[32:35], v[180:183], v[196:199], v[32:35]
	v_mfma_f32_16x16x32_bf16 v[20:23], v[172:175], v[204:207], v[20:23]
	v_mfma_f32_16x16x32_bf16 v[20:23], v[176:179], v[208:211], v[20:23]
	v_mfma_f32_16x16x32_bf16 v[16:19], v[184:187], v[208:211], v[16:19]
	v_mfma_f32_16x16x32_bf16 v[16:19], v[180:183], v[204:207], v[16:19]
	v_mfma_f32_16x16x32_bf16 v[4:7], v[172:175], v[212:215], v[4:7]
	v_mfma_f32_16x16x32_bf16 v[4:7], v[176:179], v[216:219], v[4:7]
	v_mfma_f32_16x16x32_bf16 v[0:3], v[184:187], v[216:219], v[0:3]
	v_mfma_f32_16x16x32_bf16 v[0:3], v[180:183], v[212:215], v[0:3]
	s_setprio 0
	s_barrier
	s_add_i32 s65, 0, 0x18000
	s_add_i32 s66, 0, 0x1c000
	v_add_u32_e32 v168, s65, v155
	v_add_u32_e32 v184, s66, v155
	ds_read_b128 v[144:147], v168
	ds_read_b128 v[148:151], v168 offset:1024
	ds_read_b128 v[164:167], v168 offset:2048
	ds_read_b128 v[168:171], v168 offset:3072
	ds_read_b128 v[172:175], v184
	ds_read_b128 v[176:179], v184 offset:1024
	ds_read_b128 v[180:183], v184 offset:2048
	ds_read_b128 v[184:187], v184 offset:3072
	s_add_u32 s34, s34, s8
	s_addc_u32 s35, s35, s9
	s_mov_b32 m0, s43
	v_lshl_add_u64 v[230:231], s[34:35], 0, v[128:129]
	ds_read_b128 v[188:191], v159 offset:32768
	ds_read_b128 v[192:195], v159 offset:33792
	ds_read_b128 v[196:199], v159 offset:34816
	ds_read_b128 v[200:203], v159 offset:35840
	ds_read_b128 v[204:207], v159 offset:36864
	ds_read_b128 v[208:211], v159 offset:37888
	ds_read_b128 v[212:215], v159 offset:38912
	ds_read_b128 v[216:219], v159 offset:39936
	global_load_lds_dwordx4 v[230:231], off
	v_lshl_add_u64 v[230:231], s[34:35], 0, v[132:133]
	s_mov_b32 m0, s44
	s_nop 0
	global_load_lds_dwordx4 v[230:231], off
	s_waitcnt vmcnt(8)
	s_waitcnt lgkmcnt(0)
	s_barrier
	s_setprio 1
	s_waitcnt lgkmcnt(0)
	v_mfma_f32_16x16x32_bf16 v[120:123], v[144:147], v[188:191], v[120:123]
	v_mfma_f32_16x16x32_bf16 v[120:123], v[148:151], v[192:195], v[120:123]
	v_mfma_f32_16x16x32_bf16 v[124:127], v[168:171], v[192:195], v[124:127]
	v_mfma_f32_16x16x32_bf16 v[124:127], v[164:167], v[188:191], v[124:127]
	v_mfma_f32_16x16x32_bf16 v[108:111], v[144:147], v[196:199], v[108:111]
	v_mfma_f32_16x16x32_bf16 v[108:111], v[148:151], v[200:203], v[108:111]
	v_mfma_f32_16x16x32_bf16 v[104:107], v[168:171], v[200:203], v[104:107]
	v_mfma_f32_16x16x32_bf16 v[104:107], v[164:167], v[196:199], v[104:107]
	v_mfma_f32_16x16x32_bf16 v[92:95], v[144:147], v[204:207], v[92:95]
	v_mfma_f32_16x16x32_bf16 v[92:95], v[148:151], v[208:211], v[92:95]
	v_mfma_f32_16x16x32_bf16 v[88:91], v[168:171], v[208:211], v[88:91]
	v_mfma_f32_16x16x32_bf16 v[88:91], v[164:167], v[204:207], v[88:91]
	v_mfma_f32_16x16x32_bf16 v[76:79], v[144:147], v[212:215], v[76:79]
	v_mfma_f32_16x16x32_bf16 v[76:79], v[148:151], v[216:219], v[76:79]
	v_mfma_f32_16x16x32_bf16 v[72:75], v[168:171], v[216:219], v[72:75]
	v_mfma_f32_16x16x32_bf16 v[72:75], v[164:167], v[212:215], v[72:75]
	s_setprio 0
	s_setprio 1
	v_mfma_f32_16x16x32_bf16 v[116:119], v[172:175], v[188:191], v[116:119]
	v_mfma_f32_16x16x32_bf16 v[116:119], v[176:179], v[192:195], v[116:119]
	v_mfma_f32_16x16x32_bf16 v[112:115], v[184:187], v[192:195], v[112:115]
	v_mfma_f32_16x16x32_bf16 v[112:115], v[180:183], v[188:191], v[112:115]
	v_mfma_f32_16x16x32_bf16 v[100:103], v[172:175], v[196:199], v[100:103]
	v_mfma_f32_16x16x32_bf16 v[100:103], v[176:179], v[200:203], v[100:103]
	v_mfma_f32_16x16x32_bf16 v[96:99], v[184:187], v[200:203], v[96:99]
	v_mfma_f32_16x16x32_bf16 v[96:99], v[180:183], v[196:199], v[96:99]
	v_mfma_f32_16x16x32_bf16 v[84:87], v[172:175], v[204:207], v[84:87]
	v_mfma_f32_16x16x32_bf16 v[84:87], v[176:179], v[208:211], v[84:87]
	v_mfma_f32_16x16x32_bf16 v[80:83], v[184:187], v[208:211], v[80:83]
	v_mfma_f32_16x16x32_bf16 v[80:83], v[180:183], v[204:207], v[80:83]
	v_mfma_f32_16x16x32_bf16 v[68:71], v[172:175], v[212:215], v[68:71]
	v_mfma_f32_16x16x32_bf16 v[68:71], v[176:179], v[216:219], v[68:71]
	v_mfma_f32_16x16x32_bf16 v[64:67], v[184:187], v[216:219], v[64:67]
	v_mfma_f32_16x16x32_bf16 v[64:67], v[180:183], v[212:215], v[64:67]
	s_setprio 0
	s_barrier
	s_add_i32 s34, s65, s40
	v_lshl_add_u64 v[152:153], v[152:153], 0, s[14:15]
	s_mov_b32 m0, s34
	ds_read_b128 v[188:191], v159 offset:49152
	ds_read_b128 v[192:195], v159 offset:50176
	ds_read_b128 v[196:199], v159 offset:51200
	ds_read_b128 v[200:203], v159 offset:52224
	ds_read_b128 v[204:207], v159 offset:53248
	ds_read_b128 v[208:211], v159 offset:54272
	ds_read_b128 v[212:215], v159 offset:55296
	ds_read_b128 v[216:219], v159 offset:56320
	global_load_lds_dwordx4 v[152:153], off
	v_lshl_add_u64 v[152:153], v[160:161], 0, s[14:15]
	s_add_i32 m0, s34, 0x2000
	s_add_i32 s34, s66, s40
	global_load_lds_dwordx4 v[152:153], off
	v_lshl_add_u64 v[152:153], v[222:223], 0, s[14:15]
	s_mov_b32 m0, s34
	s_nop 0
	global_load_lds_dwordx4 v[152:153], off
	v_lshl_add_u64 v[152:153], v[224:225], 0, s[14:15]
	s_add_i32 m0, s34, 0x2000
	s_nop 0
	global_load_lds_dwordx4 v[152:153], off
	v_lshl_add_u64 v[152:153], v[226:227], 0, s[14:15]
	s_mov_b32 m0, s46
	s_nop 0
	global_load_lds_dwordx4 v[152:153], off
	v_lshl_add_u64 v[152:153], v[228:229], 0, s[14:15]
	s_mov_b32 m0, s47
	s_nop 0
	global_load_lds_dwordx4 v[152:153], off
	s_waitcnt vmcnt(8)
	s_waitcnt lgkmcnt(0)
	s_barrier
	s_setprio 1
	s_waitcnt lgkmcnt(0)
	v_mfma_f32_16x16x32_bf16 v[60:63], v[144:147], v[188:191], v[60:63]
	v_mfma_f32_16x16x32_bf16 v[60:63], v[148:151], v[192:195], v[60:63]
	v_mfma_f32_16x16x32_bf16 v[56:59], v[168:171], v[192:195], v[56:59]
	v_mfma_f32_16x16x32_bf16 v[56:59], v[164:167], v[188:191], v[56:59]
	v_mfma_f32_16x16x32_bf16 v[44:47], v[144:147], v[196:199], v[44:47]
	v_mfma_f32_16x16x32_bf16 v[44:47], v[148:151], v[200:203], v[44:47]
	v_mfma_f32_16x16x32_bf16 v[40:43], v[168:171], v[200:203], v[40:43]
	v_mfma_f32_16x16x32_bf16 v[40:43], v[164:167], v[196:199], v[40:43]
	v_mfma_f32_16x16x32_bf16 v[28:31], v[144:147], v[204:207], v[28:31]
	v_mfma_f32_16x16x32_bf16 v[28:31], v[148:151], v[208:211], v[28:31]
	v_mfma_f32_16x16x32_bf16 v[24:27], v[168:171], v[208:211], v[24:27]
	v_mfma_f32_16x16x32_bf16 v[24:27], v[164:167], v[204:207], v[24:27]
	v_mfma_f32_16x16x32_bf16 v[12:15], v[144:147], v[212:215], v[12:15]
	v_mfma_f32_16x16x32_bf16 v[12:15], v[148:151], v[216:219], v[12:15]
	v_mfma_f32_16x16x32_bf16 v[8:11], v[168:171], v[216:219], v[8:11]
	v_mfma_f32_16x16x32_bf16 v[8:11], v[164:167], v[212:215], v[8:11]
	s_setprio 0
	s_setprio 1
	v_mfma_f32_16x16x32_bf16 v[52:55], v[172:175], v[188:191], v[52:55]
	v_mfma_f32_16x16x32_bf16 v[52:55], v[176:179], v[192:195], v[52:55]
	v_mfma_f32_16x16x32_bf16 v[48:51], v[184:187], v[192:195], v[48:51]
	v_mfma_f32_16x16x32_bf16 v[48:51], v[180:183], v[188:191], v[48:51]
	v_mfma_f32_16x16x32_bf16 v[36:39], v[172:175], v[196:199], v[36:39]
	v_mfma_f32_16x16x32_bf16 v[36:39], v[176:179], v[200:203], v[36:39]
	v_mfma_f32_16x16x32_bf16 v[32:35], v[184:187], v[200:203], v[32:35]
	v_mfma_f32_16x16x32_bf16 v[32:35], v[180:183], v[196:199], v[32:35]
	v_mfma_f32_16x16x32_bf16 v[20:23], v[172:175], v[204:207], v[20:23]
	v_mfma_f32_16x16x32_bf16 v[20:23], v[176:179], v[208:211], v[20:23]
	v_mfma_f32_16x16x32_bf16 v[16:19], v[184:187], v[208:211], v[16:19]
	v_mfma_f32_16x16x32_bf16 v[16:19], v[180:183], v[204:207], v[16:19]
	v_mfma_f32_16x16x32_bf16 v[4:7], v[172:175], v[212:215], v[4:7]
	v_mfma_f32_16x16x32_bf16 v[4:7], v[176:179], v[216:219], v[4:7]
	v_mfma_f32_16x16x32_bf16 v[0:3], v[184:187], v[216:219], v[0:3]
	v_mfma_f32_16x16x32_bf16 v[0:3], v[180:183], v[212:215], v[0:3]
	s_setprio 0
	s_barrier
	s_add_u32 s30, s30, 0x100
	s_addc_u32 s31, s31, 0
	s_add_u32 s62, s62, 0x100
	s_addc_u32 s63, s63, 0
	s_cmp_ge_i32 s64, s48
	s_mov_b32 s34, s64
	s_cbranch_scc0 .LBB0_592

.LBB0_763:
	ds_read_b128 v[128:131], v181
	ds_read_b128 v[132:135], v181 offset:1024
	ds_read_b128 v[136:139], v181 offset:2048
	ds_read_b128 v[140:143], v181 offset:3072
	ds_read_b128 v[144:147], v182
	ds_read_b128 v[148:151], v182 offset:1024
	ds_read_b128 v[168:171], v182 offset:2048
	ds_read_b128 v[172:175], v182 offset:3072
	s_add_i32 s54, s26, 2
	s_add_u32 s55, s24, 0x80
	s_addc_u32 s27, s25, 0
	s_cmp_eq_u32 s43, s26
	s_cselect_b32 s26, s2, s55
	s_cselect_b32 s27, s3, s27
	s_cselect_b32 s61, s23, s53
	s_cselect_b32 s60, s22, s52
	v_lshl_add_u64 v[176:177], s[24:25], 0, v[160:161]
	s_add_i32 m0, s35, 0xc000
	ds_read_b128 v[184:187], v183
	ds_read_b128 v[188:191], v183 offset:1024
	ds_read_b128 v[192:195], v183 offset:2048
	ds_read_b128 v[196:199], v183 offset:3072
	ds_read_b128 v[200:203], v183 offset:4096
	ds_read_b128 v[204:207], v183 offset:5120
	ds_read_b128 v[208:211], v183 offset:6144
	ds_read_b128 v[212:215], v183 offset:7168
	global_load_lds_dwordx4 v[176:177], off
	v_lshl_add_u64 v[176:177], s[24:25], 0, v[162:163]
	s_add_i32 m0, s35, 0xe000
	s_nop 0
	global_load_lds_dwordx4 v[176:177], off
	s_waitcnt vmcnt(8)
	s_waitcnt lgkmcnt(0)
	s_barrier
	s_setprio 1
	s_waitcnt lgkmcnt(0)
	v_mfma_f32_16x16x32_bf16 v[120:123], v[128:131], v[184:187], v[120:123]
	v_mfma_f32_16x16x32_bf16 v[120:123], v[132:135], v[188:191], v[120:123]
	v_mfma_f32_16x16x32_bf16 v[124:127], v[140:143], v[188:191], v[124:127]
	v_mfma_f32_16x16x32_bf16 v[124:127], v[136:139], v[184:187], v[124:127]
	v_mfma_f32_16x16x32_bf16 v[108:111], v[128:131], v[192:195], v[108:111]
	v_mfma_f32_16x16x32_bf16 v[108:111], v[132:135], v[196:199], v[108:111]
	v_mfma_f32_16x16x32_bf16 v[104:107], v[140:143], v[196:199], v[104:107]
	v_mfma_f32_16x16x32_bf16 v[104:107], v[136:139], v[192:195], v[104:107]
	v_mfma_f32_16x16x32_bf16 v[92:95], v[128:131], v[200:203], v[92:95]
	v_mfma_f32_16x16x32_bf16 v[92:95], v[132:135], v[204:207], v[92:95]
	v_mfma_f32_16x16x32_bf16 v[88:91], v[140:143], v[204:207], v[88:91]
	v_mfma_f32_16x16x32_bf16 v[88:91], v[136:139], v[200:203], v[88:91]
	v_mfma_f32_16x16x32_bf16 v[76:79], v[128:131], v[208:211], v[76:79]
	v_mfma_f32_16x16x32_bf16 v[76:79], v[132:135], v[212:215], v[76:79]
	v_mfma_f32_16x16x32_bf16 v[72:75], v[140:143], v[212:215], v[72:75]
	v_mfma_f32_16x16x32_bf16 v[72:75], v[136:139], v[208:211], v[72:75]
	s_setprio 0
	s_setprio 1
	v_mfma_f32_16x16x32_bf16 v[116:119], v[144:147], v[184:187], v[116:119]
	v_mfma_f32_16x16x32_bf16 v[116:119], v[148:151], v[188:191], v[116:119]
	v_mfma_f32_16x16x32_bf16 v[112:115], v[172:175], v[188:191], v[112:115]
	v_mfma_f32_16x16x32_bf16 v[112:115], v[168:171], v[184:187], v[112:115]
	v_mfma_f32_16x16x32_bf16 v[100:103], v[144:147], v[192:195], v[100:103]
	v_mfma_f32_16x16x32_bf16 v[100:103], v[148:151], v[196:199], v[100:103]
	v_mfma_f32_16x16x32_bf16 v[96:99], v[172:175], v[196:199], v[96:99]
	v_mfma_f32_16x16x32_bf16 v[96:99], v[168:171], v[192:195], v[96:99]
	v_mfma_f32_16x16x32_bf16 v[84:87], v[144:147], v[200:203], v[84:87]
	v_mfma_f32_16x16x32_bf16 v[84:87], v[148:151], v[204:207], v[84:87]
	v_mfma_f32_16x16x32_bf16 v[80:83], v[172:175], v[204:207], v[80:83]
	v_mfma_f32_16x16x32_bf16 v[80:83], v[168:171], v[200:203], v[80:83]
	v_mfma_f32_16x16x32_bf16 v[68:71], v[144:147], v[208:211], v[68:71]
	v_mfma_f32_16x16x32_bf16 v[68:71], v[148:151], v[212:215], v[68:71]
	v_mfma_f32_16x16x32_bf16 v[64:67], v[172:175], v[212:215], v[64:67]
	v_mfma_f32_16x16x32_bf16 v[64:67], v[168:171], v[208:211], v[64:67]
	s_setprio 0
	s_barrier
	s_add_i32 s55, s46, s34
	v_lshl_add_u64 v[176:177], s[60:61], 0, v[154:155]
	s_mov_b32 m0, s55
	ds_read_b128 v[184:187], v183 offset:16384
	ds_read_b128 v[188:191], v183 offset:17408
	ds_read_b128 v[192:195], v183 offset:18432
	ds_read_b128 v[196:199], v183 offset:19456
	ds_read_b128 v[200:203], v183 offset:20480
	ds_read_b128 v[204:207], v183 offset:21504
	ds_read_b128 v[208:211], v183 offset:22528
	ds_read_b128 v[212:215], v183 offset:23552
	global_load_lds_dwordx4 v[176:177], off
	s_add_i32 m0, s55, 0x2000
	v_lshl_add_u64 v[216:217], s[60:61], 0, v[158:159]
	s_add_u32 s60, s60, s8
	s_addc_u32 s61, s61, s9
	s_add_i32 s55, s47, s34
	global_load_lds_dwordx4 v[216:217], off
	v_lshl_add_u64 v[218:219], s[60:61], 0, v[154:155]
	s_mov_b32 m0, s55
	v_lshl_add_u64 v[222:223], s[60:61], 0, v[158:159]
	global_load_lds_dwordx4 v[218:219], off
	s_add_i32 m0, s55, 0x2000
	v_lshl_add_u64 v[224:225], s[26:27], 0, v[152:153]
	global_load_lds_dwordx4 v[222:223], off
	s_mov_b32 m0, s35
	v_lshl_add_u64 v[226:227], s[26:27], 0, v[156:157]
	global_load_lds_dwordx4 v[224:225], off
	s_mov_b32 m0, s36
	s_nop 0
	global_load_lds_dwordx4 v[226:227], off
	s_waitcnt vmcnt(8)
	s_waitcnt lgkmcnt(0)
	s_barrier
	s_setprio 1
	s_waitcnt lgkmcnt(0)
	v_mfma_f32_16x16x32_bf16 v[60:63], v[128:131], v[184:187], v[60:63]
	v_mfma_f32_16x16x32_bf16 v[60:63], v[132:135], v[188:191], v[60:63]
	v_mfma_f32_16x16x32_bf16 v[56:59], v[140:143], v[188:191], v[56:59]
	v_mfma_f32_16x16x32_bf16 v[56:59], v[136:139], v[184:187], v[56:59]
	v_mfma_f32_16x16x32_bf16 v[44:47], v[128:131], v[192:195], v[44:47]
	v_mfma_f32_16x16x32_bf16 v[44:47], v[132:135], v[196:199], v[44:47]
	v_mfma_f32_16x16x32_bf16 v[40:43], v[140:143], v[196:199], v[40:43]
	v_mfma_f32_16x16x32_bf16 v[40:43], v[136:139], v[192:195], v[40:43]
	v_mfma_f32_16x16x32_bf16 v[28:31], v[128:131], v[200:203], v[28:31]
	v_mfma_f32_16x16x32_bf16 v[28:31], v[132:135], v[204:207], v[28:31]
	v_mfma_f32_16x16x32_bf16 v[24:27], v[140:143], v[204:207], v[24:27]
	v_mfma_f32_16x16x32_bf16 v[24:27], v[136:139], v[200:203], v[24:27]
	v_mfma_f32_16x16x32_bf16 v[12:15], v[128:131], v[208:211], v[12:15]
	v_mfma_f32_16x16x32_bf16 v[12:15], v[132:135], v[212:215], v[12:15]
	v_mfma_f32_16x16x32_bf16 v[8:11], v[140:143], v[212:215], v[8:11]
	v_mfma_f32_16x16x32_bf16 v[8:11], v[136:139], v[208:211], v[8:11]
	s_setprio 0
	s_setprio 1
	v_mfma_f32_16x16x32_bf16 v[52:55], v[144:147], v[184:187], v[52:55]
	v_mfma_f32_16x16x32_bf16 v[52:55], v[148:151], v[188:191], v[52:55]
	v_mfma_f32_16x16x32_bf16 v[48:51], v[172:175], v[188:191], v[48:51]
	v_mfma_f32_16x16x32_bf16 v[48:51], v[168:171], v[184:187], v[48:51]
	v_mfma_f32_16x16x32_bf16 v[36:39], v[144:147], v[192:195], v[36:39]
	v_mfma_f32_16x16x32_bf16 v[36:39], v[148:151], v[196:199], v[36:39]
	v_mfma_f32_16x16x32_bf16 v[32:35], v[172:175], v[196:199], v[32:35]
	v_mfma_f32_16x16x32_bf16 v[32:35], v[168:171], v[192:195], v[32:35]
	v_mfma_f32_16x16x32_bf16 v[20:23], v[144:147], v[200:203], v[20:23]
	v_mfma_f32_16x16x32_bf16 v[20:23], v[148:151], v[204:207], v[20:23]
	v_mfma_f32_16x16x32_bf16 v[16:19], v[172:175], v[204:207], v[16:19]
	v_mfma_f32_16x16x32_bf16 v[16:19], v[168:171], v[200:203], v[16:19]
	v_mfma_f32_16x16x32_bf16 v[4:7], v[144:147], v[208:211], v[4:7]
	v_mfma_f32_16x16x32_bf16 v[4:7], v[148:151], v[212:215], v[4:7]
	v_mfma_f32_16x16x32_bf16 v[0:3], v[172:175], v[212:215], v[0:3]
	v_mfma_f32_16x16x32_bf16 v[0:3], v[168:171], v[208:211], v[0:3]
	s_setprio 0
	s_barrier
	s_add_i32 s55, 0, 0x18000
	s_add_i32 s60, 0, 0x1c000
	v_add_u32_e32 v140, s55, v179
	v_add_u32_e32 v172, s60, v179
	ds_read_b128 v[128:131], v140
	ds_read_b128 v[132:135], v140 offset:1024
	ds_read_b128 v[136:139], v140 offset:2048
	ds_read_b128 v[140:143], v140 offset:3072
	ds_read_b128 v[144:147], v172
	ds_read_b128 v[148:151], v172 offset:1024
	ds_read_b128 v[168:171], v172 offset:2048
	ds_read_b128 v[172:175], v172 offset:3072
	s_add_u32 s26, s26, s8
	s_addc_u32 s27, s27, s9
	s_mov_b32 m0, s37
	v_lshl_add_u64 v[228:229], s[26:27], 0, v[152:153]
	ds_read_b128 v[184:187], v183 offset:32768
	ds_read_b128 v[188:191], v183 offset:33792
	ds_read_b128 v[192:195], v183 offset:34816
	ds_read_b128 v[196:199], v183 offset:35840
	ds_read_b128 v[200:203], v183 offset:36864
	ds_read_b128 v[204:207], v183 offset:37888
	ds_read_b128 v[208:211], v183 offset:38912
	ds_read_b128 v[212:215], v183 offset:39936
	global_load_lds_dwordx4 v[228:229], off
	v_lshl_add_u64 v[228:229], s[26:27], 0, v[156:157]
	s_mov_b32 m0, s38
	s_nop 0
	global_load_lds_dwordx4 v[228:229], off
	s_waitcnt vmcnt(8)
	s_waitcnt lgkmcnt(0)
	s_barrier
	s_setprio 1
	s_waitcnt lgkmcnt(0)
	v_mfma_f32_16x16x32_bf16 v[120:123], v[128:131], v[184:187], v[120:123]
	v_mfma_f32_16x16x32_bf16 v[120:123], v[132:135], v[188:191], v[120:123]
	v_mfma_f32_16x16x32_bf16 v[124:127], v[140:143], v[188:191], v[124:127]
	v_mfma_f32_16x16x32_bf16 v[124:127], v[136:139], v[184:187], v[124:127]
	v_mfma_f32_16x16x32_bf16 v[108:111], v[128:131], v[192:195], v[108:111]
	v_mfma_f32_16x16x32_bf16 v[108:111], v[132:135], v[196:199], v[108:111]
	v_mfma_f32_16x16x32_bf16 v[104:107], v[140:143], v[196:199], v[104:107]
	v_mfma_f32_16x16x32_bf16 v[104:107], v[136:139], v[192:195], v[104:107]
	v_mfma_f32_16x16x32_bf16 v[92:95], v[128:131], v[200:203], v[92:95]
	v_mfma_f32_16x16x32_bf16 v[92:95], v[132:135], v[204:207], v[92:95]
	v_mfma_f32_16x16x32_bf16 v[88:91], v[140:143], v[204:207], v[88:91]
	v_mfma_f32_16x16x32_bf16 v[88:91], v[136:139], v[200:203], v[88:91]
	v_mfma_f32_16x16x32_bf16 v[76:79], v[128:131], v[208:211], v[76:79]
	v_mfma_f32_16x16x32_bf16 v[76:79], v[132:135], v[212:215], v[76:79]
	v_mfma_f32_16x16x32_bf16 v[72:75], v[140:143], v[212:215], v[72:75]
	v_mfma_f32_16x16x32_bf16 v[72:75], v[136:139], v[208:211], v[72:75]
	s_setprio 0
	s_setprio 1
	v_mfma_f32_16x16x32_bf16 v[116:119], v[144:147], v[184:187], v[116:119]
	v_mfma_f32_16x16x32_bf16 v[116:119], v[148:151], v[188:191], v[116:119]
	v_mfma_f32_16x16x32_bf16 v[112:115], v[172:175], v[188:191], v[112:115]
	v_mfma_f32_16x16x32_bf16 v[112:115], v[168:171], v[184:187], v[112:115]
	v_mfma_f32_16x16x32_bf16 v[100:103], v[144:147], v[192:195], v[100:103]
	v_mfma_f32_16x16x32_bf16 v[100:103], v[148:151], v[196:199], v[100:103]
	v_mfma_f32_16x16x32_bf16 v[96:99], v[172:175], v[196:199], v[96:99]
	v_mfma_f32_16x16x32_bf16 v[96:99], v[168:171], v[192:195], v[96:99]
	v_mfma_f32_16x16x32_bf16 v[84:87], v[144:147], v[200:203], v[84:87]
	v_mfma_f32_16x16x32_bf16 v[84:87], v[148:151], v[204:207], v[84:87]
	v_mfma_f32_16x16x32_bf16 v[80:83], v[172:175], v[204:207], v[80:83]
	v_mfma_f32_16x16x32_bf16 v[80:83], v[168:171], v[200:203], v[80:83]
	v_mfma_f32_16x16x32_bf16 v[68:71], v[144:147], v[208:211], v[68:71]
	v_mfma_f32_16x16x32_bf16 v[68:71], v[148:151], v[212:215], v[68:71]
	v_mfma_f32_16x16x32_bf16 v[64:67], v[172:175], v[212:215], v[64:67]
	v_mfma_f32_16x16x32_bf16 v[64:67], v[168:171], v[208:211], v[64:67]
	s_setprio 0
	s_barrier
	s_add_i32 s26, s55, s34
	v_lshl_add_u64 v[176:177], v[176:177], 0, s[16:17]
	s_mov_b32 m0, s26
	ds_read_b128 v[184:187], v183 offset:49152
	ds_read_b128 v[188:191], v183 offset:50176
	ds_read_b128 v[192:195], v183 offset:51200
	ds_read_b128 v[196:199], v183 offset:52224
	ds_read_b128 v[200:203], v183 offset:53248
	ds_read_b128 v[204:207], v183 offset:54272
	ds_read_b128 v[208:211], v183 offset:55296
	ds_read_b128 v[212:215], v183 offset:56320
	global_load_lds_dwordx4 v[176:177], off
	v_lshl_add_u64 v[176:177], v[216:217], 0, s[16:17]
	s_add_i32 m0, s26, 0x2000
	s_add_i32 s26, s60, s34
	global_load_lds_dwordx4 v[176:177], off
	v_lshl_add_u64 v[176:177], v[218:219], 0, s[16:17]
	s_mov_b32 m0, s26
	s_nop 0
	global_load_lds_dwordx4 v[176:177], off
	v_lshl_add_u64 v[176:177], v[222:223], 0, s[16:17]
	s_add_i32 m0, s26, 0x2000
	s_nop 0
	global_load_lds_dwordx4 v[176:177], off
	v_lshl_add_u64 v[176:177], v[224:225], 0, s[16:17]
	s_mov_b32 m0, s40
	s_nop 0
	global_load_lds_dwordx4 v[176:177], off
	v_lshl_add_u64 v[176:177], v[226:227], 0, s[16:17]
	s_mov_b32 m0, s41
	s_nop 0
	global_load_lds_dwordx4 v[176:177], off
	s_waitcnt vmcnt(8)
	s_waitcnt lgkmcnt(0)
	s_barrier
	s_setprio 1
	s_waitcnt lgkmcnt(0)
	v_mfma_f32_16x16x32_bf16 v[60:63], v[128:131], v[184:187], v[60:63]
	v_mfma_f32_16x16x32_bf16 v[60:63], v[132:135], v[188:191], v[60:63]
	v_mfma_f32_16x16x32_bf16 v[56:59], v[140:143], v[188:191], v[56:59]
	v_mfma_f32_16x16x32_bf16 v[56:59], v[136:139], v[184:187], v[56:59]
	v_mfma_f32_16x16x32_bf16 v[44:47], v[128:131], v[192:195], v[44:47]
	v_mfma_f32_16x16x32_bf16 v[44:47], v[132:135], v[196:199], v[44:47]
	v_mfma_f32_16x16x32_bf16 v[40:43], v[140:143], v[196:199], v[40:43]
	v_mfma_f32_16x16x32_bf16 v[40:43], v[136:139], v[192:195], v[40:43]
	v_mfma_f32_16x16x32_bf16 v[28:31], v[128:131], v[200:203], v[28:31]
	v_mfma_f32_16x16x32_bf16 v[28:31], v[132:135], v[204:207], v[28:31]
	v_mfma_f32_16x16x32_bf16 v[24:27], v[140:143], v[204:207], v[24:27]
	v_mfma_f32_16x16x32_bf16 v[24:27], v[136:139], v[200:203], v[24:27]
	v_mfma_f32_16x16x32_bf16 v[12:15], v[128:131], v[208:211], v[12:15]
	v_mfma_f32_16x16x32_bf16 v[12:15], v[132:135], v[212:215], v[12:15]
	v_mfma_f32_16x16x32_bf16 v[8:11], v[140:143], v[212:215], v[8:11]
	v_mfma_f32_16x16x32_bf16 v[8:11], v[136:139], v[208:211], v[8:11]
	s_setprio 0
	s_setprio 1
	v_mfma_f32_16x16x32_bf16 v[52:55], v[144:147], v[184:187], v[52:55]
	v_mfma_f32_16x16x32_bf16 v[52:55], v[148:151], v[188:191], v[52:55]
	v_mfma_f32_16x16x32_bf16 v[48:51], v[172:175], v[188:191], v[48:51]
	v_mfma_f32_16x16x32_bf16 v[48:51], v[168:171], v[184:187], v[48:51]
	v_mfma_f32_16x16x32_bf16 v[36:39], v[144:147], v[192:195], v[36:39]
	v_mfma_f32_16x16x32_bf16 v[36:39], v[148:151], v[196:199], v[36:39]
	v_mfma_f32_16x16x32_bf16 v[32:35], v[172:175], v[196:199], v[32:35]
	v_mfma_f32_16x16x32_bf16 v[32:35], v[168:171], v[192:195], v[32:35]
	v_mfma_f32_16x16x32_bf16 v[20:23], v[144:147], v[200:203], v[20:23]
	v_mfma_f32_16x16x32_bf16 v[20:23], v[148:151], v[204:207], v[20:23]
	v_mfma_f32_16x16x32_bf16 v[16:19], v[172:175], v[204:207], v[16:19]
	v_mfma_f32_16x16x32_bf16 v[16:19], v[168:171], v[200:203], v[16:19]
	v_mfma_f32_16x16x32_bf16 v[4:7], v[144:147], v[208:211], v[4:7]
	v_mfma_f32_16x16x32_bf16 v[4:7], v[148:151], v[212:215], v[4:7]
	v_mfma_f32_16x16x32_bf16 v[0:3], v[172:175], v[212:215], v[0:3]
	v_mfma_f32_16x16x32_bf16 v[0:3], v[168:171], v[208:211], v[0:3]
	s_setprio 0
	s_barrier
	s_add_u32 s24, s24, 0x100
	s_addc_u32 s25, s25, 0
	s_add_u32 s52, s52, 0x100
	s_addc_u32 s53, s53, 0
	s_cmp_ge_i32 s54, s42
	s_mov_b32 s26, s54
	s_cbranch_scc0 .LBB0_763

.LBB0_849:
	ds_read_b128 v[112:115], v209
	ds_read_b128 v[116:119], v209 offset:1024
	ds_read_b128 v[120:123], v209 offset:2048
	ds_read_b128 v[128:131], v209 offset:3072
	ds_read_b128 v[144:147], v210
	ds_read_b128 v[148:151], v210 offset:1024
	ds_read_b128 v[152:155], v210 offset:2048
	ds_read_b128 v[156:159], v210 offset:3072
	s_add_i32 s62, s30, 2
	s_add_u32 s63, s28, 0x80
	s_addc_u32 s31, s29, 0
	s_cmp_eq_u32 s46, s30
	s_cselect_b32 s30, s4, s63
	s_cselect_b32 s31, s5, s31
	s_cselect_b32 s65, s27, s61
	s_cselect_b32 s64, s26, s60
	v_lshl_add_u64 v[204:205], s[28:29], 0, v[180:181]
	s_add_i32 m0, s38, 0xc000
	ds_read_b128 v[160:163], v211
	ds_read_b128 v[164:167], v211 offset:1024
	ds_read_b128 v[168:171], v211 offset:2048
	ds_read_b128 v[172:175], v211 offset:3072
	ds_read_b128 v[188:191], v211 offset:4096
	ds_read_b128 v[192:195], v211 offset:5120
	ds_read_b128 v[196:199], v211 offset:6144
	ds_read_b128 v[200:203], v211 offset:7168
	global_load_lds_dwordx4 v[204:205], off
	v_lshl_add_u64 v[204:205], s[28:29], 0, v[182:183]
	s_add_i32 m0, s38, 0xe000
	s_nop 0
	global_load_lds_dwordx4 v[204:205], off
	s_waitcnt vmcnt(8)
	s_waitcnt lgkmcnt(0)
	s_barrier
	s_setprio 1
	s_waitcnt lgkmcnt(0)
	v_mfma_f32_16x16x32_bf16 v[136:139], v[112:115], v[160:163], v[136:139]
	v_mfma_f32_16x16x32_bf16 v[136:139], v[116:119], v[164:167], v[136:139]
	v_mfma_f32_16x16x32_bf16 v[140:143], v[128:131], v[164:167], v[140:143]
	v_mfma_f32_16x16x32_bf16 v[140:143], v[120:123], v[160:163], v[140:143]
	v_mfma_f32_16x16x32_bf16 v[108:111], v[112:115], v[168:171], v[108:111]
	v_mfma_f32_16x16x32_bf16 v[108:111], v[116:119], v[172:175], v[108:111]
	v_mfma_f32_16x16x32_bf16 v[104:107], v[128:131], v[172:175], v[104:107]
	v_mfma_f32_16x16x32_bf16 v[104:107], v[120:123], v[168:171], v[104:107]
	v_mfma_f32_16x16x32_bf16 v[92:95], v[112:115], v[188:191], v[92:95]
	v_mfma_f32_16x16x32_bf16 v[92:95], v[116:119], v[192:195], v[92:95]
	v_mfma_f32_16x16x32_bf16 v[88:91], v[128:131], v[192:195], v[88:91]
	v_mfma_f32_16x16x32_bf16 v[88:91], v[120:123], v[188:191], v[88:91]
	v_mfma_f32_16x16x32_bf16 v[76:79], v[112:115], v[196:199], v[76:79]
	v_mfma_f32_16x16x32_bf16 v[76:79], v[116:119], v[200:203], v[76:79]
	v_mfma_f32_16x16x32_bf16 v[72:75], v[128:131], v[200:203], v[72:75]
	v_mfma_f32_16x16x32_bf16 v[72:75], v[120:123], v[196:199], v[72:75]
	s_setprio 0
	s_setprio 1
	v_mfma_f32_16x16x32_bf16 v[132:135], v[144:147], v[160:163], v[132:135]
	v_mfma_f32_16x16x32_bf16 v[132:135], v[148:151], v[164:167], v[132:135]
	v_mfma_f32_16x16x32_bf16 v[124:127], v[156:159], v[164:167], v[124:127]
	v_mfma_f32_16x16x32_bf16 v[124:127], v[152:155], v[160:163], v[124:127]
	v_mfma_f32_16x16x32_bf16 v[100:103], v[144:147], v[168:171], v[100:103]
	v_mfma_f32_16x16x32_bf16 v[100:103], v[148:151], v[172:175], v[100:103]
	v_mfma_f32_16x16x32_bf16 v[96:99], v[156:159], v[172:175], v[96:99]
	v_mfma_f32_16x16x32_bf16 v[96:99], v[152:155], v[168:171], v[96:99]
	v_mfma_f32_16x16x32_bf16 v[84:87], v[144:147], v[188:191], v[84:87]
	v_mfma_f32_16x16x32_bf16 v[84:87], v[148:151], v[192:195], v[84:87]
	v_mfma_f32_16x16x32_bf16 v[80:83], v[156:159], v[192:195], v[80:83]
	v_mfma_f32_16x16x32_bf16 v[80:83], v[152:155], v[188:191], v[80:83]
	v_mfma_f32_16x16x32_bf16 v[68:71], v[144:147], v[196:199], v[68:71]
	v_mfma_f32_16x16x32_bf16 v[68:71], v[148:151], v[200:203], v[68:71]
	v_mfma_f32_16x16x32_bf16 v[64:67], v[156:159], v[200:203], v[64:67]
	v_mfma_f32_16x16x32_bf16 v[64:67], v[152:155], v[196:199], v[64:67]
	s_setprio 0
	s_barrier
	s_add_i32 s63, s50, s37
	v_lshl_add_u64 v[204:205], s[64:65], 0, v[176:177]
	s_mov_b32 m0, s63
	ds_read_b128 v[160:163], v211 offset:16384
	ds_read_b128 v[164:167], v211 offset:17408
	ds_read_b128 v[168:171], v211 offset:18432
	ds_read_b128 v[172:175], v211 offset:19456
	ds_read_b128 v[188:191], v211 offset:20480
	ds_read_b128 v[192:195], v211 offset:21504
	ds_read_b128 v[196:199], v211 offset:22528
	ds_read_b128 v[200:203], v211 offset:23552
	global_load_lds_dwordx4 v[204:205], off
	s_add_i32 m0, s63, 0x2000
	v_lshl_add_u64 v[214:215], s[64:65], 0, v[178:179]
	s_add_u32 s64, s64, s10
	s_addc_u32 s65, s65, s11
	s_add_i32 s63, s51, s37
	global_load_lds_dwordx4 v[214:215], off
	v_lshl_add_u64 v[216:217], s[64:65], 0, v[176:177]
	s_mov_b32 m0, s63
	v_lshl_add_u64 v[218:219], s[64:65], 0, v[178:179]
	global_load_lds_dwordx4 v[216:217], off
	s_add_i32 m0, s63, 0x2000
	v_lshl_add_u64 v[222:223], s[30:31], 0, v[176:177]
	global_load_lds_dwordx4 v[218:219], off
	s_mov_b32 m0, s38
	v_lshl_add_u64 v[224:225], s[30:31], 0, v[178:179]
	global_load_lds_dwordx4 v[222:223], off
	s_mov_b32 m0, s39
	s_nop 0
	global_load_lds_dwordx4 v[224:225], off
	s_waitcnt vmcnt(8)
	s_waitcnt lgkmcnt(0)
	s_barrier
	s_setprio 1
	s_waitcnt lgkmcnt(0)
	v_mfma_f32_16x16x32_bf16 v[60:63], v[112:115], v[160:163], v[60:63]
	v_mfma_f32_16x16x32_bf16 v[60:63], v[116:119], v[164:167], v[60:63]
	v_mfma_f32_16x16x32_bf16 v[56:59], v[128:131], v[164:167], v[56:59]
	v_mfma_f32_16x16x32_bf16 v[56:59], v[120:123], v[160:163], v[56:59]
	v_mfma_f32_16x16x32_bf16 v[44:47], v[112:115], v[168:171], v[44:47]
	v_mfma_f32_16x16x32_bf16 v[44:47], v[116:119], v[172:175], v[44:47]
	v_mfma_f32_16x16x32_bf16 v[40:43], v[128:131], v[172:175], v[40:43]
	v_mfma_f32_16x16x32_bf16 v[40:43], v[120:123], v[168:171], v[40:43]
	v_mfma_f32_16x16x32_bf16 v[28:31], v[112:115], v[188:191], v[28:31]
	v_mfma_f32_16x16x32_bf16 v[28:31], v[116:119], v[192:195], v[28:31]
	v_mfma_f32_16x16x32_bf16 v[24:27], v[128:131], v[192:195], v[24:27]
	v_mfma_f32_16x16x32_bf16 v[24:27], v[120:123], v[188:191], v[24:27]
	v_mfma_f32_16x16x32_bf16 v[12:15], v[112:115], v[196:199], v[12:15]
	v_mfma_f32_16x16x32_bf16 v[12:15], v[116:119], v[200:203], v[12:15]
	v_mfma_f32_16x16x32_bf16 v[8:11], v[128:131], v[200:203], v[8:11]
	v_mfma_f32_16x16x32_bf16 v[8:11], v[120:123], v[196:199], v[8:11]
	s_setprio 0
	s_setprio 1
	v_mfma_f32_16x16x32_bf16 v[52:55], v[144:147], v[160:163], v[52:55]
	v_mfma_f32_16x16x32_bf16 v[52:55], v[148:151], v[164:167], v[52:55]
	v_mfma_f32_16x16x32_bf16 v[48:51], v[156:159], v[164:167], v[48:51]
	v_mfma_f32_16x16x32_bf16 v[48:51], v[152:155], v[160:163], v[48:51]
	v_mfma_f32_16x16x32_bf16 v[36:39], v[144:147], v[168:171], v[36:39]
	v_mfma_f32_16x16x32_bf16 v[36:39], v[148:151], v[172:175], v[36:39]
	v_mfma_f32_16x16x32_bf16 v[32:35], v[156:159], v[172:175], v[32:35]
	v_mfma_f32_16x16x32_bf16 v[32:35], v[152:155], v[168:171], v[32:35]
	v_mfma_f32_16x16x32_bf16 v[20:23], v[144:147], v[188:191], v[20:23]
	v_mfma_f32_16x16x32_bf16 v[20:23], v[148:151], v[192:195], v[20:23]
	v_mfma_f32_16x16x32_bf16 v[16:19], v[156:159], v[192:195], v[16:19]
	v_mfma_f32_16x16x32_bf16 v[16:19], v[152:155], v[188:191], v[16:19]
	v_mfma_f32_16x16x32_bf16 v[4:7], v[144:147], v[196:199], v[4:7]
	v_mfma_f32_16x16x32_bf16 v[4:7], v[148:151], v[200:203], v[4:7]
	v_mfma_f32_16x16x32_bf16 v[0:3], v[156:159], v[200:203], v[0:3]
	v_mfma_f32_16x16x32_bf16 v[0:3], v[152:155], v[196:199], v[0:3]
	s_setprio 0
	s_barrier
	s_add_i32 s63, 0, 0x18000
	s_add_i32 s64, 0, 0x1c000
	v_add_u32_e32 v128, s63, v207
	v_add_u32_e32 v156, s64, v207
	ds_read_b128 v[112:115], v128
	ds_read_b128 v[116:119], v128 offset:1024
	ds_read_b128 v[120:123], v128 offset:2048
	ds_read_b128 v[128:131], v128 offset:3072
	ds_read_b128 v[144:147], v156
	ds_read_b128 v[148:151], v156 offset:1024
	ds_read_b128 v[152:155], v156 offset:2048
	ds_read_b128 v[156:159], v156 offset:3072
	s_add_u32 s30, s30, s10
	s_addc_u32 s31, s31, s11
	s_mov_b32 m0, s40
	v_lshl_add_u64 v[226:227], s[30:31], 0, v[176:177]
	ds_read_b128 v[160:163], v211 offset:32768
	ds_read_b128 v[164:167], v211 offset:33792
	ds_read_b128 v[168:171], v211 offset:34816
	ds_read_b128 v[172:175], v211 offset:35840
	ds_read_b128 v[188:191], v211 offset:36864
	ds_read_b128 v[192:195], v211 offset:37888
	ds_read_b128 v[196:199], v211 offset:38912
	ds_read_b128 v[200:203], v211 offset:39936
	global_load_lds_dwordx4 v[226:227], off
	v_lshl_add_u64 v[226:227], s[30:31], 0, v[178:179]
	s_mov_b32 m0, s41
	s_nop 0
	global_load_lds_dwordx4 v[226:227], off
	s_waitcnt vmcnt(8)
	s_waitcnt lgkmcnt(0)
	s_barrier
	s_setprio 1
	s_waitcnt lgkmcnt(0)
	v_mfma_f32_16x16x32_bf16 v[136:139], v[112:115], v[160:163], v[136:139]
	v_mfma_f32_16x16x32_bf16 v[136:139], v[116:119], v[164:167], v[136:139]
	v_mfma_f32_16x16x32_bf16 v[140:143], v[128:131], v[164:167], v[140:143]
	v_mfma_f32_16x16x32_bf16 v[140:143], v[120:123], v[160:163], v[140:143]
	v_mfma_f32_16x16x32_bf16 v[108:111], v[112:115], v[168:171], v[108:111]
	v_mfma_f32_16x16x32_bf16 v[108:111], v[116:119], v[172:175], v[108:111]
	v_mfma_f32_16x16x32_bf16 v[104:107], v[128:131], v[172:175], v[104:107]
	v_mfma_f32_16x16x32_bf16 v[104:107], v[120:123], v[168:171], v[104:107]
	v_mfma_f32_16x16x32_bf16 v[92:95], v[112:115], v[188:191], v[92:95]
	v_mfma_f32_16x16x32_bf16 v[92:95], v[116:119], v[192:195], v[92:95]
	v_mfma_f32_16x16x32_bf16 v[88:91], v[128:131], v[192:195], v[88:91]
	v_mfma_f32_16x16x32_bf16 v[88:91], v[120:123], v[188:191], v[88:91]
	v_mfma_f32_16x16x32_bf16 v[76:79], v[112:115], v[196:199], v[76:79]
	v_mfma_f32_16x16x32_bf16 v[76:79], v[116:119], v[200:203], v[76:79]
	v_mfma_f32_16x16x32_bf16 v[72:75], v[128:131], v[200:203], v[72:75]
	v_mfma_f32_16x16x32_bf16 v[72:75], v[120:123], v[196:199], v[72:75]
	s_setprio 0
	s_setprio 1
	v_mfma_f32_16x16x32_bf16 v[132:135], v[144:147], v[160:163], v[132:135]
	v_mfma_f32_16x16x32_bf16 v[132:135], v[148:151], v[164:167], v[132:135]
	v_mfma_f32_16x16x32_bf16 v[124:127], v[156:159], v[164:167], v[124:127]
	v_mfma_f32_16x16x32_bf16 v[124:127], v[152:155], v[160:163], v[124:127]
	v_mfma_f32_16x16x32_bf16 v[100:103], v[144:147], v[168:171], v[100:103]
	v_mfma_f32_16x16x32_bf16 v[100:103], v[148:151], v[172:175], v[100:103]
	v_mfma_f32_16x16x32_bf16 v[96:99], v[156:159], v[172:175], v[96:99]
	v_mfma_f32_16x16x32_bf16 v[96:99], v[152:155], v[168:171], v[96:99]
	v_mfma_f32_16x16x32_bf16 v[84:87], v[144:147], v[188:191], v[84:87]
	v_mfma_f32_16x16x32_bf16 v[84:87], v[148:151], v[192:195], v[84:87]
	v_mfma_f32_16x16x32_bf16 v[80:83], v[156:159], v[192:195], v[80:83]
	v_mfma_f32_16x16x32_bf16 v[80:83], v[152:155], v[188:191], v[80:83]
	v_mfma_f32_16x16x32_bf16 v[68:71], v[144:147], v[196:199], v[68:71]
	v_mfma_f32_16x16x32_bf16 v[68:71], v[148:151], v[200:203], v[68:71]
	v_mfma_f32_16x16x32_bf16 v[64:67], v[156:159], v[200:203], v[64:67]
	v_mfma_f32_16x16x32_bf16 v[64:67], v[152:155], v[196:199], v[64:67]
	s_setprio 0
	s_barrier
	s_add_i32 s30, s63, s37
	v_lshl_add_u64 v[204:205], v[204:205], 0, s[18:19]
	s_mov_b32 m0, s30
	ds_read_b128 v[160:163], v211 offset:49152
	ds_read_b128 v[164:167], v211 offset:50176
	ds_read_b128 v[168:171], v211 offset:51200
	ds_read_b128 v[172:175], v211 offset:52224
	ds_read_b128 v[188:191], v211 offset:53248
	ds_read_b128 v[192:195], v211 offset:54272
	ds_read_b128 v[196:199], v211 offset:55296
	ds_read_b128 v[200:203], v211 offset:56320
	global_load_lds_dwordx4 v[204:205], off
	v_lshl_add_u64 v[204:205], v[214:215], 0, s[18:19]
	s_add_i32 m0, s30, 0x2000
	s_add_i32 s30, s64, s37
	global_load_lds_dwordx4 v[204:205], off
	v_lshl_add_u64 v[204:205], v[216:217], 0, s[18:19]
	s_mov_b32 m0, s30
	s_nop 0
	global_load_lds_dwordx4 v[204:205], off
	v_lshl_add_u64 v[204:205], v[218:219], 0, s[18:19]
	s_add_i32 m0, s30, 0x2000
	s_nop 0
	global_load_lds_dwordx4 v[204:205], off
	v_lshl_add_u64 v[204:205], v[222:223], 0, s[18:19]
	s_mov_b32 m0, s43
	s_nop 0
	global_load_lds_dwordx4 v[204:205], off
	v_lshl_add_u64 v[204:205], v[224:225], 0, s[18:19]
	s_mov_b32 m0, s44
	s_nop 0
	global_load_lds_dwordx4 v[204:205], off
	s_waitcnt vmcnt(8)
	s_waitcnt lgkmcnt(0)
	s_barrier
	s_setprio 1
	s_waitcnt lgkmcnt(0)
	v_mfma_f32_16x16x32_bf16 v[60:63], v[112:115], v[160:163], v[60:63]
	v_mfma_f32_16x16x32_bf16 v[60:63], v[116:119], v[164:167], v[60:63]
	v_mfma_f32_16x16x32_bf16 v[56:59], v[128:131], v[164:167], v[56:59]
	v_mfma_f32_16x16x32_bf16 v[56:59], v[120:123], v[160:163], v[56:59]
	v_mfma_f32_16x16x32_bf16 v[44:47], v[112:115], v[168:171], v[44:47]
	v_mfma_f32_16x16x32_bf16 v[44:47], v[116:119], v[172:175], v[44:47]
	v_mfma_f32_16x16x32_bf16 v[40:43], v[128:131], v[172:175], v[40:43]
	v_mfma_f32_16x16x32_bf16 v[40:43], v[120:123], v[168:171], v[40:43]
	v_mfma_f32_16x16x32_bf16 v[28:31], v[112:115], v[188:191], v[28:31]
	v_mfma_f32_16x16x32_bf16 v[28:31], v[116:119], v[192:195], v[28:31]
	v_mfma_f32_16x16x32_bf16 v[24:27], v[128:131], v[192:195], v[24:27]
	v_mfma_f32_16x16x32_bf16 v[24:27], v[120:123], v[188:191], v[24:27]
	v_mfma_f32_16x16x32_bf16 v[12:15], v[112:115], v[196:199], v[12:15]
	v_mfma_f32_16x16x32_bf16 v[12:15], v[116:119], v[200:203], v[12:15]
	v_mfma_f32_16x16x32_bf16 v[8:11], v[128:131], v[200:203], v[8:11]
	v_mfma_f32_16x16x32_bf16 v[8:11], v[120:123], v[196:199], v[8:11]
	s_setprio 0
	s_setprio 1
	v_mfma_f32_16x16x32_bf16 v[52:55], v[144:147], v[160:163], v[52:55]
	v_mfma_f32_16x16x32_bf16 v[52:55], v[148:151], v[164:167], v[52:55]
	v_mfma_f32_16x16x32_bf16 v[48:51], v[156:159], v[164:167], v[48:51]
	v_mfma_f32_16x16x32_bf16 v[48:51], v[152:155], v[160:163], v[48:51]
	v_mfma_f32_16x16x32_bf16 v[36:39], v[144:147], v[168:171], v[36:39]
	v_mfma_f32_16x16x32_bf16 v[36:39], v[148:151], v[172:175], v[36:39]
	v_mfma_f32_16x16x32_bf16 v[32:35], v[156:159], v[172:175], v[32:35]
	v_mfma_f32_16x16x32_bf16 v[32:35], v[152:155], v[168:171], v[32:35]
	v_mfma_f32_16x16x32_bf16 v[20:23], v[144:147], v[188:191], v[20:23]
	v_mfma_f32_16x16x32_bf16 v[20:23], v[148:151], v[192:195], v[20:23]
	v_mfma_f32_16x16x32_bf16 v[16:19], v[156:159], v[192:195], v[16:19]
	v_mfma_f32_16x16x32_bf16 v[16:19], v[152:155], v[188:191], v[16:19]
	v_mfma_f32_16x16x32_bf16 v[4:7], v[144:147], v[196:199], v[4:7]
	v_mfma_f32_16x16x32_bf16 v[4:7], v[148:151], v[200:203], v[4:7]
	v_mfma_f32_16x16x32_bf16 v[0:3], v[156:159], v[200:203], v[0:3]
	v_mfma_f32_16x16x32_bf16 v[0:3], v[152:155], v[196:199], v[0:3]
	s_setprio 0
	s_barrier
	s_add_u32 s28, s28, 0x100
	s_addc_u32 s29, s29, 0
	s_add_u32 s60, s60, 0x100
	s_addc_u32 s61, s61, 0
	s_cmp_ge_i32 s62, s45
	s_mov_b32 s30, s62
	s_cbranch_scc0 .LBB0_849

.LBB0_949:
	ds_read_b128 v[164:167], v157
	ds_read_b128 v[168:171], v157 offset:1024
	ds_read_b128 v[172:175], v157 offset:2048
	ds_read_b128 v[176:179], v157 offset:3072
	ds_read_b128 v[180:183], v162
	ds_read_b128 v[184:187], v162 offset:1024
	ds_read_b128 v[188:191], v162 offset:2048
	ds_read_b128 v[192:195], v162 offset:3072
	s_add_i32 s68, s34, 2
	s_add_u32 s69, s30, 0x80
	s_addc_u32 s35, s31, 0
	s_cmp_eq_u32 s49, s34
	s_cselect_b32 s34, s2, s69
	s_cselect_b32 s35, s3, s35
	s_cselect_b32 s71, s29, s67
	s_cselect_b32 s70, s28, s66
	v_lshl_add_u64 v[230:231], s[30:31], 0, v[136:137]
	s_add_i32 m0, s41, 0xc000
	ds_read_b128 v[196:199], v163
	ds_read_b128 v[200:203], v163 offset:1024
	ds_read_b128 v[204:207], v163 offset:2048
	ds_read_b128 v[208:211], v163 offset:3072
	ds_read_b128 v[212:215], v163 offset:4096
	ds_read_b128 v[216:219], v163 offset:5120
	ds_read_b128 v[222:225], v163 offset:6144
	ds_read_b128 v[226:229], v163 offset:7168
	global_load_lds_dwordx4 v[230:231], off
	v_lshl_add_u64 v[230:231], s[30:31], 0, v[138:139]
	s_add_i32 m0, s41, 0xe000
	s_nop 0
	global_load_lds_dwordx4 v[230:231], off
	s_waitcnt vmcnt(8)
	s_waitcnt lgkmcnt(0)
	s_barrier
	s_setprio 1
	s_waitcnt lgkmcnt(0)
	v_mfma_f32_16x16x32_bf16 v[120:123], v[164:167], v[196:199], v[120:123]
	v_mfma_f32_16x16x32_bf16 v[120:123], v[168:171], v[200:203], v[120:123]
	v_mfma_f32_16x16x32_bf16 v[124:127], v[176:179], v[200:203], v[124:127]
	v_mfma_f32_16x16x32_bf16 v[124:127], v[172:175], v[196:199], v[124:127]
	v_mfma_f32_16x16x32_bf16 v[108:111], v[164:167], v[204:207], v[108:111]
	v_mfma_f32_16x16x32_bf16 v[108:111], v[168:171], v[208:211], v[108:111]
	v_mfma_f32_16x16x32_bf16 v[104:107], v[176:179], v[208:211], v[104:107]
	v_mfma_f32_16x16x32_bf16 v[104:107], v[172:175], v[204:207], v[104:107]
	v_mfma_f32_16x16x32_bf16 v[92:95], v[164:167], v[212:215], v[92:95]
	v_mfma_f32_16x16x32_bf16 v[92:95], v[168:171], v[216:219], v[92:95]
	v_mfma_f32_16x16x32_bf16 v[88:91], v[176:179], v[216:219], v[88:91]
	v_mfma_f32_16x16x32_bf16 v[88:91], v[172:175], v[212:215], v[88:91]
	v_mfma_f32_16x16x32_bf16 v[76:79], v[164:167], v[222:225], v[76:79]
	v_mfma_f32_16x16x32_bf16 v[76:79], v[168:171], v[226:229], v[76:79]
	v_mfma_f32_16x16x32_bf16 v[72:75], v[176:179], v[226:229], v[72:75]
	v_mfma_f32_16x16x32_bf16 v[72:75], v[172:175], v[222:225], v[72:75]
	s_setprio 0
	s_setprio 1
	v_mfma_f32_16x16x32_bf16 v[116:119], v[180:183], v[196:199], v[116:119]
	v_mfma_f32_16x16x32_bf16 v[116:119], v[184:187], v[200:203], v[116:119]
	v_mfma_f32_16x16x32_bf16 v[112:115], v[192:195], v[200:203], v[112:115]
	v_mfma_f32_16x16x32_bf16 v[112:115], v[188:191], v[196:199], v[112:115]
	v_mfma_f32_16x16x32_bf16 v[100:103], v[180:183], v[204:207], v[100:103]
	v_mfma_f32_16x16x32_bf16 v[100:103], v[184:187], v[208:211], v[100:103]
	v_mfma_f32_16x16x32_bf16 v[96:99], v[192:195], v[208:211], v[96:99]
	v_mfma_f32_16x16x32_bf16 v[96:99], v[188:191], v[204:207], v[96:99]
	v_mfma_f32_16x16x32_bf16 v[84:87], v[180:183], v[212:215], v[84:87]
	v_mfma_f32_16x16x32_bf16 v[84:87], v[184:187], v[216:219], v[84:87]
	v_mfma_f32_16x16x32_bf16 v[80:83], v[192:195], v[216:219], v[80:83]
	v_mfma_f32_16x16x32_bf16 v[80:83], v[188:191], v[212:215], v[80:83]
	v_mfma_f32_16x16x32_bf16 v[68:71], v[180:183], v[222:225], v[68:71]
	v_mfma_f32_16x16x32_bf16 v[68:71], v[184:187], v[226:229], v[68:71]
	v_mfma_f32_16x16x32_bf16 v[64:67], v[192:195], v[226:229], v[64:67]
	v_mfma_f32_16x16x32_bf16 v[64:67], v[188:191], v[222:225], v[64:67]
	s_setprio 0
	s_barrier
	s_add_i32 s69, s52, s40
	v_lshl_add_u64 v[230:231], s[70:71], 0, v[130:131]
	s_mov_b32 m0, s69
	ds_read_b128 v[196:199], v163 offset:16384
	ds_read_b128 v[200:203], v163 offset:17408
	ds_read_b128 v[204:207], v163 offset:18432
	ds_read_b128 v[208:211], v163 offset:19456
	ds_read_b128 v[212:215], v163 offset:20480
	ds_read_b128 v[216:219], v163 offset:21504
	ds_read_b128 v[222:225], v163 offset:22528
	ds_read_b128 v[226:229], v163 offset:23552
	global_load_lds_dwordx4 v[230:231], off
	s_add_i32 m0, s69, 0x2000
	v_lshl_add_u64 v[232:233], s[70:71], 0, v[134:135]
	s_add_u32 s70, s70, s6
	s_addc_u32 s71, s71, s7
	s_add_i32 s69, s53, s40
	global_load_lds_dwordx4 v[232:233], off
	v_lshl_add_u64 v[234:235], s[70:71], 0, v[130:131]
	s_mov_b32 m0, s69
	v_lshl_add_u64 v[236:237], s[70:71], 0, v[134:135]
	global_load_lds_dwordx4 v[234:235], off
	s_add_i32 m0, s69, 0x2000
	v_lshl_add_u64 v[238:239], s[34:35], 0, v[128:129]
	global_load_lds_dwordx4 v[236:237], off
	s_mov_b32 m0, s41
	v_lshl_add_u64 v[240:241], s[34:35], 0, v[132:133]
	global_load_lds_dwordx4 v[238:239], off
	s_mov_b32 m0, s42
	s_nop 0
	global_load_lds_dwordx4 v[240:241], off
	s_waitcnt vmcnt(8)
	s_waitcnt lgkmcnt(0)
	s_barrier
	s_setprio 1
	s_waitcnt lgkmcnt(0)
	v_mfma_f32_16x16x32_bf16 v[60:63], v[164:167], v[196:199], v[60:63]
	v_mfma_f32_16x16x32_bf16 v[60:63], v[168:171], v[200:203], v[60:63]
	v_mfma_f32_16x16x32_bf16 v[56:59], v[176:179], v[200:203], v[56:59]
	v_mfma_f32_16x16x32_bf16 v[56:59], v[172:175], v[196:199], v[56:59]
	v_mfma_f32_16x16x32_bf16 v[44:47], v[164:167], v[204:207], v[44:47]
	v_mfma_f32_16x16x32_bf16 v[44:47], v[168:171], v[208:211], v[44:47]
	v_mfma_f32_16x16x32_bf16 v[40:43], v[176:179], v[208:211], v[40:43]
	v_mfma_f32_16x16x32_bf16 v[40:43], v[172:175], v[204:207], v[40:43]
	v_mfma_f32_16x16x32_bf16 v[28:31], v[164:167], v[212:215], v[28:31]
	v_mfma_f32_16x16x32_bf16 v[28:31], v[168:171], v[216:219], v[28:31]
	v_mfma_f32_16x16x32_bf16 v[24:27], v[176:179], v[216:219], v[24:27]
	v_mfma_f32_16x16x32_bf16 v[24:27], v[172:175], v[212:215], v[24:27]
	v_mfma_f32_16x16x32_bf16 v[12:15], v[164:167], v[222:225], v[12:15]
	v_mfma_f32_16x16x32_bf16 v[12:15], v[168:171], v[226:229], v[12:15]
	v_mfma_f32_16x16x32_bf16 v[8:11], v[176:179], v[226:229], v[8:11]
	v_mfma_f32_16x16x32_bf16 v[8:11], v[172:175], v[222:225], v[8:11]
	s_setprio 0
	s_setprio 1
	v_mfma_f32_16x16x32_bf16 v[52:55], v[180:183], v[196:199], v[52:55]
	v_mfma_f32_16x16x32_bf16 v[52:55], v[184:187], v[200:203], v[52:55]
	v_mfma_f32_16x16x32_bf16 v[48:51], v[192:195], v[200:203], v[48:51]
	v_mfma_f32_16x16x32_bf16 v[48:51], v[188:191], v[196:199], v[48:51]
	v_mfma_f32_16x16x32_bf16 v[36:39], v[180:183], v[204:207], v[36:39]
	v_mfma_f32_16x16x32_bf16 v[36:39], v[184:187], v[208:211], v[36:39]
	v_mfma_f32_16x16x32_bf16 v[32:35], v[192:195], v[208:211], v[32:35]
	v_mfma_f32_16x16x32_bf16 v[32:35], v[188:191], v[204:207], v[32:35]
	v_mfma_f32_16x16x32_bf16 v[20:23], v[180:183], v[212:215], v[20:23]
	v_mfma_f32_16x16x32_bf16 v[20:23], v[184:187], v[216:219], v[20:23]
	v_mfma_f32_16x16x32_bf16 v[16:19], v[192:195], v[216:219], v[16:19]
	v_mfma_f32_16x16x32_bf16 v[16:19], v[188:191], v[212:215], v[16:19]
	v_mfma_f32_16x16x32_bf16 v[4:7], v[180:183], v[222:225], v[4:7]
	v_mfma_f32_16x16x32_bf16 v[4:7], v[184:187], v[226:229], v[4:7]
	v_mfma_f32_16x16x32_bf16 v[0:3], v[192:195], v[226:229], v[0:3]
	v_mfma_f32_16x16x32_bf16 v[0:3], v[188:191], v[222:225], v[0:3]
	s_setprio 0
	s_barrier
	s_add_i32 s69, 0, 0x18000
	s_add_i32 s70, 0, 0x1c000
	v_add_u32_e32 v176, s69, v154
	v_add_u32_e32 v192, s70, v154
	ds_read_b128 v[164:167], v176
	ds_read_b128 v[168:171], v176 offset:1024
	ds_read_b128 v[172:175], v176 offset:2048
	ds_read_b128 v[176:179], v176 offset:3072
	ds_read_b128 v[180:183], v192
	ds_read_b128 v[184:187], v192 offset:1024
	ds_read_b128 v[188:191], v192 offset:2048
	ds_read_b128 v[192:195], v192 offset:3072
	s_add_u32 s34, s34, s6
	s_addc_u32 s35, s35, s7
	s_mov_b32 m0, s43
	v_lshl_add_u64 v[242:243], s[34:35], 0, v[128:129]
	ds_read_b128 v[196:199], v163 offset:32768
	ds_read_b128 v[200:203], v163 offset:33792
	ds_read_b128 v[204:207], v163 offset:34816
	ds_read_b128 v[208:211], v163 offset:35840
	ds_read_b128 v[212:215], v163 offset:36864
	ds_read_b128 v[216:219], v163 offset:37888
	ds_read_b128 v[222:225], v163 offset:38912
	ds_read_b128 v[226:229], v163 offset:39936
	global_load_lds_dwordx4 v[242:243], off
	v_lshl_add_u64 v[242:243], s[34:35], 0, v[132:133]
	s_mov_b32 m0, s44
	s_nop 0
	global_load_lds_dwordx4 v[242:243], off
	s_waitcnt vmcnt(8)
	s_waitcnt lgkmcnt(0)
	s_barrier
	s_setprio 1
	s_waitcnt lgkmcnt(0)
	v_mfma_f32_16x16x32_bf16 v[120:123], v[164:167], v[196:199], v[120:123]
	v_mfma_f32_16x16x32_bf16 v[120:123], v[168:171], v[200:203], v[120:123]
	v_mfma_f32_16x16x32_bf16 v[124:127], v[176:179], v[200:203], v[124:127]
	v_mfma_f32_16x16x32_bf16 v[124:127], v[172:175], v[196:199], v[124:127]
	v_mfma_f32_16x16x32_bf16 v[108:111], v[164:167], v[204:207], v[108:111]
	v_mfma_f32_16x16x32_bf16 v[108:111], v[168:171], v[208:211], v[108:111]
	v_mfma_f32_16x16x32_bf16 v[104:107], v[176:179], v[208:211], v[104:107]
	v_mfma_f32_16x16x32_bf16 v[104:107], v[172:175], v[204:207], v[104:107]
	v_mfma_f32_16x16x32_bf16 v[92:95], v[164:167], v[212:215], v[92:95]
	v_mfma_f32_16x16x32_bf16 v[92:95], v[168:171], v[216:219], v[92:95]
	v_mfma_f32_16x16x32_bf16 v[88:91], v[176:179], v[216:219], v[88:91]
	v_mfma_f32_16x16x32_bf16 v[88:91], v[172:175], v[212:215], v[88:91]
	v_mfma_f32_16x16x32_bf16 v[76:79], v[164:167], v[222:225], v[76:79]
	v_mfma_f32_16x16x32_bf16 v[76:79], v[168:171], v[226:229], v[76:79]
	v_mfma_f32_16x16x32_bf16 v[72:75], v[176:179], v[226:229], v[72:75]
	v_mfma_f32_16x16x32_bf16 v[72:75], v[172:175], v[222:225], v[72:75]
	s_setprio 0
	s_setprio 1
	v_mfma_f32_16x16x32_bf16 v[116:119], v[180:183], v[196:199], v[116:119]
	v_mfma_f32_16x16x32_bf16 v[116:119], v[184:187], v[200:203], v[116:119]
	v_mfma_f32_16x16x32_bf16 v[112:115], v[192:195], v[200:203], v[112:115]
	v_mfma_f32_16x16x32_bf16 v[112:115], v[188:191], v[196:199], v[112:115]
	v_mfma_f32_16x16x32_bf16 v[100:103], v[180:183], v[204:207], v[100:103]
	v_mfma_f32_16x16x32_bf16 v[100:103], v[184:187], v[208:211], v[100:103]
	v_mfma_f32_16x16x32_bf16 v[96:99], v[192:195], v[208:211], v[96:99]
	v_mfma_f32_16x16x32_bf16 v[96:99], v[188:191], v[204:207], v[96:99]
	v_mfma_f32_16x16x32_bf16 v[84:87], v[180:183], v[212:215], v[84:87]
	v_mfma_f32_16x16x32_bf16 v[84:87], v[184:187], v[216:219], v[84:87]
	v_mfma_f32_16x16x32_bf16 v[80:83], v[192:195], v[216:219], v[80:83]
	v_mfma_f32_16x16x32_bf16 v[80:83], v[188:191], v[212:215], v[80:83]
	v_mfma_f32_16x16x32_bf16 v[68:71], v[180:183], v[222:225], v[68:71]
	v_mfma_f32_16x16x32_bf16 v[68:71], v[184:187], v[226:229], v[68:71]
	v_mfma_f32_16x16x32_bf16 v[64:67], v[192:195], v[226:229], v[64:67]
	v_mfma_f32_16x16x32_bf16 v[64:67], v[188:191], v[222:225], v[64:67]
	s_setprio 0
	s_barrier
	s_add_i32 s34, s69, s40
	v_lshl_add_u64 v[230:231], v[230:231], 0, s[12:13]
	s_mov_b32 m0, s34
	ds_read_b128 v[196:199], v163 offset:49152
	ds_read_b128 v[200:203], v163 offset:50176
	ds_read_b128 v[204:207], v163 offset:51200
	ds_read_b128 v[208:211], v163 offset:52224
	ds_read_b128 v[212:215], v163 offset:53248
	ds_read_b128 v[216:219], v163 offset:54272
	ds_read_b128 v[222:225], v163 offset:55296
	ds_read_b128 v[226:229], v163 offset:56320
	global_load_lds_dwordx4 v[230:231], off
	v_lshl_add_u64 v[230:231], v[232:233], 0, s[12:13]
	s_add_i32 m0, s34, 0x2000
	s_add_i32 s34, s70, s40
	global_load_lds_dwordx4 v[230:231], off
	v_lshl_add_u64 v[230:231], v[234:235], 0, s[12:13]
	s_mov_b32 m0, s34
	s_nop 0
	global_load_lds_dwordx4 v[230:231], off
	v_lshl_add_u64 v[230:231], v[236:237], 0, s[12:13]
	s_add_i32 m0, s34, 0x2000
	s_nop 0
	global_load_lds_dwordx4 v[230:231], off
	v_lshl_add_u64 v[230:231], v[238:239], 0, s[12:13]
	s_mov_b32 m0, s46
	s_nop 0
	global_load_lds_dwordx4 v[230:231], off
	v_lshl_add_u64 v[230:231], v[240:241], 0, s[12:13]
	s_mov_b32 m0, s47
	s_nop 0
	global_load_lds_dwordx4 v[230:231], off
	s_waitcnt vmcnt(8)
	s_waitcnt lgkmcnt(0)
	s_barrier
	s_setprio 1
	s_waitcnt lgkmcnt(0)
	v_mfma_f32_16x16x32_bf16 v[60:63], v[164:167], v[196:199], v[60:63]
	v_mfma_f32_16x16x32_bf16 v[60:63], v[168:171], v[200:203], v[60:63]
	v_mfma_f32_16x16x32_bf16 v[56:59], v[176:179], v[200:203], v[56:59]
	v_mfma_f32_16x16x32_bf16 v[56:59], v[172:175], v[196:199], v[56:59]
	v_mfma_f32_16x16x32_bf16 v[44:47], v[164:167], v[204:207], v[44:47]
	v_mfma_f32_16x16x32_bf16 v[44:47], v[168:171], v[208:211], v[44:47]
	v_mfma_f32_16x16x32_bf16 v[40:43], v[176:179], v[208:211], v[40:43]
	v_mfma_f32_16x16x32_bf16 v[40:43], v[172:175], v[204:207], v[40:43]
	v_mfma_f32_16x16x32_bf16 v[28:31], v[164:167], v[212:215], v[28:31]
	v_mfma_f32_16x16x32_bf16 v[28:31], v[168:171], v[216:219], v[28:31]
	v_mfma_f32_16x16x32_bf16 v[24:27], v[176:179], v[216:219], v[24:27]
	v_mfma_f32_16x16x32_bf16 v[24:27], v[172:175], v[212:215], v[24:27]
	v_mfma_f32_16x16x32_bf16 v[12:15], v[164:167], v[222:225], v[12:15]
	v_mfma_f32_16x16x32_bf16 v[12:15], v[168:171], v[226:229], v[12:15]
	v_mfma_f32_16x16x32_bf16 v[8:11], v[176:179], v[226:229], v[8:11]
	v_mfma_f32_16x16x32_bf16 v[8:11], v[172:175], v[222:225], v[8:11]
	s_setprio 0
	s_setprio 1
	v_mfma_f32_16x16x32_bf16 v[52:55], v[180:183], v[196:199], v[52:55]
	v_mfma_f32_16x16x32_bf16 v[52:55], v[184:187], v[200:203], v[52:55]
	v_mfma_f32_16x16x32_bf16 v[48:51], v[192:195], v[200:203], v[48:51]
	v_mfma_f32_16x16x32_bf16 v[48:51], v[188:191], v[196:199], v[48:51]
	v_mfma_f32_16x16x32_bf16 v[36:39], v[180:183], v[204:207], v[36:39]
	v_mfma_f32_16x16x32_bf16 v[36:39], v[184:187], v[208:211], v[36:39]
	v_mfma_f32_16x16x32_bf16 v[32:35], v[192:195], v[208:211], v[32:35]
	v_mfma_f32_16x16x32_bf16 v[32:35], v[188:191], v[204:207], v[32:35]
	v_mfma_f32_16x16x32_bf16 v[20:23], v[180:183], v[212:215], v[20:23]
	v_mfma_f32_16x16x32_bf16 v[20:23], v[184:187], v[216:219], v[20:23]
	v_mfma_f32_16x16x32_bf16 v[16:19], v[192:195], v[216:219], v[16:19]
	v_mfma_f32_16x16x32_bf16 v[16:19], v[188:191], v[212:215], v[16:19]
	v_mfma_f32_16x16x32_bf16 v[4:7], v[180:183], v[222:225], v[4:7]
	v_mfma_f32_16x16x32_bf16 v[4:7], v[184:187], v[226:229], v[4:7]
	v_mfma_f32_16x16x32_bf16 v[0:3], v[192:195], v[226:229], v[0:3]
	v_mfma_f32_16x16x32_bf16 v[0:3], v[188:191], v[222:225], v[0:3]
	s_setprio 0
	s_barrier
	s_add_u32 s30, s30, 0x100
	s_addc_u32 s31, s31, 0
	s_add_u32 s66, s66, 0x100
	s_addc_u32 s67, s67, 0
	s_cmp_ge_i32 s68, s48
	s_mov_b32 s34, s68
	s_cbranch_scc0 .LBB0_949

.LBB0_970:
	ds_read_b128 v[170:173], v139
	ds_read_b128 v[174:177], v139 offset:1024
	ds_read_b128 v[178:181], v139 offset:2048
	ds_read_b128 v[182:185], v139 offset:3072
	ds_read_b128 v[186:189], v165
	ds_read_b128 v[190:193], v165 offset:1024
	ds_read_b128 v[194:197], v165 offset:2048
	ds_read_b128 v[198:201], v165 offset:3072
	s_add_i32 s8, s4, 2
	s_add_u32 s9, s2, 0x80
	s_addc_u32 s5, s3, 0
	s_cmp_eq_u32 s52, s4
	s_cselect_b32 s4, s30, s9
	s_cselect_b32 s5, s31, s5
	s_cselect_b32 s11, s35, s7
	s_cselect_b32 s10, s34, s6
	v_lshl_add_u64 v[218:219], s[2:3], 0, v[156:157]
	s_add_i32 m0, s42, 0xc000
	ds_read_b128 v[202:205], v166
	ds_read_b128 v[206:209], v166 offset:1024
	ds_read_b128 v[210:213], v166 offset:2048
	ds_read_b128 v[214:217], v166 offset:3072
	ds_read_b128 v[222:225], v166 offset:4096
	ds_read_b128 v[226:229], v166 offset:5120
	ds_read_b128 v[230:233], v166 offset:6144
	ds_read_b128 v[234:237], v166 offset:7168
	global_load_lds_dwordx4 v[218:219], off
	v_lshl_add_u64 v[218:219], s[2:3], 0, v[158:159]
	s_add_i32 m0, s42, 0xe000
	s_nop 0
	global_load_lds_dwordx4 v[218:219], off
	s_waitcnt vmcnt(8)
	s_waitcnt lgkmcnt(0)
	s_barrier
	s_setprio 1
	s_waitcnt lgkmcnt(0)
	v_mfma_f32_16x16x32_bf16 v[124:127], v[170:173], v[202:205], v[124:127]
	v_mfma_f32_16x16x32_bf16 v[124:127], v[174:177], v[206:209], v[124:127]
	v_mfma_f32_16x16x32_bf16 v[120:123], v[182:185], v[206:209], v[120:123]
	v_mfma_f32_16x16x32_bf16 v[120:123], v[178:181], v[202:205], v[120:123]
	v_mfma_f32_16x16x32_bf16 v[108:111], v[170:173], v[210:213], v[108:111]
	v_mfma_f32_16x16x32_bf16 v[108:111], v[174:177], v[214:217], v[108:111]
	v_mfma_f32_16x16x32_bf16 v[104:107], v[182:185], v[214:217], v[104:107]
	v_mfma_f32_16x16x32_bf16 v[104:107], v[178:181], v[210:213], v[104:107]
	v_mfma_f32_16x16x32_bf16 v[92:95], v[170:173], v[222:225], v[92:95]
	v_mfma_f32_16x16x32_bf16 v[92:95], v[174:177], v[226:229], v[92:95]
	v_mfma_f32_16x16x32_bf16 v[88:91], v[182:185], v[226:229], v[88:91]
	v_mfma_f32_16x16x32_bf16 v[88:91], v[178:181], v[222:225], v[88:91]
	v_mfma_f32_16x16x32_bf16 v[76:79], v[170:173], v[230:233], v[76:79]
	v_mfma_f32_16x16x32_bf16 v[76:79], v[174:177], v[234:237], v[76:79]
	v_mfma_f32_16x16x32_bf16 v[72:75], v[182:185], v[234:237], v[72:75]
	v_mfma_f32_16x16x32_bf16 v[72:75], v[178:181], v[230:233], v[72:75]
	s_setprio 0
	s_setprio 1
	v_mfma_f32_16x16x32_bf16 v[116:119], v[186:189], v[202:205], v[116:119]
	v_mfma_f32_16x16x32_bf16 v[116:119], v[190:193], v[206:209], v[116:119]
	v_mfma_f32_16x16x32_bf16 v[112:115], v[198:201], v[206:209], v[112:115]
	v_mfma_f32_16x16x32_bf16 v[112:115], v[194:197], v[202:205], v[112:115]
	v_mfma_f32_16x16x32_bf16 v[100:103], v[186:189], v[210:213], v[100:103]
	v_mfma_f32_16x16x32_bf16 v[100:103], v[190:193], v[214:217], v[100:103]
	v_mfma_f32_16x16x32_bf16 v[96:99], v[198:201], v[214:217], v[96:99]
	v_mfma_f32_16x16x32_bf16 v[96:99], v[194:197], v[210:213], v[96:99]
	v_mfma_f32_16x16x32_bf16 v[84:87], v[186:189], v[222:225], v[84:87]
	v_mfma_f32_16x16x32_bf16 v[84:87], v[190:193], v[226:229], v[84:87]
	v_mfma_f32_16x16x32_bf16 v[80:83], v[198:201], v[226:229], v[80:83]
	v_mfma_f32_16x16x32_bf16 v[80:83], v[194:197], v[222:225], v[80:83]
	v_mfma_f32_16x16x32_bf16 v[68:71], v[186:189], v[230:233], v[68:71]
	v_mfma_f32_16x16x32_bf16 v[68:71], v[190:193], v[234:237], v[68:71]
	v_mfma_f32_16x16x32_bf16 v[64:67], v[198:201], v[234:237], v[64:67]
	v_mfma_f32_16x16x32_bf16 v[64:67], v[194:197], v[230:233], v[64:67]
	s_setprio 0
	s_barrier
	s_add_i32 s9, s60, s39
	v_lshl_add_u64 v[218:219], s[10:11], 0, v[132:133]
	s_mov_b32 m0, s9
	ds_read_b128 v[202:205], v166 offset:16384
	ds_read_b128 v[206:209], v166 offset:17408
	ds_read_b128 v[210:213], v166 offset:18432
	ds_read_b128 v[214:217], v166 offset:19456
	ds_read_b128 v[222:225], v166 offset:20480
	ds_read_b128 v[226:229], v166 offset:21504
	ds_read_b128 v[230:233], v166 offset:22528
	ds_read_b128 v[234:237], v166 offset:23552
	global_load_lds_dwordx4 v[218:219], off
	s_add_i32 m0, s9, 0x2000
	v_lshl_add_u64 v[238:239], s[10:11], 0, v[128:129]
	s_add_u32 s10, s10, s18
	s_addc_u32 s11, s11, s19
	s_add_i32 s9, s61, s39
	global_load_lds_dwordx4 v[238:239], off
	v_lshl_add_u64 v[240:241], s[10:11], 0, v[132:133]
	s_mov_b32 m0, s9
	v_lshl_add_u64 v[242:243], s[10:11], 0, v[128:129]
	global_load_lds_dwordx4 v[240:241], off
	s_add_i32 m0, s9, 0x2000
	v_lshl_add_u64 v[244:245], s[4:5], 0, v[134:135]
	global_load_lds_dwordx4 v[242:243], off
	s_mov_b32 m0, s42
	v_lshl_add_u64 v[246:247], s[4:5], 0, v[130:131]
	global_load_lds_dwordx4 v[244:245], off
	s_mov_b32 m0, s43
	s_nop 0
	global_load_lds_dwordx4 v[246:247], off
	s_waitcnt vmcnt(8)
	s_waitcnt lgkmcnt(0)
	s_barrier
	s_setprio 1
	s_waitcnt lgkmcnt(0)
	v_mfma_f32_16x16x32_bf16 v[60:63], v[170:173], v[202:205], v[60:63]
	v_mfma_f32_16x16x32_bf16 v[60:63], v[174:177], v[206:209], v[60:63]
	v_mfma_f32_16x16x32_bf16 v[56:59], v[182:185], v[206:209], v[56:59]
	v_mfma_f32_16x16x32_bf16 v[56:59], v[178:181], v[202:205], v[56:59]
	v_mfma_f32_16x16x32_bf16 v[44:47], v[170:173], v[210:213], v[44:47]
	v_mfma_f32_16x16x32_bf16 v[44:47], v[174:177], v[214:217], v[44:47]
	v_mfma_f32_16x16x32_bf16 v[40:43], v[182:185], v[214:217], v[40:43]
	v_mfma_f32_16x16x32_bf16 v[40:43], v[178:181], v[210:213], v[40:43]
	v_mfma_f32_16x16x32_bf16 v[28:31], v[170:173], v[222:225], v[28:31]
	v_mfma_f32_16x16x32_bf16 v[28:31], v[174:177], v[226:229], v[28:31]
	v_mfma_f32_16x16x32_bf16 v[24:27], v[182:185], v[226:229], v[24:27]
	v_mfma_f32_16x16x32_bf16 v[24:27], v[178:181], v[222:225], v[24:27]
	v_mfma_f32_16x16x32_bf16 v[12:15], v[170:173], v[230:233], v[12:15]
	v_mfma_f32_16x16x32_bf16 v[12:15], v[174:177], v[234:237], v[12:15]
	v_mfma_f32_16x16x32_bf16 v[8:11], v[182:185], v[234:237], v[8:11]
	v_mfma_f32_16x16x32_bf16 v[8:11], v[178:181], v[230:233], v[8:11]
	s_setprio 0
	s_setprio 1
	v_mfma_f32_16x16x32_bf16 v[52:55], v[186:189], v[202:205], v[52:55]
	v_mfma_f32_16x16x32_bf16 v[52:55], v[190:193], v[206:209], v[52:55]
	v_mfma_f32_16x16x32_bf16 v[48:51], v[198:201], v[206:209], v[48:51]
	v_mfma_f32_16x16x32_bf16 v[48:51], v[194:197], v[202:205], v[48:51]
	v_mfma_f32_16x16x32_bf16 v[36:39], v[186:189], v[210:213], v[36:39]
	v_mfma_f32_16x16x32_bf16 v[36:39], v[190:193], v[214:217], v[36:39]
	v_mfma_f32_16x16x32_bf16 v[32:35], v[198:201], v[214:217], v[32:35]
	v_mfma_f32_16x16x32_bf16 v[32:35], v[194:197], v[210:213], v[32:35]
	v_mfma_f32_16x16x32_bf16 v[20:23], v[186:189], v[222:225], v[20:23]
	v_mfma_f32_16x16x32_bf16 v[20:23], v[190:193], v[226:229], v[20:23]
	v_mfma_f32_16x16x32_bf16 v[16:19], v[198:201], v[226:229], v[16:19]
	v_mfma_f32_16x16x32_bf16 v[16:19], v[194:197], v[222:225], v[16:19]
	v_mfma_f32_16x16x32_bf16 v[4:7], v[186:189], v[230:233], v[4:7]
	v_mfma_f32_16x16x32_bf16 v[4:7], v[190:193], v[234:237], v[4:7]
	v_mfma_f32_16x16x32_bf16 v[0:3], v[198:201], v[234:237], v[0:3]
	v_mfma_f32_16x16x32_bf16 v[0:3], v[194:197], v[230:233], v[0:3]
	s_setprio 0
	s_barrier
	s_add_i32 s9, 0, 0x18000
	v_add_u32_e32 v169, s9, v164
	s_add_i32 s10, 0, 0x1c000
	ds_read_b128 v[170:173], v169
	ds_read_b128 v[174:177], v169 offset:1024
	ds_read_b128 v[178:181], v169 offset:2048
	ds_read_b128 v[182:185], v169 offset:3072
	v_add_u32_e32 v169, s10, v164
	ds_read_b128 v[186:189], v169
	ds_read_b128 v[190:193], v169 offset:1024
	ds_read_b128 v[194:197], v169 offset:2048
	ds_read_b128 v[198:201], v169 offset:3072
	s_add_u32 s4, s4, s18
	s_addc_u32 s5, s5, s19
	s_mov_b32 m0, s44
	v_lshl_add_u64 v[248:249], s[4:5], 0, v[134:135]
	ds_read_b128 v[202:205], v166 offset:32768
	ds_read_b128 v[206:209], v166 offset:33792
	ds_read_b128 v[210:213], v166 offset:34816
	ds_read_b128 v[214:217], v166 offset:35840
	ds_read_b128 v[222:225], v166 offset:36864
	ds_read_b128 v[226:229], v166 offset:37888
	ds_read_b128 v[230:233], v166 offset:38912
	ds_read_b128 v[234:237], v166 offset:39936
	global_load_lds_dwordx4 v[248:249], off
	v_lshl_add_u64 v[248:249], s[4:5], 0, v[130:131]
	s_mov_b32 m0, s45
	s_nop 0
	global_load_lds_dwordx4 v[248:249], off
	s_waitcnt vmcnt(8)
	s_waitcnt lgkmcnt(0)
	s_barrier
	s_setprio 1
	s_waitcnt lgkmcnt(0)
	v_mfma_f32_16x16x32_bf16 v[124:127], v[170:173], v[202:205], v[124:127]
	v_mfma_f32_16x16x32_bf16 v[124:127], v[174:177], v[206:209], v[124:127]
	v_mfma_f32_16x16x32_bf16 v[120:123], v[182:185], v[206:209], v[120:123]
	v_mfma_f32_16x16x32_bf16 v[120:123], v[178:181], v[202:205], v[120:123]
	v_mfma_f32_16x16x32_bf16 v[108:111], v[170:173], v[210:213], v[108:111]
	v_mfma_f32_16x16x32_bf16 v[108:111], v[174:177], v[214:217], v[108:111]
	v_mfma_f32_16x16x32_bf16 v[104:107], v[182:185], v[214:217], v[104:107]
	v_mfma_f32_16x16x32_bf16 v[104:107], v[178:181], v[210:213], v[104:107]
	v_mfma_f32_16x16x32_bf16 v[92:95], v[170:173], v[222:225], v[92:95]
	v_mfma_f32_16x16x32_bf16 v[92:95], v[174:177], v[226:229], v[92:95]
	v_mfma_f32_16x16x32_bf16 v[88:91], v[182:185], v[226:229], v[88:91]
	v_mfma_f32_16x16x32_bf16 v[88:91], v[178:181], v[222:225], v[88:91]
	v_mfma_f32_16x16x32_bf16 v[76:79], v[170:173], v[230:233], v[76:79]
	v_mfma_f32_16x16x32_bf16 v[76:79], v[174:177], v[234:237], v[76:79]
	v_mfma_f32_16x16x32_bf16 v[72:75], v[182:185], v[234:237], v[72:75]
	v_mfma_f32_16x16x32_bf16 v[72:75], v[178:181], v[230:233], v[72:75]
	s_setprio 0
	s_setprio 1
	v_mfma_f32_16x16x32_bf16 v[116:119], v[186:189], v[202:205], v[116:119]
	v_mfma_f32_16x16x32_bf16 v[116:119], v[190:193], v[206:209], v[116:119]
	v_mfma_f32_16x16x32_bf16 v[112:115], v[198:201], v[206:209], v[112:115]
	v_mfma_f32_16x16x32_bf16 v[112:115], v[194:197], v[202:205], v[112:115]
	v_mfma_f32_16x16x32_bf16 v[100:103], v[186:189], v[210:213], v[100:103]
	v_mfma_f32_16x16x32_bf16 v[100:103], v[190:193], v[214:217], v[100:103]
	v_mfma_f32_16x16x32_bf16 v[96:99], v[198:201], v[214:217], v[96:99]
	v_mfma_f32_16x16x32_bf16 v[96:99], v[194:197], v[210:213], v[96:99]
	v_mfma_f32_16x16x32_bf16 v[84:87], v[186:189], v[222:225], v[84:87]
	v_mfma_f32_16x16x32_bf16 v[84:87], v[190:193], v[226:229], v[84:87]
	v_mfma_f32_16x16x32_bf16 v[80:83], v[198:201], v[226:229], v[80:83]
	v_mfma_f32_16x16x32_bf16 v[80:83], v[194:197], v[222:225], v[80:83]
	v_mfma_f32_16x16x32_bf16 v[68:71], v[186:189], v[230:233], v[68:71]
	v_mfma_f32_16x16x32_bf16 v[68:71], v[190:193], v[234:237], v[68:71]
	v_mfma_f32_16x16x32_bf16 v[64:67], v[198:201], v[234:237], v[64:67]
	v_mfma_f32_16x16x32_bf16 v[64:67], v[194:197], v[230:233], v[64:67]
	s_setprio 0
	s_barrier
	s_add_i32 s4, s9, s39
	v_lshl_add_u64 v[218:219], v[218:219], 0, s[24:25]
	s_mov_b32 m0, s4
	ds_read_b128 v[202:205], v166 offset:49152
	ds_read_b128 v[206:209], v166 offset:50176
	ds_read_b128 v[210:213], v166 offset:51200
	ds_read_b128 v[214:217], v166 offset:52224
	ds_read_b128 v[222:225], v166 offset:53248
	ds_read_b128 v[226:229], v166 offset:54272
	ds_read_b128 v[230:233], v166 offset:55296
	ds_read_b128 v[234:237], v166 offset:56320
	global_load_lds_dwordx4 v[218:219], off
	v_lshl_add_u64 v[218:219], v[238:239], 0, s[24:25]
	s_add_i32 m0, s4, 0x2000
	s_add_i32 s4, s10, s39
	global_load_lds_dwordx4 v[218:219], off
	v_lshl_add_u64 v[218:219], v[240:241], 0, s[24:25]
	s_mov_b32 m0, s4
	s_nop 0
	global_load_lds_dwordx4 v[218:219], off
	v_lshl_add_u64 v[218:219], v[242:243], 0, s[24:25]
	s_add_i32 m0, s4, 0x2000
	s_nop 0
	global_load_lds_dwordx4 v[218:219], off
	v_lshl_add_u64 v[218:219], v[244:245], 0, s[24:25]
	s_mov_b32 m0, s49
	s_nop 0
	global_load_lds_dwordx4 v[218:219], off
	v_lshl_add_u64 v[218:219], v[246:247], 0, s[24:25]
	s_mov_b32 m0, s50
	s_nop 0
	global_load_lds_dwordx4 v[218:219], off
	s_waitcnt vmcnt(8)
	s_waitcnt lgkmcnt(0)
	s_barrier
	s_setprio 1
	s_waitcnt lgkmcnt(0)
	v_mfma_f32_16x16x32_bf16 v[60:63], v[170:173], v[202:205], v[60:63]
	v_mfma_f32_16x16x32_bf16 v[60:63], v[174:177], v[206:209], v[60:63]
	v_mfma_f32_16x16x32_bf16 v[56:59], v[182:185], v[206:209], v[56:59]
	v_mfma_f32_16x16x32_bf16 v[56:59], v[178:181], v[202:205], v[56:59]
	v_mfma_f32_16x16x32_bf16 v[44:47], v[170:173], v[210:213], v[44:47]
	v_mfma_f32_16x16x32_bf16 v[44:47], v[174:177], v[214:217], v[44:47]
	v_mfma_f32_16x16x32_bf16 v[40:43], v[182:185], v[214:217], v[40:43]
	v_mfma_f32_16x16x32_bf16 v[40:43], v[178:181], v[210:213], v[40:43]
	v_mfma_f32_16x16x32_bf16 v[28:31], v[170:173], v[222:225], v[28:31]
	v_mfma_f32_16x16x32_bf16 v[28:31], v[174:177], v[226:229], v[28:31]
	v_mfma_f32_16x16x32_bf16 v[24:27], v[182:185], v[226:229], v[24:27]
	v_mfma_f32_16x16x32_bf16 v[24:27], v[178:181], v[222:225], v[24:27]
	v_mfma_f32_16x16x32_bf16 v[12:15], v[170:173], v[230:233], v[12:15]
	v_mfma_f32_16x16x32_bf16 v[12:15], v[174:177], v[234:237], v[12:15]
	v_mfma_f32_16x16x32_bf16 v[8:11], v[182:185], v[234:237], v[8:11]
	v_mfma_f32_16x16x32_bf16 v[8:11], v[178:181], v[230:233], v[8:11]
	s_setprio 0
	s_setprio 1
	v_mfma_f32_16x16x32_bf16 v[52:55], v[186:189], v[202:205], v[52:55]
	v_mfma_f32_16x16x32_bf16 v[52:55], v[190:193], v[206:209], v[52:55]
	v_mfma_f32_16x16x32_bf16 v[48:51], v[198:201], v[206:209], v[48:51]
	v_mfma_f32_16x16x32_bf16 v[48:51], v[194:197], v[202:205], v[48:51]
	v_mfma_f32_16x16x32_bf16 v[36:39], v[186:189], v[210:213], v[36:39]
	v_mfma_f32_16x16x32_bf16 v[36:39], v[190:193], v[214:217], v[36:39]
	v_mfma_f32_16x16x32_bf16 v[32:35], v[198:201], v[214:217], v[32:35]
	v_mfma_f32_16x16x32_bf16 v[32:35], v[194:197], v[210:213], v[32:35]
	v_mfma_f32_16x16x32_bf16 v[20:23], v[186:189], v[222:225], v[20:23]
	v_mfma_f32_16x16x32_bf16 v[20:23], v[190:193], v[226:229], v[20:23]
	v_mfma_f32_16x16x32_bf16 v[16:19], v[198:201], v[226:229], v[16:19]
	v_mfma_f32_16x16x32_bf16 v[16:19], v[194:197], v[222:225], v[16:19]
	v_mfma_f32_16x16x32_bf16 v[4:7], v[186:189], v[230:233], v[4:7]
	v_mfma_f32_16x16x32_bf16 v[4:7], v[190:193], v[234:237], v[4:7]
	v_mfma_f32_16x16x32_bf16 v[0:3], v[198:201], v[234:237], v[0:3]
	v_mfma_f32_16x16x32_bf16 v[0:3], v[194:197], v[230:233], v[0:3]
	s_setprio 0
	s_barrier
	s_add_u32 s2, s2, 0x100
	s_addc_u32 s3, s3, 0
	s_add_u32 s6, s6, 0x100
	s_addc_u32 s7, s7, 0
	s_cmp_ge_i32 s8, s51
	s_mov_b32 s4, s8
	s_cbranch_scc0 .LBB0_970

.LBB0_1056:
	ds_read_b128 v[140:143], v222
	ds_read_b128 v[144:147], v222 offset:1024
	ds_read_b128 v[148:151], v222 offset:2048
	ds_read_b128 v[152:155], v222 offset:3072
	ds_read_b128 v[156:159], v223
	ds_read_b128 v[160:163], v223 offset:1024
	ds_read_b128 v[164:167], v223 offset:2048
	ds_read_b128 v[168:171], v223 offset:3072
	s_add_i32 s62, s26, 2
	s_add_u32 s27, s24, 0x4000
	s_addc_u32 s28, s25, 0
	s_cmp_eq_u32 s46, s26
	s_cselect_b32 s30, s0, s27
	s_cselect_b32 s31, s1, s28
	s_cselect_b32 s28, s22, s60
	s_cselect_b32 s29, s23, s61
	s_add_u32 s26, s30, 0x8000
	s_addc_u32 s27, s31, 0
	v_lshl_add_u64 v[204:205], s[24:25], 0, v[132:133]
	s_add_i32 m0, s38, 0xc000
	ds_read_b128 v[172:175], v224
	ds_read_b128 v[176:179], v224 offset:1024
	ds_read_b128 v[180:183], v224 offset:2048
	ds_read_b128 v[184:187], v224 offset:3072
	ds_read_b128 v[188:191], v224 offset:4096
	ds_read_b128 v[192:195], v224 offset:5120
	ds_read_b128 v[196:199], v224 offset:6144
	ds_read_b128 v[200:203], v224 offset:7168
	global_load_lds_dwordx4 v[204:205], off
	v_lshl_add_u64 v[204:205], s[24:25], 0, v[134:135]
	s_add_i32 m0, s38, 0xe000
	s_nop 0
	global_load_lds_dwordx4 v[204:205], off
	s_waitcnt vmcnt(8)
	s_waitcnt lgkmcnt(0)
	s_barrier
	s_setprio 1
	s_waitcnt lgkmcnt(0)
	v_mfma_f32_16x16x32_bf16 v[124:127], v[140:143], v[172:175], v[124:127]
	v_mfma_f32_16x16x32_bf16 v[124:127], v[144:147], v[176:179], v[124:127]
	v_mfma_f32_16x16x32_bf16 v[120:123], v[152:155], v[176:179], v[120:123]
	v_mfma_f32_16x16x32_bf16 v[120:123], v[148:151], v[172:175], v[120:123]
	v_mfma_f32_16x16x32_bf16 v[116:119], v[140:143], v[180:183], v[116:119]
	v_mfma_f32_16x16x32_bf16 v[116:119], v[144:147], v[184:187], v[116:119]
	v_mfma_f32_16x16x32_bf16 v[112:115], v[152:155], v[184:187], v[112:115]
	v_mfma_f32_16x16x32_bf16 v[112:115], v[148:151], v[180:183], v[112:115]
	v_mfma_f32_16x16x32_bf16 v[104:107], v[140:143], v[188:191], v[104:107]
	v_mfma_f32_16x16x32_bf16 v[104:107], v[144:147], v[192:195], v[104:107]
	v_mfma_f32_16x16x32_bf16 v[96:99], v[152:155], v[192:195], v[96:99]
	v_mfma_f32_16x16x32_bf16 v[96:99], v[148:151], v[188:191], v[96:99]
	v_mfma_f32_16x16x32_bf16 v[88:91], v[140:143], v[196:199], v[88:91]
	v_mfma_f32_16x16x32_bf16 v[88:91], v[144:147], v[200:203], v[88:91]
	v_mfma_f32_16x16x32_bf16 v[80:83], v[152:155], v[200:203], v[80:83]
	v_mfma_f32_16x16x32_bf16 v[80:83], v[148:151], v[196:199], v[80:83]
	s_setprio 0
	s_setprio 1
	v_mfma_f32_16x16x32_bf16 v[108:111], v[156:159], v[172:175], v[108:111]
	v_mfma_f32_16x16x32_bf16 v[108:111], v[160:163], v[176:179], v[108:111]
	v_mfma_f32_16x16x32_bf16 v[100:103], v[168:171], v[176:179], v[100:103]
	v_mfma_f32_16x16x32_bf16 v[100:103], v[164:167], v[172:175], v[100:103]
	v_mfma_f32_16x16x32_bf16 v[92:95], v[156:159], v[180:183], v[92:95]
	v_mfma_f32_16x16x32_bf16 v[92:95], v[160:163], v[184:187], v[92:95]
	v_mfma_f32_16x16x32_bf16 v[84:87], v[168:171], v[184:187], v[84:87]
	v_mfma_f32_16x16x32_bf16 v[84:87], v[164:167], v[180:183], v[84:87]
	v_mfma_f32_16x16x32_bf16 v[76:79], v[156:159], v[188:191], v[76:79]
	v_mfma_f32_16x16x32_bf16 v[76:79], v[160:163], v[192:195], v[76:79]
	v_mfma_f32_16x16x32_bf16 v[72:75], v[168:171], v[192:195], v[72:75]
	v_mfma_f32_16x16x32_bf16 v[72:75], v[164:167], v[188:191], v[72:75]
	v_mfma_f32_16x16x32_bf16 v[68:71], v[156:159], v[196:199], v[68:71]
	v_mfma_f32_16x16x32_bf16 v[68:71], v[160:163], v[200:203], v[68:71]
	v_mfma_f32_16x16x32_bf16 v[64:67], v[168:171], v[200:203], v[64:67]
	v_mfma_f32_16x16x32_bf16 v[64:67], v[164:167], v[196:199], v[64:67]
	s_setprio 0
	s_barrier
	s_add_i32 s63, s50, s37
	v_lshl_add_u64 v[204:205], s[28:29], 0, v[128:129]
	s_mov_b32 m0, s63
	ds_read_b128 v[172:175], v224 offset:16384
	ds_read_b128 v[176:179], v224 offset:17408
	ds_read_b128 v[180:183], v224 offset:18432
	ds_read_b128 v[184:187], v224 offset:19456
	ds_read_b128 v[188:191], v224 offset:20480
	ds_read_b128 v[192:195], v224 offset:21504
	ds_read_b128 v[196:199], v224 offset:22528
	ds_read_b128 v[200:203], v224 offset:23552
	global_load_lds_dwordx4 v[204:205], off
	s_add_i32 m0, s63, 0x2000
	s_add_u32 s64, s28, 0x4000
	v_lshl_add_u64 v[204:205], s[28:29], 0, v[130:131]
	s_addc_u32 s65, s29, 0
	s_add_i32 s63, s51, s37
	global_load_lds_dwordx4 v[204:205], off
	v_lshl_add_u64 v[204:205], s[64:65], 0, v[128:129]
	s_mov_b32 m0, s63
	s_nop 0
	global_load_lds_dwordx4 v[204:205], off
	v_lshl_add_u64 v[204:205], s[64:65], 0, v[130:131]
	s_add_i32 m0, s63, 0x2000
	s_nop 0
	global_load_lds_dwordx4 v[204:205], off
	v_lshl_add_u64 v[204:205], s[30:31], 0, v[128:129]
	s_mov_b32 m0, s38
	s_nop 0
	global_load_lds_dwordx4 v[204:205], off
	v_lshl_add_u64 v[204:205], s[30:31], 0, v[130:131]
	s_mov_b32 m0, s39
	s_nop 0
	global_load_lds_dwordx4 v[204:205], off
	s_waitcnt vmcnt(8)
	s_waitcnt lgkmcnt(0)
	s_barrier
	s_setprio 1
	s_waitcnt lgkmcnt(0)
	v_mfma_f32_16x16x32_bf16 v[60:63], v[140:143], v[172:175], v[60:63]
	v_mfma_f32_16x16x32_bf16 v[60:63], v[144:147], v[176:179], v[60:63]
	v_mfma_f32_16x16x32_bf16 v[56:59], v[152:155], v[176:179], v[56:59]
	v_mfma_f32_16x16x32_bf16 v[56:59], v[148:151], v[172:175], v[56:59]
	v_mfma_f32_16x16x32_bf16 v[52:55], v[140:143], v[180:183], v[52:55]
	v_mfma_f32_16x16x32_bf16 v[52:55], v[144:147], v[184:187], v[52:55]
	v_mfma_f32_16x16x32_bf16 v[48:51], v[152:155], v[184:187], v[48:51]
	v_mfma_f32_16x16x32_bf16 v[48:51], v[148:151], v[180:183], v[48:51]
	v_mfma_f32_16x16x32_bf16 v[40:43], v[140:143], v[188:191], v[40:43]
	v_mfma_f32_16x16x32_bf16 v[40:43], v[144:147], v[192:195], v[40:43]
	v_mfma_f32_16x16x32_bf16 v[32:35], v[152:155], v[192:195], v[32:35]
	v_mfma_f32_16x16x32_bf16 v[32:35], v[148:151], v[188:191], v[32:35]
	v_mfma_f32_16x16x32_bf16 v[24:27], v[140:143], v[196:199], v[24:27]
	v_mfma_f32_16x16x32_bf16 v[24:27], v[144:147], v[200:203], v[24:27]
	v_mfma_f32_16x16x32_bf16 v[16:19], v[152:155], v[200:203], v[16:19]
	v_mfma_f32_16x16x32_bf16 v[16:19], v[148:151], v[196:199], v[16:19]
	s_setprio 0
	s_setprio 1
	v_mfma_f32_16x16x32_bf16 v[44:47], v[156:159], v[172:175], v[44:47]
	v_mfma_f32_16x16x32_bf16 v[44:47], v[160:163], v[176:179], v[44:47]
	v_mfma_f32_16x16x32_bf16 v[36:39], v[168:171], v[176:179], v[36:39]
	v_mfma_f32_16x16x32_bf16 v[36:39], v[164:167], v[172:175], v[36:39]
	v_mfma_f32_16x16x32_bf16 v[28:31], v[156:159], v[180:183], v[28:31]
	v_mfma_f32_16x16x32_bf16 v[28:31], v[160:163], v[184:187], v[28:31]
	v_mfma_f32_16x16x32_bf16 v[20:23], v[168:171], v[184:187], v[20:23]
	v_mfma_f32_16x16x32_bf16 v[20:23], v[164:167], v[180:183], v[20:23]
	v_mfma_f32_16x16x32_bf16 v[12:15], v[156:159], v[188:191], v[12:15]
	v_mfma_f32_16x16x32_bf16 v[12:15], v[160:163], v[192:195], v[12:15]
	v_mfma_f32_16x16x32_bf16 v[8:11], v[168:171], v[192:195], v[8:11]
	v_mfma_f32_16x16x32_bf16 v[8:11], v[164:167], v[188:191], v[8:11]
	v_mfma_f32_16x16x32_bf16 v[4:7], v[156:159], v[196:199], v[4:7]
	v_mfma_f32_16x16x32_bf16 v[4:7], v[160:163], v[200:203], v[4:7]
	v_mfma_f32_16x16x32_bf16 v[0:3], v[168:171], v[200:203], v[0:3]
	v_mfma_f32_16x16x32_bf16 v[0:3], v[164:167], v[196:199], v[0:3]
	s_setprio 0
	s_barrier
	s_add_i32 s63, 0, 0x18000
	s_add_i32 s64, 0, 0x1c000
	v_add_u32_e32 v152, s63, v219
	v_add_u32_e32 v168, s64, v219
	ds_read_b128 v[140:143], v152
	ds_read_b128 v[144:147], v152 offset:1024
	ds_read_b128 v[148:151], v152 offset:2048
	ds_read_b128 v[152:155], v152 offset:3072
	ds_read_b128 v[156:159], v168
	ds_read_b128 v[160:163], v168 offset:1024
	ds_read_b128 v[164:167], v168 offset:2048
	ds_read_b128 v[168:171], v168 offset:3072
	s_add_u32 s30, s30, 0x4000
	s_addc_u32 s31, s31, 0
	s_mov_b32 m0, s40
	v_lshl_add_u64 v[204:205], s[30:31], 0, v[128:129]
	ds_read_b128 v[172:175], v224 offset:32768
	ds_read_b128 v[176:179], v224 offset:33792
	ds_read_b128 v[180:183], v224 offset:34816
	ds_read_b128 v[184:187], v224 offset:35840
	ds_read_b128 v[188:191], v224 offset:36864
	ds_read_b128 v[192:195], v224 offset:37888
	ds_read_b128 v[196:199], v224 offset:38912
	ds_read_b128 v[200:203], v224 offset:39936
	global_load_lds_dwordx4 v[204:205], off
	v_lshl_add_u64 v[204:205], s[30:31], 0, v[130:131]
	s_mov_b32 m0, s41
	s_nop 0
	global_load_lds_dwordx4 v[204:205], off
	s_waitcnt vmcnt(8)
	s_waitcnt lgkmcnt(0)
	s_barrier
	s_setprio 1
	s_waitcnt lgkmcnt(0)
	v_mfma_f32_16x16x32_bf16 v[124:127], v[140:143], v[172:175], v[124:127]
	v_mfma_f32_16x16x32_bf16 v[124:127], v[144:147], v[176:179], v[124:127]
	v_mfma_f32_16x16x32_bf16 v[120:123], v[152:155], v[176:179], v[120:123]
	v_mfma_f32_16x16x32_bf16 v[120:123], v[148:151], v[172:175], v[120:123]
	v_mfma_f32_16x16x32_bf16 v[116:119], v[140:143], v[180:183], v[116:119]
	v_mfma_f32_16x16x32_bf16 v[116:119], v[144:147], v[184:187], v[116:119]
	v_mfma_f32_16x16x32_bf16 v[112:115], v[152:155], v[184:187], v[112:115]
	v_mfma_f32_16x16x32_bf16 v[112:115], v[148:151], v[180:183], v[112:115]
	v_mfma_f32_16x16x32_bf16 v[104:107], v[140:143], v[188:191], v[104:107]
	v_mfma_f32_16x16x32_bf16 v[104:107], v[144:147], v[192:195], v[104:107]
	v_mfma_f32_16x16x32_bf16 v[96:99], v[152:155], v[192:195], v[96:99]
	v_mfma_f32_16x16x32_bf16 v[96:99], v[148:151], v[188:191], v[96:99]
	v_mfma_f32_16x16x32_bf16 v[88:91], v[140:143], v[196:199], v[88:91]
	v_mfma_f32_16x16x32_bf16 v[88:91], v[144:147], v[200:203], v[88:91]
	v_mfma_f32_16x16x32_bf16 v[80:83], v[152:155], v[200:203], v[80:83]
	v_mfma_f32_16x16x32_bf16 v[80:83], v[148:151], v[196:199], v[80:83]
	s_setprio 0
	s_setprio 1
	v_mfma_f32_16x16x32_bf16 v[108:111], v[156:159], v[172:175], v[108:111]
	v_mfma_f32_16x16x32_bf16 v[108:111], v[160:163], v[176:179], v[108:111]
	v_mfma_f32_16x16x32_bf16 v[100:103], v[168:171], v[176:179], v[100:103]
	v_mfma_f32_16x16x32_bf16 v[100:103], v[164:167], v[172:175], v[100:103]
	v_mfma_f32_16x16x32_bf16 v[92:95], v[156:159], v[180:183], v[92:95]
	v_mfma_f32_16x16x32_bf16 v[92:95], v[160:163], v[184:187], v[92:95]
	v_mfma_f32_16x16x32_bf16 v[84:87], v[168:171], v[184:187], v[84:87]
	v_mfma_f32_16x16x32_bf16 v[84:87], v[164:167], v[180:183], v[84:87]
	v_mfma_f32_16x16x32_bf16 v[76:79], v[156:159], v[188:191], v[76:79]
	v_mfma_f32_16x16x32_bf16 v[76:79], v[160:163], v[192:195], v[76:79]
	v_mfma_f32_16x16x32_bf16 v[72:75], v[168:171], v[192:195], v[72:75]
	v_mfma_f32_16x16x32_bf16 v[72:75], v[164:167], v[188:191], v[72:75]
	v_mfma_f32_16x16x32_bf16 v[68:71], v[156:159], v[196:199], v[68:71]
	v_mfma_f32_16x16x32_bf16 v[68:71], v[160:163], v[200:203], v[68:71]
	v_mfma_f32_16x16x32_bf16 v[64:67], v[168:171], v[200:203], v[64:67]
	v_mfma_f32_16x16x32_bf16 v[64:67], v[164:167], v[196:199], v[64:67]
	s_setprio 0
	s_barrier
	s_add_u32 s30, s28, 0x8000
	s_addc_u32 s31, s29, 0
	s_add_i32 s63, s63, s37
	v_lshl_add_u64 v[204:205], s[30:31], 0, v[128:129]
	s_mov_b32 m0, s63
	ds_read_b128 v[172:175], v224 offset:49152
	ds_read_b128 v[176:179], v224 offset:50176
	ds_read_b128 v[180:183], v224 offset:51200
	ds_read_b128 v[184:187], v224 offset:52224
	ds_read_b128 v[188:191], v224 offset:53248
	ds_read_b128 v[192:195], v224 offset:54272
	ds_read_b128 v[196:199], v224 offset:55296
	ds_read_b128 v[200:203], v224 offset:56320
	global_load_lds_dwordx4 v[204:205], off
	s_add_i32 m0, s63, 0x2000
	s_add_u32 s28, s28, 0xc000
	v_lshl_add_u64 v[204:205], s[30:31], 0, v[130:131]
	s_addc_u32 s29, s29, 0
	s_add_i32 s30, s64, s37
	global_load_lds_dwordx4 v[204:205], off
	v_lshl_add_u64 v[204:205], s[28:29], 0, v[128:129]
	s_mov_b32 m0, s30
	s_nop 0
	global_load_lds_dwordx4 v[204:205], off
	v_lshl_add_u64 v[204:205], s[28:29], 0, v[130:131]
	s_add_i32 m0, s30, 0x2000
	s_nop 0
	global_load_lds_dwordx4 v[204:205], off
	v_lshl_add_u64 v[204:205], s[26:27], 0, v[128:129]
	s_mov_b32 m0, s44
	s_nop 0
	global_load_lds_dwordx4 v[204:205], off
	v_lshl_add_u64 v[204:205], s[26:27], 0, v[130:131]
	s_mov_b32 m0, s45
	s_nop 0
	global_load_lds_dwordx4 v[204:205], off
	s_waitcnt vmcnt(8)
	s_waitcnt lgkmcnt(0)
	s_barrier
	s_setprio 1
	s_waitcnt lgkmcnt(0)
	v_mfma_f32_16x16x32_bf16 v[60:63], v[140:143], v[172:175], v[60:63]
	v_mfma_f32_16x16x32_bf16 v[60:63], v[144:147], v[176:179], v[60:63]
	v_mfma_f32_16x16x32_bf16 v[56:59], v[152:155], v[176:179], v[56:59]
	v_mfma_f32_16x16x32_bf16 v[56:59], v[148:151], v[172:175], v[56:59]
	v_mfma_f32_16x16x32_bf16 v[52:55], v[140:143], v[180:183], v[52:55]
	v_mfma_f32_16x16x32_bf16 v[52:55], v[144:147], v[184:187], v[52:55]
	v_mfma_f32_16x16x32_bf16 v[48:51], v[152:155], v[184:187], v[48:51]
	v_mfma_f32_16x16x32_bf16 v[48:51], v[148:151], v[180:183], v[48:51]
	v_mfma_f32_16x16x32_bf16 v[40:43], v[140:143], v[188:191], v[40:43]
	v_mfma_f32_16x16x32_bf16 v[40:43], v[144:147], v[192:195], v[40:43]
	v_mfma_f32_16x16x32_bf16 v[32:35], v[152:155], v[192:195], v[32:35]
	v_mfma_f32_16x16x32_bf16 v[32:35], v[148:151], v[188:191], v[32:35]
	v_mfma_f32_16x16x32_bf16 v[24:27], v[140:143], v[196:199], v[24:27]
	v_mfma_f32_16x16x32_bf16 v[24:27], v[144:147], v[200:203], v[24:27]
	v_mfma_f32_16x16x32_bf16 v[16:19], v[152:155], v[200:203], v[16:19]
	v_mfma_f32_16x16x32_bf16 v[16:19], v[148:151], v[196:199], v[16:19]
	s_setprio 0
	s_setprio 1
	v_mfma_f32_16x16x32_bf16 v[44:47], v[156:159], v[172:175], v[44:47]
	v_mfma_f32_16x16x32_bf16 v[44:47], v[160:163], v[176:179], v[44:47]
	v_mfma_f32_16x16x32_bf16 v[36:39], v[168:171], v[176:179], v[36:39]
	v_mfma_f32_16x16x32_bf16 v[36:39], v[164:167], v[172:175], v[36:39]
	v_mfma_f32_16x16x32_bf16 v[28:31], v[156:159], v[180:183], v[28:31]
	v_mfma_f32_16x16x32_bf16 v[28:31], v[160:163], v[184:187], v[28:31]
	v_mfma_f32_16x16x32_bf16 v[20:23], v[168:171], v[184:187], v[20:23]
	v_mfma_f32_16x16x32_bf16 v[20:23], v[164:167], v[180:183], v[20:23]
	v_mfma_f32_16x16x32_bf16 v[12:15], v[156:159], v[188:191], v[12:15]
	v_mfma_f32_16x16x32_bf16 v[12:15], v[160:163], v[192:195], v[12:15]
	v_mfma_f32_16x16x32_bf16 v[8:11], v[168:171], v[192:195], v[8:11]
	v_mfma_f32_16x16x32_bf16 v[8:11], v[164:167], v[188:191], v[8:11]
	v_mfma_f32_16x16x32_bf16 v[4:7], v[156:159], v[196:199], v[4:7]
	v_mfma_f32_16x16x32_bf16 v[4:7], v[160:163], v[200:203], v[4:7]
	v_mfma_f32_16x16x32_bf16 v[0:3], v[168:171], v[200:203], v[0:3]
	v_mfma_f32_16x16x32_bf16 v[0:3], v[164:167], v[196:199], v[0:3]
	s_setprio 0
	s_barrier
	s_add_u32 s24, s24, 0x10000
	s_addc_u32 s25, s25, 0
	s_add_u32 s60, s60, 0x10000
	s_addc_u32 s61, s61, 0
	s_cmp_ge_i32 s62, s43
	s_mov_b32 s26, s62
	s_cbranch_scc0 .LBB0_1056
	v_pk_mul_f32 v[198:199], v[126:127], 0.5 op_sel_hi:[1,0]
	v_pk_mul_f32 v[200:201], v[124:125], 0.5 op_sel_hi:[1,0]
	v_pk_mul_f32 v[202:203], v[122:123], 0.5 op_sel_hi:[1,0]
	v_pk_mul_f32 v[204:205], v[120:121], 0.5 op_sel_hi:[1,0]
	v_pk_mul_f32 v[208:209], v[110:111], 0.5 op_sel_hi:[1,0]
	v_pk_mul_f32 v[206:207], v[108:109], 0.5 op_sel_hi:[1,0]
	v_pk_mul_f32 v[196:197], v[102:103], 0.5 op_sel_hi:[1,0]
	v_pk_mul_f32 v[194:195], v[100:101], 0.5 op_sel_hi:[1,0]
	v_pk_mul_f32 v[192:193], v[118:119], 0.5 op_sel_hi:[1,0]
	v_pk_mul_f32 v[190:191], v[116:117], 0.5 op_sel_hi:[1,0]
	v_pk_mul_f32 v[188:189], v[114:115], 0.5 op_sel_hi:[1,0]
	v_pk_mul_f32 v[186:187], v[112:113], 0.5 op_sel_hi:[1,0]
	v_pk_mul_f32 v[184:185], v[94:95], 0.5 op_sel_hi:[1,0]
	v_pk_mul_f32 v[182:183], v[92:93], 0.5 op_sel_hi:[1,0]
	v_pk_mul_f32 v[180:181], v[86:87], 0.5 op_sel_hi:[1,0]
	v_pk_mul_f32 v[178:179], v[84:85], 0.5 op_sel_hi:[1,0]
	v_pk_mul_f32 v[176:177], v[106:107], 0.5 op_sel_hi:[1,0]
	v_pk_mul_f32 v[174:175], v[104:105], 0.5 op_sel_hi:[1,0]
	v_pk_mul_f32 v[172:173], v[98:99], 0.5 op_sel_hi:[1,0]
	v_pk_mul_f32 v[170:171], v[96:97], 0.5 op_sel_hi:[1,0]
	v_pk_mul_f32 v[168:169], v[78:79], 0.5 op_sel_hi:[1,0]
	v_pk_mul_f32 v[166:167], v[76:77], 0.5 op_sel_hi:[1,0]
	v_pk_mul_f32 v[164:165], v[74:75], 0.5 op_sel_hi:[1,0]
	v_pk_mul_f32 v[162:163], v[72:73], 0.5 op_sel_hi:[1,0]
	v_pk_mul_f32 v[160:161], v[90:91], 0.5 op_sel_hi:[1,0]
	v_pk_mul_f32 v[158:159], v[88:89], 0.5 op_sel_hi:[1,0]
	v_pk_mul_f32 v[156:157], v[82:83], 0.5 op_sel_hi:[1,0]
	v_pk_mul_f32 v[154:155], v[80:81], 0.5 op_sel_hi:[1,0]
	v_pk_mul_f32 v[152:153], v[70:71], 0.5 op_sel_hi:[1,0]
	v_pk_mul_f32 v[150:151], v[68:69], 0.5 op_sel_hi:[1,0]
	v_pk_mul_f32 v[148:149], v[66:67], 0.5 op_sel_hi:[1,0]
	v_pk_mul_f32 v[146:147], v[64:65], 0.5 op_sel_hi:[1,0]
	v_pk_mul_f32 v[142:143], v[62:63], 0.5 op_sel_hi:[1,0]
	v_pk_mul_f32 v[140:141], v[60:61], 0.5 op_sel_hi:[1,0]
	v_pk_mul_f32 v[126:127], v[58:59], 0.5 op_sel_hi:[1,0]
	v_pk_mul_f32 v[124:125], v[56:57], 0.5 op_sel_hi:[1,0]
	v_pk_mul_f32 v[122:123], v[46:47], 0.5 op_sel_hi:[1,0]
	v_pk_mul_f32 v[120:121], v[44:45], 0.5 op_sel_hi:[1,0]
	v_pk_mul_f32 v[118:119], v[38:39], 0.5 op_sel_hi:[1,0]
	v_pk_mul_f32 v[116:117], v[36:37], 0.5 op_sel_hi:[1,0]
	v_pk_mul_f32 v[114:115], v[54:55], 0.5 op_sel_hi:[1,0]
	v_pk_mul_f32 v[112:113], v[52:53], 0.5 op_sel_hi:[1,0]
	v_pk_mul_f32 v[110:111], v[50:51], 0.5 op_sel_hi:[1,0]
	v_pk_mul_f32 v[108:109], v[48:49], 0.5 op_sel_hi:[1,0]
	v_pk_mul_f32 v[106:107], v[30:31], 0.5 op_sel_hi:[1,0]
	v_pk_mul_f32 v[104:105], v[28:29], 0.5 op_sel_hi:[1,0]
	v_pk_mul_f32 v[102:103], v[22:23], 0.5 op_sel_hi:[1,0]
	v_pk_mul_f32 v[100:101], v[20:21], 0.5 op_sel_hi:[1,0]
	v_pk_mul_f32 v[98:99], v[42:43], 0.5 op_sel_hi:[1,0]
	v_pk_mul_f32 v[96:97], v[40:41], 0.5 op_sel_hi:[1,0]
	v_pk_mul_f32 v[94:95], v[34:35], 0.5 op_sel_hi:[1,0]
	v_pk_mul_f32 v[92:93], v[32:33], 0.5 op_sel_hi:[1,0]
	v_pk_mul_f32 v[90:91], v[14:15], 0.5 op_sel_hi:[1,0]
	v_pk_mul_f32 v[88:89], v[12:13], 0.5 op_sel_hi:[1,0]
	v_pk_mul_f32 v[86:87], v[10:11], 0.5 op_sel_hi:[1,0]
	v_pk_mul_f32 v[84:85], v[8:9], 0.5 op_sel_hi:[1,0]
	v_pk_mul_f32 v[82:83], v[26:27], 0.5 op_sel_hi:[1,0]
	v_pk_mul_f32 v[80:81], v[24:25], 0.5 op_sel_hi:[1,0]
	v_pk_mul_f32 v[78:79], v[18:19], 0.5 op_sel_hi:[1,0]
	v_pk_mul_f32 v[76:77], v[16:17], 0.5 op_sel_hi:[1,0]
	v_pk_mul_f32 v[74:75], v[6:7], 0.5 op_sel_hi:[1,0]
	v_pk_mul_f32 v[72:73], v[4:5], 0.5 op_sel_hi:[1,0]
	v_pk_mul_f32 v[70:71], v[2:3], 0.5 op_sel_hi:[1,0]
	v_pk_mul_f32 v[68:69], v[0:1], 0.5 op_sel_hi:[1,0]

.LBB0_1159:
	ds_read_b128 v[128:131], v205
	ds_read_b128 v[132:135], v205 offset:1024
	ds_read_b128 v[136:139], v205 offset:2048
	ds_read_b128 v[140:143], v205 offset:3072
	ds_read_b128 v[144:147], v206
	ds_read_b128 v[160:163], v206 offset:1024
	ds_read_b128 v[164:167], v206 offset:2048
	ds_read_b128 v[168:171], v206 offset:3072
	s_add_i32 s41, s6, 2
	s_add_u32 s68, s0, 0x80
	s_addc_u32 s7, s1, 0
	s_cmp_eq_u32 s57, s6
	s_cselect_b32 s6, s34, s68
	s_cselect_b32 s7, s35, s7
	s_cselect_b32 s69, s37, s39
	s_cselect_b32 s68, s36, s38
	v_lshl_add_u64 v[200:201], s[0:1], 0, v[152:153]
	s_add_i32 m0, s47, 0xc000
	ds_read_b128 v[172:175], v207
	ds_read_b128 v[176:179], v207 offset:1024
	ds_read_b128 v[180:183], v207 offset:2048
	ds_read_b128 v[184:187], v207 offset:3072
	ds_read_b128 v[188:191], v207 offset:4096
	ds_read_b128 v[192:195], v207 offset:5120
	ds_read_b128 v[196:199], v207 offset:6144
	ds_read_b128 v[212:215], v207 offset:7168
	global_load_lds_dwordx4 v[200:201], off
	v_lshl_add_u64 v[200:201], s[0:1], 0, v[154:155]
	s_add_i32 m0, s47, 0xe000
	s_nop 0
	global_load_lds_dwordx4 v[200:201], off
	s_waitcnt vmcnt(8)
	s_waitcnt lgkmcnt(0)
	s_barrier
	s_setprio 1
	s_waitcnt lgkmcnt(0)
	v_mfma_f32_16x16x32_bf16 v[124:127], v[128:131], v[172:175], v[124:127]
	v_mfma_f32_16x16x32_bf16 v[124:127], v[132:135], v[176:179], v[124:127]
	v_mfma_f32_16x16x32_bf16 v[120:123], v[140:143], v[176:179], v[120:123]
	v_mfma_f32_16x16x32_bf16 v[120:123], v[136:139], v[172:175], v[120:123]
	v_mfma_f32_16x16x32_bf16 v[108:111], v[128:131], v[180:183], v[108:111]
	v_mfma_f32_16x16x32_bf16 v[108:111], v[132:135], v[184:187], v[108:111]
	v_mfma_f32_16x16x32_bf16 v[104:107], v[140:143], v[184:187], v[104:107]
	v_mfma_f32_16x16x32_bf16 v[104:107], v[136:139], v[180:183], v[104:107]
	v_mfma_f32_16x16x32_bf16 v[92:95], v[128:131], v[188:191], v[92:95]
	v_mfma_f32_16x16x32_bf16 v[92:95], v[132:135], v[192:195], v[92:95]
	v_mfma_f32_16x16x32_bf16 v[88:91], v[140:143], v[192:195], v[88:91]
	v_mfma_f32_16x16x32_bf16 v[88:91], v[136:139], v[188:191], v[88:91]
	v_mfma_f32_16x16x32_bf16 v[76:79], v[128:131], v[196:199], v[76:79]
	v_mfma_f32_16x16x32_bf16 v[76:79], v[132:135], v[212:215], v[76:79]
	v_mfma_f32_16x16x32_bf16 v[72:75], v[140:143], v[212:215], v[72:75]
	v_mfma_f32_16x16x32_bf16 v[72:75], v[136:139], v[196:199], v[72:75]
	s_setprio 0
	s_setprio 1
	v_mfma_f32_16x16x32_bf16 v[116:119], v[144:147], v[172:175], v[116:119]
	v_mfma_f32_16x16x32_bf16 v[116:119], v[160:163], v[176:179], v[116:119]
	v_mfma_f32_16x16x32_bf16 v[112:115], v[168:171], v[176:179], v[112:115]
	v_mfma_f32_16x16x32_bf16 v[112:115], v[164:167], v[172:175], v[112:115]
	v_mfma_f32_16x16x32_bf16 v[100:103], v[144:147], v[180:183], v[100:103]
	v_mfma_f32_16x16x32_bf16 v[100:103], v[160:163], v[184:187], v[100:103]
	v_mfma_f32_16x16x32_bf16 v[96:99], v[168:171], v[184:187], v[96:99]
	v_mfma_f32_16x16x32_bf16 v[96:99], v[164:167], v[180:183], v[96:99]
	v_mfma_f32_16x16x32_bf16 v[84:87], v[144:147], v[188:191], v[84:87]
	v_mfma_f32_16x16x32_bf16 v[84:87], v[160:163], v[192:195], v[84:87]
	v_mfma_f32_16x16x32_bf16 v[80:83], v[168:171], v[192:195], v[80:83]
	v_mfma_f32_16x16x32_bf16 v[80:83], v[164:167], v[188:191], v[80:83]
	v_mfma_f32_16x16x32_bf16 v[68:71], v[144:147], v[196:199], v[68:71]
	v_mfma_f32_16x16x32_bf16 v[68:71], v[160:163], v[212:215], v[68:71]
	v_mfma_f32_16x16x32_bf16 v[64:67], v[168:171], v[212:215], v[64:67]
	v_mfma_f32_16x16x32_bf16 v[64:67], v[164:167], v[196:199], v[64:67]
	s_setprio 0
	s_barrier
	s_add_i32 s70, s60, s46
	v_lshl_add_u64 v[200:201], s[68:69], 0, v[148:149]
	s_mov_b32 m0, s70
	ds_read_b128 v[172:175], v207 offset:16384
	ds_read_b128 v[176:179], v207 offset:17408
	ds_read_b128 v[180:183], v207 offset:18432
	ds_read_b128 v[184:187], v207 offset:19456
	ds_read_b128 v[188:191], v207 offset:20480
	ds_read_b128 v[192:195], v207 offset:21504
	ds_read_b128 v[196:199], v207 offset:22528
	ds_read_b128 v[212:215], v207 offset:23552
	global_load_lds_dwordx4 v[200:201], off
	s_add_i32 m0, s70, 0x2000
	v_lshl_add_u64 v[216:217], s[68:69], 0, v[150:151]
	s_add_u32 s68, s68, s10
	s_addc_u32 s69, s69, s11
	s_add_i32 s70, s61, s46
	global_load_lds_dwordx4 v[216:217], off
	v_lshl_add_u64 v[218:219], s[68:69], 0, v[148:149]
	s_mov_b32 m0, s70
	v_lshl_add_u64 v[220:221], s[68:69], 0, v[150:151]
	global_load_lds_dwordx4 v[218:219], off
	s_add_i32 m0, s70, 0x2000
	v_lshl_add_u64 v[222:223], s[6:7], 0, v[148:149]
	global_load_lds_dwordx4 v[220:221], off
	s_mov_b32 m0, s47
	v_lshl_add_u64 v[224:225], s[6:7], 0, v[150:151]
	global_load_lds_dwordx4 v[222:223], off
	s_mov_b32 m0, s48
	s_nop 0
	global_load_lds_dwordx4 v[224:225], off
	s_waitcnt vmcnt(8)
	s_waitcnt lgkmcnt(0)
	s_barrier
	s_setprio 1
	s_waitcnt lgkmcnt(0)
	v_mfma_f32_16x16x32_bf16 v[60:63], v[128:131], v[172:175], v[60:63]
	v_mfma_f32_16x16x32_bf16 v[60:63], v[132:135], v[176:179], v[60:63]
	v_mfma_f32_16x16x32_bf16 v[56:59], v[140:143], v[176:179], v[56:59]
	v_mfma_f32_16x16x32_bf16 v[56:59], v[136:139], v[172:175], v[56:59]
	v_mfma_f32_16x16x32_bf16 v[44:47], v[128:131], v[180:183], v[44:47]
	v_mfma_f32_16x16x32_bf16 v[44:47], v[132:135], v[184:187], v[44:47]
	v_mfma_f32_16x16x32_bf16 v[40:43], v[140:143], v[184:187], v[40:43]
	v_mfma_f32_16x16x32_bf16 v[40:43], v[136:139], v[180:183], v[40:43]
	v_mfma_f32_16x16x32_bf16 v[28:31], v[128:131], v[188:191], v[28:31]
	v_mfma_f32_16x16x32_bf16 v[28:31], v[132:135], v[192:195], v[28:31]
	v_mfma_f32_16x16x32_bf16 v[24:27], v[140:143], v[192:195], v[24:27]
	v_mfma_f32_16x16x32_bf16 v[24:27], v[136:139], v[188:191], v[24:27]
	v_mfma_f32_16x16x32_bf16 v[12:15], v[128:131], v[196:199], v[12:15]
	v_mfma_f32_16x16x32_bf16 v[12:15], v[132:135], v[212:215], v[12:15]
	v_mfma_f32_16x16x32_bf16 v[8:11], v[140:143], v[212:215], v[8:11]
	v_mfma_f32_16x16x32_bf16 v[8:11], v[136:139], v[196:199], v[8:11]
	s_setprio 0
	s_setprio 1
	v_mfma_f32_16x16x32_bf16 v[52:55], v[144:147], v[172:175], v[52:55]
	v_mfma_f32_16x16x32_bf16 v[52:55], v[160:163], v[176:179], v[52:55]
	v_mfma_f32_16x16x32_bf16 v[48:51], v[168:171], v[176:179], v[48:51]
	v_mfma_f32_16x16x32_bf16 v[48:51], v[164:167], v[172:175], v[48:51]
	v_mfma_f32_16x16x32_bf16 v[36:39], v[144:147], v[180:183], v[36:39]
	v_mfma_f32_16x16x32_bf16 v[36:39], v[160:163], v[184:187], v[36:39]
	v_mfma_f32_16x16x32_bf16 v[32:35], v[168:171], v[184:187], v[32:35]
	v_mfma_f32_16x16x32_bf16 v[32:35], v[164:167], v[180:183], v[32:35]
	v_mfma_f32_16x16x32_bf16 v[20:23], v[144:147], v[188:191], v[20:23]
	v_mfma_f32_16x16x32_bf16 v[20:23], v[160:163], v[192:195], v[20:23]
	v_mfma_f32_16x16x32_bf16 v[16:19], v[168:171], v[192:195], v[16:19]
	v_mfma_f32_16x16x32_bf16 v[16:19], v[164:167], v[188:191], v[16:19]
	v_mfma_f32_16x16x32_bf16 v[4:7], v[144:147], v[196:199], v[4:7]
	v_mfma_f32_16x16x32_bf16 v[4:7], v[160:163], v[212:215], v[4:7]
	v_mfma_f32_16x16x32_bf16 v[0:3], v[168:171], v[212:215], v[0:3]
	v_mfma_f32_16x16x32_bf16 v[0:3], v[164:167], v[196:199], v[0:3]
	s_setprio 0
	s_barrier
	s_add_i32 s68, 0, 0x18000
	s_add_i32 s69, 0, 0x1c000
	v_add_u32_e32 v140, s68, v203
	v_add_u32_e32 v168, s69, v203
	ds_read_b128 v[128:131], v140
	ds_read_b128 v[132:135], v140 offset:1024
	ds_read_b128 v[136:139], v140 offset:2048
	ds_read_b128 v[140:143], v140 offset:3072
	ds_read_b128 v[144:147], v168
	ds_read_b128 v[160:163], v168 offset:1024
	ds_read_b128 v[164:167], v168 offset:2048
	ds_read_b128 v[168:171], v168 offset:3072
	s_add_u32 s6, s6, s10
	s_addc_u32 s7, s7, s11
	s_mov_b32 m0, s49
	v_lshl_add_u64 v[226:227], s[6:7], 0, v[148:149]
	ds_read_b128 v[172:175], v207 offset:32768
	ds_read_b128 v[176:179], v207 offset:33792
	ds_read_b128 v[180:183], v207 offset:34816
	ds_read_b128 v[184:187], v207 offset:35840
	ds_read_b128 v[188:191], v207 offset:36864
	ds_read_b128 v[192:195], v207 offset:37888
	ds_read_b128 v[196:199], v207 offset:38912
	ds_read_b128 v[212:215], v207 offset:39936
	global_load_lds_dwordx4 v[226:227], off
	v_lshl_add_u64 v[226:227], s[6:7], 0, v[150:151]
	s_mov_b32 m0, s50
	s_nop 0
	global_load_lds_dwordx4 v[226:227], off
	s_waitcnt vmcnt(8)
	s_waitcnt lgkmcnt(0)
	s_barrier
	s_setprio 1
	s_waitcnt lgkmcnt(0)
	v_mfma_f32_16x16x32_bf16 v[124:127], v[128:131], v[172:175], v[124:127]
	v_mfma_f32_16x16x32_bf16 v[124:127], v[132:135], v[176:179], v[124:127]
	v_mfma_f32_16x16x32_bf16 v[120:123], v[140:143], v[176:179], v[120:123]
	v_mfma_f32_16x16x32_bf16 v[120:123], v[136:139], v[172:175], v[120:123]
	v_mfma_f32_16x16x32_bf16 v[108:111], v[128:131], v[180:183], v[108:111]
	v_mfma_f32_16x16x32_bf16 v[108:111], v[132:135], v[184:187], v[108:111]
	v_mfma_f32_16x16x32_bf16 v[104:107], v[140:143], v[184:187], v[104:107]
	v_mfma_f32_16x16x32_bf16 v[104:107], v[136:139], v[180:183], v[104:107]
	v_mfma_f32_16x16x32_bf16 v[92:95], v[128:131], v[188:191], v[92:95]
	v_mfma_f32_16x16x32_bf16 v[92:95], v[132:135], v[192:195], v[92:95]
	v_mfma_f32_16x16x32_bf16 v[88:91], v[140:143], v[192:195], v[88:91]
	v_mfma_f32_16x16x32_bf16 v[88:91], v[136:139], v[188:191], v[88:91]
	v_mfma_f32_16x16x32_bf16 v[76:79], v[128:131], v[196:199], v[76:79]
	v_mfma_f32_16x16x32_bf16 v[76:79], v[132:135], v[212:215], v[76:79]
	v_mfma_f32_16x16x32_bf16 v[72:75], v[140:143], v[212:215], v[72:75]
	v_mfma_f32_16x16x32_bf16 v[72:75], v[136:139], v[196:199], v[72:75]
	s_setprio 0
	s_setprio 1
	v_mfma_f32_16x16x32_bf16 v[116:119], v[144:147], v[172:175], v[116:119]
	v_mfma_f32_16x16x32_bf16 v[116:119], v[160:163], v[176:179], v[116:119]
	v_mfma_f32_16x16x32_bf16 v[112:115], v[168:171], v[176:179], v[112:115]
	v_mfma_f32_16x16x32_bf16 v[112:115], v[164:167], v[172:175], v[112:115]
	v_mfma_f32_16x16x32_bf16 v[100:103], v[144:147], v[180:183], v[100:103]
	v_mfma_f32_16x16x32_bf16 v[100:103], v[160:163], v[184:187], v[100:103]
	v_mfma_f32_16x16x32_bf16 v[96:99], v[168:171], v[184:187], v[96:99]
	v_mfma_f32_16x16x32_bf16 v[96:99], v[164:167], v[180:183], v[96:99]
	v_mfma_f32_16x16x32_bf16 v[84:87], v[144:147], v[188:191], v[84:87]
	v_mfma_f32_16x16x32_bf16 v[84:87], v[160:163], v[192:195], v[84:87]
	v_mfma_f32_16x16x32_bf16 v[80:83], v[168:171], v[192:195], v[80:83]
	v_mfma_f32_16x16x32_bf16 v[80:83], v[164:167], v[188:191], v[80:83]
	v_mfma_f32_16x16x32_bf16 v[68:71], v[144:147], v[196:199], v[68:71]
	v_mfma_f32_16x16x32_bf16 v[68:71], v[160:163], v[212:215], v[68:71]
	v_mfma_f32_16x16x32_bf16 v[64:67], v[168:171], v[212:215], v[64:67]
	v_mfma_f32_16x16x32_bf16 v[64:67], v[164:167], v[196:199], v[64:67]
	s_setprio 0
	s_barrier
	s_add_i32 s6, s68, s46
	v_lshl_add_u64 v[200:201], v[200:201], 0, s[20:21]
	s_mov_b32 m0, s6
	ds_read_b128 v[172:175], v207 offset:49152
	ds_read_b128 v[176:179], v207 offset:50176
	ds_read_b128 v[180:183], v207 offset:51200
	ds_read_b128 v[184:187], v207 offset:52224
	ds_read_b128 v[188:191], v207 offset:53248
	ds_read_b128 v[192:195], v207 offset:54272
	ds_read_b128 v[196:199], v207 offset:55296
	ds_read_b128 v[212:215], v207 offset:56320
	global_load_lds_dwordx4 v[200:201], off
	v_lshl_add_u64 v[200:201], v[216:217], 0, s[20:21]
	s_add_i32 m0, s6, 0x2000
	s_add_i32 s6, s69, s46
	global_load_lds_dwordx4 v[200:201], off
	v_lshl_add_u64 v[200:201], v[218:219], 0, s[20:21]
	s_mov_b32 m0, s6
	s_nop 0
	global_load_lds_dwordx4 v[200:201], off
	v_lshl_add_u64 v[200:201], v[220:221], 0, s[20:21]
	s_add_i32 m0, s6, 0x2000
	s_nop 0
	global_load_lds_dwordx4 v[200:201], off
	v_lshl_add_u64 v[200:201], v[222:223], 0, s[20:21]
	s_mov_b32 m0, s54
	s_nop 0
	global_load_lds_dwordx4 v[200:201], off
	v_lshl_add_u64 v[200:201], v[224:225], 0, s[20:21]
	s_mov_b32 m0, s55
	s_nop 0
	global_load_lds_dwordx4 v[200:201], off
	s_waitcnt vmcnt(8)
	s_waitcnt lgkmcnt(0)
	s_barrier
	s_setprio 1
	s_waitcnt lgkmcnt(0)
	v_mfma_f32_16x16x32_bf16 v[60:63], v[128:131], v[172:175], v[60:63]
	v_mfma_f32_16x16x32_bf16 v[60:63], v[132:135], v[176:179], v[60:63]
	v_mfma_f32_16x16x32_bf16 v[56:59], v[140:143], v[176:179], v[56:59]
	v_mfma_f32_16x16x32_bf16 v[56:59], v[136:139], v[172:175], v[56:59]
	v_mfma_f32_16x16x32_bf16 v[44:47], v[128:131], v[180:183], v[44:47]
	v_mfma_f32_16x16x32_bf16 v[44:47], v[132:135], v[184:187], v[44:47]
	v_mfma_f32_16x16x32_bf16 v[40:43], v[140:143], v[184:187], v[40:43]
	v_mfma_f32_16x16x32_bf16 v[40:43], v[136:139], v[180:183], v[40:43]
	v_mfma_f32_16x16x32_bf16 v[28:31], v[128:131], v[188:191], v[28:31]
	v_mfma_f32_16x16x32_bf16 v[28:31], v[132:135], v[192:195], v[28:31]
	v_mfma_f32_16x16x32_bf16 v[24:27], v[140:143], v[192:195], v[24:27]
	v_mfma_f32_16x16x32_bf16 v[24:27], v[136:139], v[188:191], v[24:27]
	v_mfma_f32_16x16x32_bf16 v[12:15], v[128:131], v[196:199], v[12:15]
	v_mfma_f32_16x16x32_bf16 v[12:15], v[132:135], v[212:215], v[12:15]
	v_mfma_f32_16x16x32_bf16 v[8:11], v[140:143], v[212:215], v[8:11]
	v_mfma_f32_16x16x32_bf16 v[8:11], v[136:139], v[196:199], v[8:11]
	s_setprio 0
	s_setprio 1
	v_mfma_f32_16x16x32_bf16 v[52:55], v[144:147], v[172:175], v[52:55]
	v_mfma_f32_16x16x32_bf16 v[52:55], v[160:163], v[176:179], v[52:55]
	v_mfma_f32_16x16x32_bf16 v[48:51], v[168:171], v[176:179], v[48:51]
	v_mfma_f32_16x16x32_bf16 v[48:51], v[164:167], v[172:175], v[48:51]
	v_mfma_f32_16x16x32_bf16 v[36:39], v[144:147], v[180:183], v[36:39]
	v_mfma_f32_16x16x32_bf16 v[36:39], v[160:163], v[184:187], v[36:39]
	v_mfma_f32_16x16x32_bf16 v[32:35], v[168:171], v[184:187], v[32:35]
	v_mfma_f32_16x16x32_bf16 v[32:35], v[164:167], v[180:183], v[32:35]
	v_mfma_f32_16x16x32_bf16 v[20:23], v[144:147], v[188:191], v[20:23]
	v_mfma_f32_16x16x32_bf16 v[20:23], v[160:163], v[192:195], v[20:23]
	v_mfma_f32_16x16x32_bf16 v[16:19], v[168:171], v[192:195], v[16:19]
	v_mfma_f32_16x16x32_bf16 v[16:19], v[164:167], v[188:191], v[16:19]
	v_mfma_f32_16x16x32_bf16 v[4:7], v[144:147], v[196:199], v[4:7]
	v_mfma_f32_16x16x32_bf16 v[4:7], v[160:163], v[212:215], v[4:7]
	v_mfma_f32_16x16x32_bf16 v[0:3], v[168:171], v[212:215], v[0:3]
	v_mfma_f32_16x16x32_bf16 v[0:3], v[164:167], v[196:199], v[0:3]
	s_setprio 0
	s_barrier
	s_add_u32 s0, s0, 0x100
	s_addc_u32 s1, s1, 0
	s_add_u32 s38, s38, 0x100
	s_addc_u32 s39, s39, 0
	s_cmp_ge_i32 s41, s56
	s_mov_b32 s6, s41
	s_cbranch_scc0 .LBB0_1159
